# strategy 1 in the GEMM hot loops: the compiler's duplicate lgkmcnt(0) after s_setprio (already drained by the inline-asm wait just before) removed at 30 sites
# speedup vs baseline: 1.0049x; 1.0025x over previous
; #define PG8_STAGE(bufoff, gbase, voff) do { _Pragma("unroll") for (int _i = 0; _i < 2; ++_i) \
;         __builtin_amdgcn_global_load_lds((const unsigned*)((const char*)(gbase) + (voff)[_i]), (PG8_LAS unsigned*)(lds + (bufoff) + ldsw + _i * 8192), 16, 0, 0); } while (0)
; #define PG8_LDA(dst, b, h) do { _Pragma("unroll") for (int m = 0; m < 4; ++m) _Pragma("unroll") for (int k = 0; k < 2; ++k) dst[m][k] = *(const PG8_LAS bf16x8*)(lds + PG8_SA(b, h) + aoff + m * 2048 + k * 1024); } while (0)
; #define PG8_WAIT_V(n) asm volatile("s_waitcnt vmcnt(" #n ")" ::: "memory")
; template <class Epi, class Sched>
; __device__ __forceinline__ void gemm_phase(PG8_LAS unsigned char* lds, const Gemm g, const Sched& S, const Epi& E) {
;     ...
;         for (int t = 0; t < nt; t += 2) {
;             const bool last = (t == nt - 2);
;             const char* a1 = cA + (size_t)(t + 1) * kstep;
;             const char* a2 = last ? nA : cA + (size_t)(t + 2) * kstep; const char* b2 = last ? nB : cB + (size_t)(t + 2) * kstep;
;             const char* a3 = a2 + kstep; const char* b3 = b2 + kstep;
;             if (last && has_next) S.a_ready(nxt);
;             PG8_LDB(B0, 0, 0); PG8_SCHED; PG8_LDA(At, 0, 0); PG8_STAGE(PG8_SA(1, 1), a1 + hstep, voffA);
;             PG8_WAIT_L(8); PG8_BAR; PG8_WAIT_L(0); PG8_MMA(0, 0, At, B0); PG8_BAR; PG8_SCHED;
;             PG8_LDB(B1, 0, 1); PG8_STAGE(PG8_SB(0, 0), b2, voffB);
;             PG8_BAR; PG8_WAIT_L(0); PG8_MMA(0, 1, At, B1); PG8_BAR;
;             PG8_LDA(At, 0, 1); PG8_STAGE(PG8_SA(0, 0), a2, voffA);
;             PG8_BAR; PG8_WAIT_L(0); PG8_MMA(1, 0, At, B0); PG8_BAR; PG8_SCHED;
;             PG8_STAGE(PG8_SB(0, 1), b2 + hstep, voffB);
;             PG8_WAIT_V(6); PG8_BAR; PG8_MMA(1, 1, At, B1); PG8_BAR;
;             PG8_LDB(B0, 1, 0); PG8_SCHED; PG8_LDA(At, 1, 0); PG8_STAGE(PG8_SA(0, 1), a2 + hstep, voffA);
;             PG8_WAIT_L(8); PG8_BAR; PG8_WAIT_L(0); PG8_MMA(0, 0, At, B0); PG8_BAR; PG8_SCHED;
;             PG8_LDB(B1, 1, 1); PG8_STAGE(PG8_SB(1, 0), b3, voffB);
;             PG8_BAR; PG8_WAIT_L(0); PG8_MMA(0, 1, At, B1); PG8_BAR;
;             PG8_LDA(At, 1, 1); PG8_STAGE(PG8_SA(1, 0), a3, voffA);
;             PG8_BAR; PG8_WAIT_L(0); PG8_MMA(1, 0, At, B0); PG8_BAR; PG8_SCHED;
;             PG8_STAGE(PG8_SB(1, 1), b3 + hstep, voffB);
;             PG8_WAIT_V(6); PG8_BAR; PG8_MMA(1, 1, At, B1); PG8_BAR;
.LBB0_114:
	s_add_u32 s20, s18, 0xfffc0080
	s_addc_u32 s21, s19, -1
	s_add_i32 s60, s46, 0x100
	v_add_u32_e32 v166, s60, v155
	ds_read_b128 v[150:153], v166
	ds_read_b128 v[158:161], v166 offset:1024
	ds_read_b128 v[162:165], v166 offset:2048
	ds_read_b128 v[166:169], v166 offset:3072
	s_cmp_eq_u32 s59, 12
	s_cselect_b32 s23, s1, s21
	s_cselect_b32 s22, s9, s20
	s_cselect_b32 s21, s7, s41
	s_cselect_b32 s20, s17, s40
	v_lshl_add_u64 v[186:187], s[18:19], 0, v[134:135]
	s_add_i32 m0, s31, 0xc000
	ds_read_b128 v[170:173], v157
	ds_read_b128 v[174:177], v157 offset:1024
	ds_read_b128 v[178:181], v157 offset:2048
	ds_read_b128 v[182:185], v157 offset:3072
	ds_read_b128 v[210:213], v157 offset:4096
	ds_read_b128 v[214:217], v157 offset:5120
	ds_read_b128 v[218:221], v157 offset:6144
	ds_read_b128 v[222:225], v157 offset:7168
	global_load_lds_dwordx4 v[186:187], off
	v_lshl_add_u64 v[186:187], s[18:19], 0, v[148:149]
	s_add_i32 m0, s31, 0xe000
	s_nop 0
	global_load_lds_dwordx4 v[186:187], off
	s_waitcnt lgkmcnt(8)
	s_barrier
	s_waitcnt lgkmcnt(0)
	s_setprio 1
	v_mfma_f32_16x16x32_bf16 v[124:127], v[150:153], v[170:173], v[124:127]
	v_mfma_f32_16x16x32_bf16 v[120:123], v[162:165], v[170:173], v[120:123]
	v_mfma_f32_16x16x32_bf16 v[112:115], v[150:153], v[178:181], v[112:115]
	v_mfma_f32_16x16x32_bf16 v[104:107], v[162:165], v[178:181], v[104:107]
	v_mfma_f32_16x16x32_bf16 v[96:99], v[150:153], v[210:213], v[96:99]
	v_mfma_f32_16x16x32_bf16 v[88:91], v[162:165], v[210:213], v[88:91]
	v_mfma_f32_16x16x32_bf16 v[80:83], v[150:153], v[218:221], v[80:83]
	v_mfma_f32_16x16x32_bf16 v[72:75], v[162:165], v[218:221], v[72:75]
	v_mfma_f32_16x16x32_bf16 v[124:127], v[158:161], v[174:177], v[124:127]
	v_mfma_f32_16x16x32_bf16 v[120:123], v[166:169], v[174:177], v[120:123]
	v_mfma_f32_16x16x32_bf16 v[112:115], v[158:161], v[182:185], v[112:115]
	v_mfma_f32_16x16x32_bf16 v[104:107], v[166:169], v[182:185], v[104:107]
	v_mfma_f32_16x16x32_bf16 v[96:99], v[158:161], v[214:217], v[96:99]
	v_mfma_f32_16x16x32_bf16 v[88:91], v[166:169], v[214:217], v[88:91]
	v_mfma_f32_16x16x32_bf16 v[80:83], v[158:161], v[222:225], v[80:83]
	v_mfma_f32_16x16x32_bf16 v[72:75], v[166:169], v[222:225], v[72:75]
	s_setprio 0
	s_barrier
	s_add_i32 s62, s48, 0x100
	v_add_u32_e32 v186, s62, v155
	s_add_i32 s60, s60, s30
	ds_read_b128 v[226:229], v186
	ds_read_b128 v[230:233], v186 offset:1024
	ds_read_b128 v[234:237], v186 offset:2048
	ds_read_b128 v[238:241], v186 offset:3072
	v_lshl_add_u64 v[186:187], s[20:21], 0, v[138:139]
	s_mov_b32 m0, s60
	v_lshl_add_u64 v[242:243], s[20:21], 0, v[132:133]
	global_load_lds_dwordx4 v[186:187], off
	s_add_i32 m0, s60, 0x2000
	s_nop 0
	global_load_lds_dwordx4 v[242:243], off
	s_barrier
	s_waitcnt lgkmcnt(0)
	s_setprio 1
	v_mfma_f32_16x16x32_bf16 v[116:119], v[226:229], v[170:173], v[116:119]
	v_mfma_f32_16x16x32_bf16 v[108:111], v[234:237], v[170:173], v[108:111]
	v_mfma_f32_16x16x32_bf16 v[100:103], v[226:229], v[178:181], v[100:103]
	v_mfma_f32_16x16x32_bf16 v[92:95], v[234:237], v[178:181], v[92:95]
	v_mfma_f32_16x16x32_bf16 v[84:87], v[226:229], v[210:213], v[84:87]
	v_mfma_f32_16x16x32_bf16 v[76:79], v[234:237], v[210:213], v[76:79]
	v_mfma_f32_16x16x32_bf16 v[68:71], v[226:229], v[218:221], v[68:71]
	v_mfma_f32_16x16x32_bf16 v[64:67], v[234:237], v[218:221], v[64:67]
	v_mfma_f32_16x16x32_bf16 v[116:119], v[230:233], v[174:177], v[116:119]
	v_mfma_f32_16x16x32_bf16 v[108:111], v[238:241], v[174:177], v[108:111]
	v_mfma_f32_16x16x32_bf16 v[100:103], v[230:233], v[182:185], v[100:103]
	v_mfma_f32_16x16x32_bf16 v[92:95], v[238:241], v[182:185], v[92:95]
	v_mfma_f32_16x16x32_bf16 v[84:87], v[230:233], v[214:217], v[84:87]
	v_mfma_f32_16x16x32_bf16 v[76:79], v[238:241], v[214:217], v[76:79]
	v_mfma_f32_16x16x32_bf16 v[68:71], v[230:233], v[222:225], v[68:71]
	v_mfma_f32_16x16x32_bf16 v[64:67], v[238:241], v[222:225], v[64:67]
	s_setprio 0
	s_mov_b32 m0, s31
	v_lshl_add_u64 v[244:245], s[22:23], 0, v[128:129]
	s_barrier
	ds_read_b128 v[170:173], v157 offset:16384
	ds_read_b128 v[174:177], v157 offset:17408
	ds_read_b128 v[178:181], v157 offset:18432
	ds_read_b128 v[182:185], v157 offset:19456
	ds_read_b128 v[210:213], v157 offset:20480
	ds_read_b128 v[214:217], v157 offset:21504
	ds_read_b128 v[218:221], v157 offset:22528
	ds_read_b128 v[222:225], v157 offset:23552
	global_load_lds_dwordx4 v[244:245], off
	v_lshl_add_u64 v[246:247], s[22:23], 0, v[130:131]
	s_mov_b32 m0, s33
	s_nop 0
	global_load_lds_dwordx4 v[246:247], off
	s_barrier
	s_waitcnt lgkmcnt(0)
	s_setprio 1
	v_mfma_f32_16x16x32_bf16 v[60:63], v[150:153], v[170:173], v[60:63]
	v_mfma_f32_16x16x32_bf16 v[56:59], v[162:165], v[170:173], v[56:59]
	v_mfma_f32_16x16x32_bf16 v[48:51], v[150:153], v[178:181], v[48:51]
	v_mfma_f32_16x16x32_bf16 v[40:43], v[162:165], v[178:181], v[40:43]
	v_mfma_f32_16x16x32_bf16 v[32:35], v[150:153], v[210:213], v[32:35]
	v_mfma_f32_16x16x32_bf16 v[24:27], v[162:165], v[210:213], v[24:27]
	v_mfma_f32_16x16x32_bf16 v[16:19], v[150:153], v[218:221], v[16:19]
	v_mfma_f32_16x16x32_bf16 v[8:11], v[162:165], v[218:221], v[8:11]
	v_mfma_f32_16x16x32_bf16 v[60:63], v[158:161], v[174:177], v[60:63]
	v_mfma_f32_16x16x32_bf16 v[56:59], v[166:169], v[174:177], v[56:59]
	v_mfma_f32_16x16x32_bf16 v[48:51], v[158:161], v[182:185], v[48:51]
	v_mfma_f32_16x16x32_bf16 v[40:43], v[166:169], v[182:185], v[40:43]
	v_mfma_f32_16x16x32_bf16 v[32:35], v[158:161], v[214:217], v[32:35]
	v_mfma_f32_16x16x32_bf16 v[24:27], v[166:169], v[214:217], v[24:27]
	v_mfma_f32_16x16x32_bf16 v[16:19], v[158:161], v[222:225], v[16:19]
	v_mfma_f32_16x16x32_bf16 v[8:11], v[166:169], v[222:225], v[8:11]
	s_setprio 0
	s_barrier
; #define PG8_STAGE(bufoff, gbase, voff) do { _Pragma("unroll") for (int _i = 0; _i < 2; ++_i) \
;         __builtin_amdgcn_global_load_lds((const unsigned*)((const char*)(gbase) + (voff)[_i]), (PG8_LAS unsigned*)(lds + (bufoff) + ldsw + _i * 8192), 16, 0, 0); } while (0)
; #define PG8_LDA(dst, b, h) do { _Pragma("unroll") for (int m = 0; m < 4; ++m) _Pragma("unroll") for (int k = 0; k < 2; ++k) dst[m][k] = *(const PG8_LAS bf16x8*)(lds + PG8_SA(b, h) + aoff + m * 2048 + k * 1024); } while (0)
; #define PG8_WAIT_V(n) asm volatile("s_waitcnt vmcnt(" #n ")" ::: "memory")
; template <class Epi, class Sched>
; __device__ __forceinline__ void gemm_phase(PG8_LAS unsigned char* lds, const Gemm g, const Sched& S, const Epi& E) {
;     ...
;         for (int t = 0; t < nt; t += 2) {
;             const bool last = (t == nt - 2);
;             const char* a1 = cA + (size_t)(t + 1) * kstep;
;             const char* a2 = last ? nA : cA + (size_t)(t + 2) * kstep; const char* b2 = last ? nB : cB + (size_t)(t + 2) * kstep;
;             const char* a3 = a2 + kstep; const char* b3 = b2 + kstep;
;             if (last && has_next) S.a_ready(nxt);
;             PG8_LDB(B0, 0, 0); PG8_SCHED; PG8_LDA(At, 0, 0); PG8_STAGE(PG8_SA(1, 1), a1 + hstep, voffA);
;             PG8_WAIT_L(8); PG8_BAR; PG8_WAIT_L(0); PG8_MMA(0, 0, At, B0); PG8_BAR; PG8_SCHED;
;             PG8_LDB(B1, 0, 1); PG8_STAGE(PG8_SB(0, 0), b2, voffB);
;             PG8_BAR; PG8_WAIT_L(0); PG8_MMA(0, 1, At, B1); PG8_BAR;
;             PG8_LDA(At, 0, 1); PG8_STAGE(PG8_SA(0, 0), a2, voffA);
;             PG8_BAR; PG8_WAIT_L(0); PG8_MMA(1, 0, At, B0); PG8_BAR; PG8_SCHED;
;             PG8_STAGE(PG8_SB(0, 1), b2 + hstep, voffB);
;             PG8_WAIT_V(6); PG8_BAR; PG8_MMA(1, 1, At, B1); PG8_BAR;
;             PG8_LDB(B0, 1, 0); PG8_SCHED; PG8_LDA(At, 1, 0); PG8_STAGE(PG8_SA(0, 1), a2 + hstep, voffA);
;             PG8_WAIT_L(8); PG8_BAR; PG8_WAIT_L(0); PG8_MMA(0, 0, At, B0); PG8_BAR; PG8_SCHED;
;             PG8_LDB(B1, 1, 1); PG8_STAGE(PG8_SB(1, 0), b3, voffB);
;             PG8_BAR; PG8_WAIT_L(0); PG8_MMA(0, 1, At, B1); PG8_BAR;
;             PG8_LDA(At, 1, 1); PG8_STAGE(PG8_SA(1, 0), a3, voffA);
;             PG8_BAR; PG8_WAIT_L(0); PG8_MMA(1, 0, At, B0); PG8_BAR; PG8_SCHED;
;             PG8_STAGE(PG8_SB(1, 1), b3 + hstep, voffB);
;             PG8_WAIT_V(6); PG8_BAR; PG8_MMA(1, 1, At, B1); PG8_BAR;
	s_add_u32 s60, s20, 0x40000
	s_addc_u32 s61, s21, 0
	s_add_i32 s62, s62, s30
	v_lshl_add_u64 v[150:151], s[60:61], 0, v[138:139]
	s_mov_b32 m0, s62
	s_nop 0
	global_load_lds_dwordx4 v[150:151], off
	v_lshl_add_u64 v[150:151], s[60:61], 0, v[132:133]
	s_add_i32 m0, s62, 0x2000
	s_nop 0
	global_load_lds_dwordx4 v[150:151], off
	s_waitcnt vmcnt(6)
	s_barrier
	s_setprio 1
	v_mfma_f32_16x16x32_bf16 v[52:55], v[226:229], v[170:173], v[52:55]
	v_mfma_f32_16x16x32_bf16 v[44:47], v[234:237], v[170:173], v[44:47]
	v_mfma_f32_16x16x32_bf16 v[36:39], v[226:229], v[178:181], v[36:39]
	v_mfma_f32_16x16x32_bf16 v[28:31], v[234:237], v[178:181], v[28:31]
	v_mfma_f32_16x16x32_bf16 v[20:23], v[226:229], v[210:213], v[20:23]
	v_mfma_f32_16x16x32_bf16 v[12:15], v[234:237], v[210:213], v[12:15]
	v_mfma_f32_16x16x32_bf16 v[4:7], v[226:229], v[218:221], v[4:7]
	v_mfma_f32_16x16x32_bf16 v[0:3], v[234:237], v[218:221], v[0:3]
	v_mfma_f32_16x16x32_bf16 v[52:55], v[230:233], v[174:177], v[52:55]
	v_mfma_f32_16x16x32_bf16 v[44:47], v[238:241], v[174:177], v[44:47]
	v_mfma_f32_16x16x32_bf16 v[36:39], v[230:233], v[182:185], v[36:39]
	v_mfma_f32_16x16x32_bf16 v[28:31], v[238:241], v[182:185], v[28:31]
	v_mfma_f32_16x16x32_bf16 v[20:23], v[230:233], v[214:217], v[20:23]
	v_mfma_f32_16x16x32_bf16 v[12:15], v[238:241], v[214:217], v[12:15]
	v_mfma_f32_16x16x32_bf16 v[4:7], v[230:233], v[222:225], v[4:7]
	v_mfma_f32_16x16x32_bf16 v[0:3], v[238:241], v[222:225], v[0:3]
	s_setprio 0
	s_add_i32 s60, s51, 0x100
	v_add_u32_e32 v166, s60, v155
	s_barrier
	ds_read_b128 v[150:153], v166
	ds_read_b128 v[158:161], v166 offset:1024
	ds_read_b128 v[162:165], v166 offset:2048
	ds_read_b128 v[166:169], v166 offset:3072
	s_add_u32 s22, s22, 0x40000
	s_addc_u32 s23, s23, 0
	s_mov_b32 m0, s34
	v_lshl_add_u64 v[226:227], s[22:23], 0, v[128:129]
	ds_read_b128 v[170:173], v157 offset:32768
	ds_read_b128 v[174:177], v157 offset:33792
	ds_read_b128 v[178:181], v157 offset:34816
	ds_read_b128 v[182:185], v157 offset:35840
	ds_read_b128 v[210:213], v157 offset:36864
	ds_read_b128 v[214:217], v157 offset:37888
	ds_read_b128 v[218:221], v157 offset:38912
	ds_read_b128 v[222:225], v157 offset:39936
	global_load_lds_dwordx4 v[226:227], off
	v_lshl_add_u64 v[226:227], s[22:23], 0, v[130:131]
	s_mov_b32 m0, s35
	s_nop 0
	global_load_lds_dwordx4 v[226:227], off
	s_waitcnt lgkmcnt(8)
	s_barrier
	s_waitcnt lgkmcnt(0)
	s_setprio 1
	v_mfma_f32_16x16x32_bf16 v[124:127], v[150:153], v[170:173], v[124:127]
	v_mfma_f32_16x16x32_bf16 v[120:123], v[162:165], v[170:173], v[120:123]
	v_mfma_f32_16x16x32_bf16 v[112:115], v[150:153], v[178:181], v[112:115]
	v_mfma_f32_16x16x32_bf16 v[104:107], v[162:165], v[178:181], v[104:107]
	v_mfma_f32_16x16x32_bf16 v[96:99], v[150:153], v[210:213], v[96:99]
	v_mfma_f32_16x16x32_bf16 v[88:91], v[162:165], v[210:213], v[88:91]
	v_mfma_f32_16x16x32_bf16 v[80:83], v[150:153], v[218:221], v[80:83]
	v_mfma_f32_16x16x32_bf16 v[72:75], v[162:165], v[218:221], v[72:75]
	v_mfma_f32_16x16x32_bf16 v[124:127], v[158:161], v[174:177], v[124:127]
	v_mfma_f32_16x16x32_bf16 v[120:123], v[166:169], v[174:177], v[120:123]
	v_mfma_f32_16x16x32_bf16 v[112:115], v[158:161], v[182:185], v[112:115]
	v_mfma_f32_16x16x32_bf16 v[104:107], v[166:169], v[182:185], v[104:107]
	v_mfma_f32_16x16x32_bf16 v[96:99], v[158:161], v[214:217], v[96:99]
	v_mfma_f32_16x16x32_bf16 v[88:91], v[166:169], v[214:217], v[88:91]
	v_mfma_f32_16x16x32_bf16 v[80:83], v[158:161], v[222:225], v[80:83]
	v_mfma_f32_16x16x32_bf16 v[72:75], v[166:169], v[222:225], v[72:75]
	s_setprio 0
	s_barrier
	s_add_i32 s22, s55, 0x100
	s_add_i32 s23, s60, s30
	v_add_u32_e32 v209, s22, v155
	v_lshl_add_u64 v[186:187], v[186:187], 0, s[94:95]
	s_mov_b32 m0, s23
	ds_read_b128 v[226:229], v209
	ds_read_b128 v[230:233], v209 offset:1024
	ds_read_b128 v[234:237], v209 offset:2048
	ds_read_b128 v[238:241], v209 offset:3072
	global_load_lds_dwordx4 v[186:187], off
	v_lshl_add_u64 v[186:187], v[242:243], 0, s[94:95]
	s_add_i32 m0, s23, 0x2000
	s_nop 0
	global_load_lds_dwordx4 v[186:187], off
	s_barrier
; #define PG8_BAR __builtin_amdgcn_s_barrier()
; template <class Epi, class Sched>
; __device__ __forceinline__ void gemm_phase(PG8_LAS unsigned char* lds, const Gemm g, const Sched& S, const Epi& E) {
;     ...
;         for (int t = 0; t < nt; t += 2) {
;             const bool last = (t == nt - 2);
;             const char* a1 = cA + (size_t)(t + 1) * kstep;
;             const char* a2 = last ? nA : cA + (size_t)(t + 2) * kstep; const char* b2 = last ? nB : cB + (size_t)(t + 2) * kstep;
;             const char* a3 = a2 + kstep; const char* b3 = b2 + kstep;
;             if (last && has_next) S.a_ready(nxt);
;             PG8_LDB(B0, 0, 0); PG8_SCHED; PG8_LDA(At, 0, 0); PG8_STAGE(PG8_SA(1, 1), a1 + hstep, voffA);
;             PG8_WAIT_L(8); PG8_BAR; PG8_WAIT_L(0); PG8_MMA(0, 0, At, B0); PG8_BAR; PG8_SCHED;
;             PG8_LDB(B1, 0, 1); PG8_STAGE(PG8_SB(0, 0), b2, voffB);
;             PG8_BAR; PG8_WAIT_L(0); PG8_MMA(0, 1, At, B1); PG8_BAR;
;             PG8_LDA(At, 0, 1); PG8_STAGE(PG8_SA(0, 0), a2, voffA);
;             PG8_BAR; PG8_WAIT_L(0); PG8_MMA(1, 0, At, B0); PG8_BAR; PG8_SCHED;
;             PG8_STAGE(PG8_SB(0, 1), b2 + hstep, voffB);
;             PG8_WAIT_V(6); PG8_BAR; PG8_MMA(1, 1, At, B1); PG8_BAR;
;             PG8_LDB(B0, 1, 0); PG8_SCHED; PG8_LDA(At, 1, 0); PG8_STAGE(PG8_SA(0, 1), a2 + hstep, voffA);
;             PG8_WAIT_L(8); PG8_BAR; PG8_WAIT_L(0); PG8_MMA(0, 0, At, B0); PG8_BAR; PG8_SCHED;
;             PG8_LDB(B1, 1, 1); PG8_STAGE(PG8_SB(1, 0), b3, voffB);
;             PG8_BAR; PG8_WAIT_L(0); PG8_MMA(0, 1, At, B1); PG8_BAR;
;             PG8_LDA(At, 1, 1); PG8_STAGE(PG8_SA(1, 0), a3, voffA);
;             PG8_BAR; PG8_WAIT_L(0); PG8_MMA(1, 0, At, B0); PG8_BAR; PG8_SCHED;
;             PG8_STAGE(PG8_SB(1, 1), b3 + hstep, voffB);
;             PG8_WAIT_V(6); PG8_BAR; PG8_MMA(1, 1, At, B1); PG8_BAR;
;   __device__ __forceinline__ void operator()(const f32x4 (&acc)[2][2][4][2], const pg8::Unit& u, int wr, int wc, int fr, int fq) const {
;     const int row0 = u.pm * 256 + wr * 64 + fr, col0 = u.pn * 256 + wc * 32 + 8 * fq;
; #pragma unroll
;     for (int ai = 0; ai < 2; ++ai)
; #pragma unroll
;       for (int m = 0; m < 4; ++m) {
;         bf16* rowp = O + (size_t)(row0 + ai * 128 + m * 16) * US + col0;
; #pragma unroll
;         for (int bj = 0; bj < 2; ++bj) {
;           if (col0 + bj * 128 < US) {
;             uint4 o;
	s_waitcnt lgkmcnt(0)
	s_setprio 1
	v_mfma_f32_16x16x32_bf16 v[116:119], v[226:229], v[170:173], v[116:119]
	v_mfma_f32_16x16x32_bf16 v[108:111], v[234:237], v[170:173], v[108:111]
	v_mfma_f32_16x16x32_bf16 v[100:103], v[226:229], v[178:181], v[100:103]
	v_mfma_f32_16x16x32_bf16 v[92:95], v[234:237], v[178:181], v[92:95]
	v_mfma_f32_16x16x32_bf16 v[84:87], v[226:229], v[210:213], v[84:87]
	v_mfma_f32_16x16x32_bf16 v[76:79], v[234:237], v[210:213], v[76:79]
	v_mfma_f32_16x16x32_bf16 v[68:71], v[226:229], v[218:221], v[68:71]
	v_mfma_f32_16x16x32_bf16 v[64:67], v[234:237], v[218:221], v[64:67]
	v_mfma_f32_16x16x32_bf16 v[116:119], v[230:233], v[174:177], v[116:119]
	v_mfma_f32_16x16x32_bf16 v[108:111], v[238:241], v[174:177], v[108:111]
	v_mfma_f32_16x16x32_bf16 v[100:103], v[230:233], v[182:185], v[100:103]
	v_mfma_f32_16x16x32_bf16 v[92:95], v[238:241], v[182:185], v[92:95]
	v_mfma_f32_16x16x32_bf16 v[84:87], v[230:233], v[214:217], v[84:87]
	v_mfma_f32_16x16x32_bf16 v[76:79], v[238:241], v[214:217], v[76:79]
	v_mfma_f32_16x16x32_bf16 v[68:71], v[230:233], v[222:225], v[68:71]
	v_mfma_f32_16x16x32_bf16 v[64:67], v[238:241], v[222:225], v[64:67]
	s_setprio 0
	s_mov_b32 m0, s36
	v_lshl_add_u64 v[186:187], v[244:245], 0, s[94:95]
	s_barrier
	ds_read_b128 v[170:173], v157 offset:49152
	ds_read_b128 v[174:177], v157 offset:50176
	ds_read_b128 v[178:181], v157 offset:51200
	ds_read_b128 v[182:185], v157 offset:52224
	ds_read_b128 v[210:213], v157 offset:53248
	ds_read_b128 v[214:217], v157 offset:54272
	ds_read_b128 v[218:221], v157 offset:55296
	ds_read_b128 v[222:225], v157 offset:56320
	global_load_lds_dwordx4 v[186:187], off
	v_lshl_add_u64 v[186:187], v[246:247], 0, s[94:95]
	s_mov_b32 m0, s37
	s_nop 0
	global_load_lds_dwordx4 v[186:187], off
	s_barrier
	s_waitcnt lgkmcnt(0)
	s_setprio 1
	v_mfma_f32_16x16x32_bf16 v[60:63], v[150:153], v[170:173], v[60:63]
	v_mfma_f32_16x16x32_bf16 v[56:59], v[162:165], v[170:173], v[56:59]
	v_mfma_f32_16x16x32_bf16 v[48:51], v[150:153], v[178:181], v[48:51]
	v_mfma_f32_16x16x32_bf16 v[40:43], v[162:165], v[178:181], v[40:43]
	v_mfma_f32_16x16x32_bf16 v[32:35], v[150:153], v[210:213], v[32:35]
	v_mfma_f32_16x16x32_bf16 v[24:27], v[162:165], v[210:213], v[24:27]
	v_mfma_f32_16x16x32_bf16 v[16:19], v[150:153], v[218:221], v[16:19]
	v_mfma_f32_16x16x32_bf16 v[8:11], v[162:165], v[218:221], v[8:11]
	v_mfma_f32_16x16x32_bf16 v[60:63], v[158:161], v[174:177], v[60:63]
	v_mfma_f32_16x16x32_bf16 v[56:59], v[166:169], v[174:177], v[56:59]
	v_mfma_f32_16x16x32_bf16 v[48:51], v[158:161], v[182:185], v[48:51]
	v_mfma_f32_16x16x32_bf16 v[40:43], v[166:169], v[182:185], v[40:43]
	v_mfma_f32_16x16x32_bf16 v[32:35], v[158:161], v[214:217], v[32:35]
	v_mfma_f32_16x16x32_bf16 v[24:27], v[166:169], v[214:217], v[24:27]
	v_mfma_f32_16x16x32_bf16 v[16:19], v[158:161], v[222:225], v[16:19]
	v_mfma_f32_16x16x32_bf16 v[8:11], v[166:169], v[222:225], v[8:11]
	s_setprio 0
	s_barrier
	s_add_u32 s20, s20, 0x40080
	s_addc_u32 s21, s21, 0
	s_add_i32 s22, s22, s30
	v_lshl_add_u64 v[150:151], s[20:21], 0, v[138:139]
	s_mov_b32 m0, s22
	s_nop 0
	global_load_lds_dwordx4 v[150:151], off
	v_lshl_add_u64 v[150:151], s[20:21], 0, v[132:133]
	s_add_i32 m0, s22, 0x2000
	s_nop 0
	global_load_lds_dwordx4 v[150:151], off
	s_waitcnt vmcnt(6)
	s_barrier
	s_setprio 1
	v_mfma_f32_16x16x32_bf16 v[52:55], v[226:229], v[170:173], v[52:55]
	v_mfma_f32_16x16x32_bf16 v[44:47], v[234:237], v[170:173], v[44:47]
	v_mfma_f32_16x16x32_bf16 v[36:39], v[226:229], v[178:181], v[36:39]
	v_mfma_f32_16x16x32_bf16 v[28:31], v[234:237], v[178:181], v[28:31]
	v_mfma_f32_16x16x32_bf16 v[20:23], v[226:229], v[210:213], v[20:23]
	v_mfma_f32_16x16x32_bf16 v[12:15], v[234:237], v[210:213], v[12:15]
	v_mfma_f32_16x16x32_bf16 v[4:7], v[226:229], v[218:221], v[4:7]
	v_mfma_f32_16x16x32_bf16 v[0:3], v[234:237], v[218:221], v[0:3]
	v_mfma_f32_16x16x32_bf16 v[52:55], v[230:233], v[174:177], v[52:55]
	v_mfma_f32_16x16x32_bf16 v[44:47], v[238:241], v[174:177], v[44:47]
	v_mfma_f32_16x16x32_bf16 v[36:39], v[230:233], v[182:185], v[36:39]
	v_mfma_f32_16x16x32_bf16 v[28:31], v[238:241], v[182:185], v[28:31]
	v_mfma_f32_16x16x32_bf16 v[20:23], v[230:233], v[214:217], v[20:23]
	v_mfma_f32_16x16x32_bf16 v[12:15], v[238:241], v[214:217], v[12:15]
	v_mfma_f32_16x16x32_bf16 v[4:7], v[230:233], v[222:225], v[4:7]
	v_mfma_f32_16x16x32_bf16 v[0:3], v[238:241], v[222:225], v[0:3]
	s_setprio 0
	s_add_i32 s59, s59, 2
	s_add_u32 s18, s18, 0x100
	s_addc_u32 s19, s19, 0
	s_add_u32 s40, s40, 0x100
	s_addc_u32 s41, s41, 0
	s_cmp_gt_u32 s59, 13
	s_barrier
	s_cbranch_scc0 .LBB0_114
	v_lshl_add_u32 v158, s16, 8, v154
	v_lshl_or_b32 v150, s0, 8, v156
	v_mov_b64_e32 v[152:153], s[4:5]
	v_ashrrev_i32_e32 v151, 31, v150
	v_mad_i64_i32 v[152:153], s[0:1], v158, s54, v[152:153]
	v_lshl_add_u64 v[152:153], v[150:151], 1, v[152:153]
	v_cmp_gt_i32_e32 vcc, s11, v150
	s_and_saveexec_b64 s[0:1], vcc
	s_cbranch_execz .LBB0_117
	v_cvt_pk_bf16_f32 v124, v124, v125
	v_cvt_pk_bf16_f32 v125, v126, v127
	v_cvt_pk_bf16_f32 v126, v120, v121
	v_cvt_pk_bf16_f32 v127, v122, v123
	global_store_dwordx4 v[152:153], v[124:127], off

; #define PG8_STAGE(bufoff, gbase, voff) do { _Pragma("unroll") for (int _i = 0; _i < 2; ++_i) \
;         __builtin_amdgcn_global_load_lds((const unsigned*)((const char*)(gbase) + (voff)[_i]), (PG8_LAS unsigned*)(lds + (bufoff) + ldsw + _i * 8192), 16, 0, 0); } while (0)
; #define PG8_LDA(dst, b, h) do { _Pragma("unroll") for (int m = 0; m < 4; ++m) _Pragma("unroll") for (int k = 0; k < 2; ++k) dst[m][k] = *(const PG8_LAS bf16x8*)(lds + PG8_SA(b, h) + aoff + m * 2048 + k * 1024); } while (0)
; #define PG8_WAIT_V(n) asm volatile("s_waitcnt vmcnt(" #n ")" ::: "memory")
; template <class Epi, class Sched>
; __device__ __forceinline__ void gemm_phase(PG8_LAS unsigned char* lds, const Gemm g, const Sched& S, const Epi& E) {
;     ...
;         for (int t = 0; t < nt; t += 2) {
;             const bool last = (t == nt - 2);
;             const char* a1 = cA + (size_t)(t + 1) * kstep;
;             const char* a2 = last ? nA : cA + (size_t)(t + 2) * kstep; const char* b2 = last ? nB : cB + (size_t)(t + 2) * kstep;
;             const char* a3 = a2 + kstep; const char* b3 = b2 + kstep;
;             if (last && has_next) S.a_ready(nxt);
;             PG8_LDB(B0, 0, 0); PG8_SCHED; PG8_LDA(At, 0, 0); PG8_STAGE(PG8_SA(1, 1), a1 + hstep, voffA);
;             PG8_WAIT_L(8); PG8_BAR; PG8_WAIT_L(0); PG8_MMA(0, 0, At, B0); PG8_BAR; PG8_SCHED;
;             PG8_LDB(B1, 0, 1); PG8_STAGE(PG8_SB(0, 0), b2, voffB);
;             PG8_BAR; PG8_WAIT_L(0); PG8_MMA(0, 1, At, B1); PG8_BAR;
;             PG8_LDA(At, 0, 1); PG8_STAGE(PG8_SA(0, 0), a2, voffA);
;             PG8_BAR; PG8_WAIT_L(0); PG8_MMA(1, 0, At, B0); PG8_BAR; PG8_SCHED;
;             PG8_STAGE(PG8_SB(0, 1), b2 + hstep, voffB);
;             PG8_WAIT_V(6); PG8_BAR; PG8_MMA(1, 1, At, B1); PG8_BAR;
;             PG8_LDB(B0, 1, 0); PG8_SCHED; PG8_LDA(At, 1, 0); PG8_STAGE(PG8_SA(0, 1), a2 + hstep, voffA);
;             PG8_WAIT_L(8); PG8_BAR; PG8_WAIT_L(0); PG8_MMA(0, 0, At, B0); PG8_BAR; PG8_SCHED;
;             PG8_LDB(B1, 1, 1); PG8_STAGE(PG8_SB(1, 0), b3, voffB);
;             PG8_BAR; PG8_WAIT_L(0); PG8_MMA(0, 1, At, B1); PG8_BAR;
;             PG8_LDA(At, 1, 1); PG8_STAGE(PG8_SA(1, 0), a3, voffA);
;             PG8_BAR; PG8_WAIT_L(0); PG8_MMA(1, 0, At, B0); PG8_BAR; PG8_SCHED;
;             PG8_STAGE(PG8_SB(1, 1), b3 + hstep, voffB);
;             PG8_WAIT_V(6); PG8_BAR; PG8_MMA(1, 1, At, B1); PG8_BAR;
.LBB0_803:
	s_add_u32 s12, s4, s24
	s_addc_u32 s13, s5, s25
	s_add_u32 s12, s12, 0x100
	s_addc_u32 s13, s13, 0
	s_add_u32 s26, s83, s24
	s_addc_u32 s27, s84, s25
	s_add_i32 s91, s46, 0x100
	v_add_u32_e32 v159, s91, v155
	ds_read_b128 v[160:163], v159
	ds_read_b128 v[164:167], v159 offset:1024
	ds_read_b128 v[168:171], v159 offset:2048
	ds_read_b128 v[172:175], v159 offset:3072
	s_cmpk_eq_i32 s24, 0x700
	s_cselect_b32 s29, s19, s13
	s_cselect_b32 s28, s85, s12
	s_cselect_b32 s27, s7, s27
	s_cselect_b32 s26, vcc_lo, s26
	v_lshl_add_u64 v[230:231], v[150:151], 0, s[24:25]
	s_add_i32 m0, s17, 0xc000
	ds_read_b128 v[176:179], v158
	ds_read_b128 v[180:183], v158 offset:1024
	ds_read_b128 v[184:187], v158 offset:2048
	ds_read_b128 v[210:213], v158 offset:3072
	ds_read_b128 v[214:217], v158 offset:4096
	ds_read_b128 v[218:221], v158 offset:5120
	ds_read_b128 v[222:225], v158 offset:6144
	ds_read_b128 v[226:229], v158 offset:7168
	global_load_lds_dwordx4 v[230:231], off
	v_lshl_add_u64 v[230:231], v[152:153], 0, s[24:25]
	s_add_i32 m0, s17, 0xe000
	s_nop 0
	global_load_lds_dwordx4 v[230:231], off
	s_waitcnt lgkmcnt(8)
	s_barrier
	s_waitcnt lgkmcnt(0)
	s_setprio 1
	v_mfma_f32_16x16x32_bf16 v[124:127], v[160:163], v[176:179], v[124:127]
	v_mfma_f32_16x16x32_bf16 v[120:123], v[168:171], v[176:179], v[120:123]
	v_mfma_f32_16x16x32_bf16 v[116:119], v[160:163], v[184:187], v[116:119]
	v_mfma_f32_16x16x32_bf16 v[112:115], v[168:171], v[184:187], v[112:115]
	v_mfma_f32_16x16x32_bf16 v[108:111], v[160:163], v[214:217], v[108:111]
	v_mfma_f32_16x16x32_bf16 v[104:107], v[168:171], v[214:217], v[104:107]
	v_mfma_f32_16x16x32_bf16 v[100:103], v[160:163], v[222:225], v[100:103]
	v_mfma_f32_16x16x32_bf16 v[96:99], v[168:171], v[222:225], v[96:99]
	v_mfma_f32_16x16x32_bf16 v[124:127], v[164:167], v[180:183], v[124:127]
	v_mfma_f32_16x16x32_bf16 v[120:123], v[172:175], v[180:183], v[120:123]
	v_mfma_f32_16x16x32_bf16 v[116:119], v[164:167], v[210:213], v[116:119]
	v_mfma_f32_16x16x32_bf16 v[112:115], v[172:175], v[210:213], v[112:115]
	v_mfma_f32_16x16x32_bf16 v[108:111], v[164:167], v[218:221], v[108:111]
	v_mfma_f32_16x16x32_bf16 v[104:107], v[172:175], v[218:221], v[104:107]
	v_mfma_f32_16x16x32_bf16 v[100:103], v[164:167], v[226:229], v[100:103]
	v_mfma_f32_16x16x32_bf16 v[96:99], v[172:175], v[226:229], v[96:99]
	s_setprio 0
	s_barrier
	s_add_i32 s69, s48, 0x100
	s_add_i32 s12, s91, s59
	v_add_u32_e32 v159, s69, v155
	v_lshl_add_u64 v[246:247], s[26:27], 0, v[138:139]
	s_mov_b32 m0, s12
	ds_read_b128 v[230:233], v159
	ds_read_b128 v[234:237], v159 offset:1024
	ds_read_b128 v[238:241], v159 offset:2048
	ds_read_b128 v[242:245], v159 offset:3072
	global_load_lds_dwordx4 v[246:247], off
	v_lshl_add_u64 v[248:249], s[26:27], 0, v[132:133]
	s_add_i32 m0, s12, 0x2000
	s_nop 0
	global_load_lds_dwordx4 v[248:249], off
	s_barrier
	s_waitcnt lgkmcnt(0)
	s_setprio 1
	v_mfma_f32_16x16x32_bf16 v[60:63], v[230:233], v[176:179], v[60:63]
	v_mfma_f32_16x16x32_bf16 v[56:59], v[238:241], v[176:179], v[56:59]
	v_mfma_f32_16x16x32_bf16 v[52:55], v[230:233], v[184:187], v[52:55]
	v_mfma_f32_16x16x32_bf16 v[48:51], v[238:241], v[184:187], v[48:51]
	v_mfma_f32_16x16x32_bf16 v[44:47], v[230:233], v[214:217], v[44:47]
	v_mfma_f32_16x16x32_bf16 v[40:43], v[238:241], v[214:217], v[40:43]
	v_mfma_f32_16x16x32_bf16 v[36:39], v[230:233], v[222:225], v[36:39]
	v_mfma_f32_16x16x32_bf16 v[32:35], v[238:241], v[222:225], v[32:35]
	v_mfma_f32_16x16x32_bf16 v[60:63], v[234:237], v[180:183], v[60:63]
	v_mfma_f32_16x16x32_bf16 v[56:59], v[242:245], v[180:183], v[56:59]
	v_mfma_f32_16x16x32_bf16 v[52:55], v[234:237], v[210:213], v[52:55]
	v_mfma_f32_16x16x32_bf16 v[48:51], v[242:245], v[210:213], v[48:51]
	v_mfma_f32_16x16x32_bf16 v[44:47], v[234:237], v[218:221], v[44:47]
	v_mfma_f32_16x16x32_bf16 v[40:43], v[242:245], v[218:221], v[40:43]
	v_mfma_f32_16x16x32_bf16 v[36:39], v[234:237], v[226:229], v[36:39]
	v_mfma_f32_16x16x32_bf16 v[32:35], v[242:245], v[226:229], v[32:35]
	s_setprio 0
	s_mov_b32 m0, s17
	v_lshl_add_u64 v[250:251], s[28:29], 0, v[128:129]
	s_barrier
	ds_read_b128 v[176:179], v158 offset:16384
	ds_read_b128 v[180:183], v158 offset:17408
	ds_read_b128 v[184:187], v158 offset:18432
	ds_read_b128 v[210:213], v158 offset:19456
	ds_read_b128 v[214:217], v158 offset:20480
	ds_read_b128 v[218:221], v158 offset:21504
	ds_read_b128 v[222:225], v158 offset:22528
	ds_read_b128 v[226:229], v158 offset:23552
	global_load_lds_dwordx4 v[250:251], off
	v_lshl_add_u64 v[252:253], s[28:29], 0, v[130:131]
	s_mov_b32 m0, s63
	s_nop 0
	global_load_lds_dwordx4 v[252:253], off
	s_barrier
	s_waitcnt lgkmcnt(0)
	s_setprio 1
	v_mfma_f32_16x16x32_bf16 v[92:95], v[160:163], v[176:179], v[92:95]
	v_mfma_f32_16x16x32_bf16 v[88:91], v[168:171], v[176:179], v[88:91]
	v_mfma_f32_16x16x32_bf16 v[84:87], v[160:163], v[184:187], v[84:87]
	v_mfma_f32_16x16x32_bf16 v[80:83], v[168:171], v[184:187], v[80:83]
	v_mfma_f32_16x16x32_bf16 v[76:79], v[160:163], v[214:217], v[76:79]
	v_mfma_f32_16x16x32_bf16 v[72:75], v[168:171], v[214:217], v[72:75]
	v_mfma_f32_16x16x32_bf16 v[68:71], v[160:163], v[222:225], v[68:71]
	v_mfma_f32_16x16x32_bf16 v[64:67], v[168:171], v[222:225], v[64:67]
	v_mfma_f32_16x16x32_bf16 v[92:95], v[164:167], v[180:183], v[92:95]
	v_mfma_f32_16x16x32_bf16 v[88:91], v[172:175], v[180:183], v[88:91]
	v_mfma_f32_16x16x32_bf16 v[84:87], v[164:167], v[210:213], v[84:87]
	v_mfma_f32_16x16x32_bf16 v[80:83], v[172:175], v[210:213], v[80:83]
	v_mfma_f32_16x16x32_bf16 v[76:79], v[164:167], v[218:221], v[76:79]
	v_mfma_f32_16x16x32_bf16 v[72:75], v[172:175], v[218:221], v[72:75]
	v_mfma_f32_16x16x32_bf16 v[68:71], v[164:167], v[226:229], v[68:71]
	v_mfma_f32_16x16x32_bf16 v[64:67], v[172:175], v[226:229], v[64:67]
	s_setprio 0
	s_barrier
; #define PG8_STAGE(bufoff, gbase, voff) do { _Pragma("unroll") for (int _i = 0; _i < 2; ++_i) \
;         __builtin_amdgcn_global_load_lds((const unsigned*)((const char*)(gbase) + (voff)[_i]), (PG8_LAS unsigned*)(lds + (bufoff) + ldsw + _i * 8192), 16, 0, 0); } while (0)
; #define PG8_LDA(dst, b, h) do { _Pragma("unroll") for (int m = 0; m < 4; ++m) _Pragma("unroll") for (int k = 0; k < 2; ++k) dst[m][k] = *(const PG8_LAS bf16x8*)(lds + PG8_SA(b, h) + aoff + m * 2048 + k * 1024); } while (0)
; #define PG8_WAIT_V(n) asm volatile("s_waitcnt vmcnt(" #n ")" ::: "memory")
; template <class Epi, class Sched>
; __device__ __forceinline__ void gemm_phase(PG8_LAS unsigned char* lds, const Gemm g, const Sched& S, const Epi& E) {
;     ...
;         for (int t = 0; t < nt; t += 2) {
;             const bool last = (t == nt - 2);
;             const char* a1 = cA + (size_t)(t + 1) * kstep;
;             const char* a2 = last ? nA : cA + (size_t)(t + 2) * kstep; const char* b2 = last ? nB : cB + (size_t)(t + 2) * kstep;
;             const char* a3 = a2 + kstep; const char* b3 = b2 + kstep;
;             if (last && has_next) S.a_ready(nxt);
;             PG8_LDB(B0, 0, 0); PG8_SCHED; PG8_LDA(At, 0, 0); PG8_STAGE(PG8_SA(1, 1), a1 + hstep, voffA);
;             PG8_WAIT_L(8); PG8_BAR; PG8_WAIT_L(0); PG8_MMA(0, 0, At, B0); PG8_BAR; PG8_SCHED;
;             PG8_LDB(B1, 0, 1); PG8_STAGE(PG8_SB(0, 0), b2, voffB);
;             PG8_BAR; PG8_WAIT_L(0); PG8_MMA(0, 1, At, B1); PG8_BAR;
;             PG8_LDA(At, 0, 1); PG8_STAGE(PG8_SA(0, 0), a2, voffA);
;             PG8_BAR; PG8_WAIT_L(0); PG8_MMA(1, 0, At, B0); PG8_BAR; PG8_SCHED;
;             PG8_STAGE(PG8_SB(0, 1), b2 + hstep, voffB);
;             PG8_WAIT_V(6); PG8_BAR; PG8_MMA(1, 1, At, B1); PG8_BAR;
;             PG8_LDB(B0, 1, 0); PG8_SCHED; PG8_LDA(At, 1, 0); PG8_STAGE(PG8_SA(0, 1), a2 + hstep, voffA);
;             PG8_WAIT_L(8); PG8_BAR; PG8_WAIT_L(0); PG8_MMA(0, 0, At, B0); PG8_BAR; PG8_SCHED;
;             PG8_LDB(B1, 1, 1); PG8_STAGE(PG8_SB(1, 0), b3, voffB);
;             PG8_BAR; PG8_WAIT_L(0); PG8_MMA(0, 1, At, B1); PG8_BAR;
;             PG8_LDA(At, 1, 1); PG8_STAGE(PG8_SA(1, 0), a3, voffA);
;             PG8_BAR; PG8_WAIT_L(0); PG8_MMA(1, 0, At, B0); PG8_BAR; PG8_SCHED;
;             PG8_STAGE(PG8_SB(1, 1), b3 + hstep, voffB);
;             PG8_WAIT_V(6); PG8_BAR; PG8_MMA(1, 1, At, B1); PG8_BAR;
	s_add_u32 s12, s26, 0x40000
	s_addc_u32 s13, s27, 0
	s_add_i32 s69, s69, s59
	v_lshl_add_u64 v[160:161], s[12:13], 0, v[138:139]
	s_mov_b32 m0, s69
	s_nop 0
	global_load_lds_dwordx4 v[160:161], off
	v_lshl_add_u64 v[160:161], s[12:13], 0, v[132:133]
	s_add_i32 m0, s69, 0x2000
	s_nop 0
	global_load_lds_dwordx4 v[160:161], off
	s_waitcnt vmcnt(6)
	s_barrier
	s_setprio 1
	v_mfma_f32_16x16x32_bf16 v[28:31], v[230:233], v[176:179], v[28:31]
	v_mfma_f32_16x16x32_bf16 v[24:27], v[238:241], v[176:179], v[24:27]
	v_mfma_f32_16x16x32_bf16 v[20:23], v[230:233], v[184:187], v[20:23]
	v_mfma_f32_16x16x32_bf16 v[16:19], v[238:241], v[184:187], v[16:19]
	v_mfma_f32_16x16x32_bf16 v[12:15], v[230:233], v[214:217], v[12:15]
	v_mfma_f32_16x16x32_bf16 v[8:11], v[238:241], v[214:217], v[8:11]
	v_mfma_f32_16x16x32_bf16 v[4:7], v[230:233], v[222:225], v[4:7]
	v_mfma_f32_16x16x32_bf16 v[0:3], v[238:241], v[222:225], v[0:3]
	v_mfma_f32_16x16x32_bf16 v[28:31], v[234:237], v[180:183], v[28:31]
	v_mfma_f32_16x16x32_bf16 v[24:27], v[242:245], v[180:183], v[24:27]
	v_mfma_f32_16x16x32_bf16 v[20:23], v[234:237], v[210:213], v[20:23]
	v_mfma_f32_16x16x32_bf16 v[16:19], v[242:245], v[210:213], v[16:19]
	v_mfma_f32_16x16x32_bf16 v[12:15], v[234:237], v[218:221], v[12:15]
	v_mfma_f32_16x16x32_bf16 v[8:11], v[242:245], v[218:221], v[8:11]
	v_mfma_f32_16x16x32_bf16 v[4:7], v[234:237], v[226:229], v[4:7]
	v_mfma_f32_16x16x32_bf16 v[0:3], v[242:245], v[226:229], v[0:3]
	s_setprio 0
	s_add_i32 s69, s51, 0x100
	v_add_u32_e32 v159, s69, v155
	s_barrier
	ds_read_b128 v[160:163], v159
	ds_read_b128 v[164:167], v159 offset:1024
	ds_read_b128 v[168:171], v159 offset:2048
	ds_read_b128 v[172:175], v159 offset:3072
	s_add_u32 s12, s28, 0x40000
	s_addc_u32 s13, s29, 0
	s_mov_b32 m0, s64
	v_lshl_add_u64 v[230:231], s[12:13], 0, v[128:129]
	ds_read_b128 v[176:179], v158 offset:32768
	ds_read_b128 v[180:183], v158 offset:33792
	ds_read_b128 v[184:187], v158 offset:34816
	ds_read_b128 v[210:213], v158 offset:35840
	ds_read_b128 v[214:217], v158 offset:36864
	ds_read_b128 v[218:221], v158 offset:37888
	ds_read_b128 v[222:225], v158 offset:38912
	ds_read_b128 v[226:229], v158 offset:39936
	global_load_lds_dwordx4 v[230:231], off
	v_lshl_add_u64 v[230:231], s[12:13], 0, v[130:131]
	s_mov_b32 m0, s65
	s_nop 0
	global_load_lds_dwordx4 v[230:231], off
	s_waitcnt lgkmcnt(8)
	s_barrier
	s_waitcnt lgkmcnt(0)
	s_setprio 1
	v_mfma_f32_16x16x32_bf16 v[124:127], v[160:163], v[176:179], v[124:127]
	v_mfma_f32_16x16x32_bf16 v[120:123], v[168:171], v[176:179], v[120:123]
	v_mfma_f32_16x16x32_bf16 v[116:119], v[160:163], v[184:187], v[116:119]
	v_mfma_f32_16x16x32_bf16 v[112:115], v[168:171], v[184:187], v[112:115]
	v_mfma_f32_16x16x32_bf16 v[108:111], v[160:163], v[214:217], v[108:111]
	v_mfma_f32_16x16x32_bf16 v[104:107], v[168:171], v[214:217], v[104:107]
	v_mfma_f32_16x16x32_bf16 v[100:103], v[160:163], v[222:225], v[100:103]
	v_mfma_f32_16x16x32_bf16 v[96:99], v[168:171], v[222:225], v[96:99]
	v_mfma_f32_16x16x32_bf16 v[124:127], v[164:167], v[180:183], v[124:127]
	v_mfma_f32_16x16x32_bf16 v[120:123], v[172:175], v[180:183], v[120:123]
	v_mfma_f32_16x16x32_bf16 v[116:119], v[164:167], v[210:213], v[116:119]
	v_mfma_f32_16x16x32_bf16 v[112:115], v[172:175], v[210:213], v[112:115]
	v_mfma_f32_16x16x32_bf16 v[108:111], v[164:167], v[218:221], v[108:111]
	v_mfma_f32_16x16x32_bf16 v[104:107], v[172:175], v[218:221], v[104:107]
	v_mfma_f32_16x16x32_bf16 v[100:103], v[164:167], v[226:229], v[100:103]
	v_mfma_f32_16x16x32_bf16 v[96:99], v[172:175], v[226:229], v[96:99]
	s_setprio 0
	s_barrier
	s_add_i32 s28, s55, 0x100
	s_add_i32 s12, s69, s59
	v_add_u32_e32 v159, s28, v155
	v_lshl_add_u64 v[246:247], v[246:247], 0, s[94:95]
	s_mov_b32 m0, s12
	ds_read_b128 v[230:233], v159
	ds_read_b128 v[234:237], v159 offset:1024
	ds_read_b128 v[238:241], v159 offset:2048
	ds_read_b128 v[242:245], v159 offset:3072
	global_load_lds_dwordx4 v[246:247], off
	v_lshl_add_u64 v[246:247], v[248:249], 0, s[94:95]
	s_add_i32 m0, s12, 0x2000
	s_nop 0
	global_load_lds_dwordx4 v[246:247], off
	s_barrier
	s_waitcnt lgkmcnt(0)
	s_setprio 1
	v_mfma_f32_16x16x32_bf16 v[60:63], v[230:233], v[176:179], v[60:63]
	v_mfma_f32_16x16x32_bf16 v[56:59], v[238:241], v[176:179], v[56:59]
	v_mfma_f32_16x16x32_bf16 v[52:55], v[230:233], v[184:187], v[52:55]
	v_mfma_f32_16x16x32_bf16 v[48:51], v[238:241], v[184:187], v[48:51]
	v_mfma_f32_16x16x32_bf16 v[44:47], v[230:233], v[214:217], v[44:47]
	v_mfma_f32_16x16x32_bf16 v[40:43], v[238:241], v[214:217], v[40:43]
	v_mfma_f32_16x16x32_bf16 v[36:39], v[230:233], v[222:225], v[36:39]
	v_mfma_f32_16x16x32_bf16 v[32:35], v[238:241], v[222:225], v[32:35]
	v_mfma_f32_16x16x32_bf16 v[60:63], v[234:237], v[180:183], v[60:63]
	v_mfma_f32_16x16x32_bf16 v[56:59], v[242:245], v[180:183], v[56:59]
	v_mfma_f32_16x16x32_bf16 v[52:55], v[234:237], v[210:213], v[52:55]
	v_mfma_f32_16x16x32_bf16 v[48:51], v[242:245], v[210:213], v[48:51]
	v_mfma_f32_16x16x32_bf16 v[44:47], v[234:237], v[218:221], v[44:47]
	v_mfma_f32_16x16x32_bf16 v[40:43], v[242:245], v[218:221], v[40:43]
	v_mfma_f32_16x16x32_bf16 v[36:39], v[234:237], v[226:229], v[36:39]
	v_mfma_f32_16x16x32_bf16 v[32:35], v[242:245], v[226:229], v[32:35]
	s_setprio 0
	s_mov_b32 m0, s66
	v_lshl_add_u64 v[246:247], v[250:251], 0, s[94:95]
	s_barrier
	ds_read_b128 v[176:179], v158 offset:49152
	ds_read_b128 v[180:183], v158 offset:50176
	ds_read_b128 v[184:187], v158 offset:51200
	ds_read_b128 v[210:213], v158 offset:52224
	ds_read_b128 v[214:217], v158 offset:53248
	ds_read_b128 v[218:221], v158 offset:54272
	ds_read_b128 v[222:225], v158 offset:55296
	ds_read_b128 v[226:229], v158 offset:56320
	global_load_lds_dwordx4 v[246:247], off
	v_lshl_add_u64 v[246:247], v[252:253], 0, s[94:95]
	s_mov_b32 m0, s67
	s_nop 0
	global_load_lds_dwordx4 v[246:247], off
	s_barrier
; #define PG8_WAIT_V(n) asm volatile("s_waitcnt vmcnt(" #n ")" ::: "memory")
; #define PG8_BAR __builtin_amdgcn_s_barrier()
; template <class Epi, class Sched>
; __device__ __forceinline__ void gemm_phase(PG8_LAS unsigned char* lds, const Gemm g, const Sched& S, const Epi& E) {
;     ...
;         for (int t = 0; t < nt; t += 2) {
;             const bool last = (t == nt - 2);
;             const char* a1 = cA + (size_t)(t + 1) * kstep;
;             const char* a2 = last ? nA : cA + (size_t)(t + 2) * kstep; const char* b2 = last ? nB : cB + (size_t)(t + 2) * kstep;
;             const char* a3 = a2 + kstep; const char* b3 = b2 + kstep;
;             if (last && has_next) S.a_ready(nxt);
;             PG8_LDB(B0, 0, 0); PG8_SCHED; PG8_LDA(At, 0, 0); PG8_STAGE(PG8_SA(1, 1), a1 + hstep, voffA);
;             PG8_WAIT_L(8); PG8_BAR; PG8_WAIT_L(0); PG8_MMA(0, 0, At, B0); PG8_BAR; PG8_SCHED;
;             PG8_LDB(B1, 0, 1); PG8_STAGE(PG8_SB(0, 0), b2, voffB);
;             PG8_BAR; PG8_WAIT_L(0); PG8_MMA(0, 1, At, B1); PG8_BAR;
;             PG8_LDA(At, 0, 1); PG8_STAGE(PG8_SA(0, 0), a2, voffA);
;             PG8_BAR; PG8_WAIT_L(0); PG8_MMA(1, 0, At, B0); PG8_BAR; PG8_SCHED;
;             PG8_STAGE(PG8_SB(0, 1), b2 + hstep, voffB);
;             PG8_WAIT_V(6); PG8_BAR; PG8_MMA(1, 1, At, B1); PG8_BAR;
;             PG8_LDB(B0, 1, 0); PG8_SCHED; PG8_LDA(At, 1, 0); PG8_STAGE(PG8_SA(0, 1), a2 + hstep, voffA);
;             PG8_WAIT_L(8); PG8_BAR; PG8_WAIT_L(0); PG8_MMA(0, 0, At, B0); PG8_BAR; PG8_SCHED;
;             PG8_LDB(B1, 1, 1); PG8_STAGE(PG8_SB(1, 0), b3, voffB);
;             PG8_BAR; PG8_WAIT_L(0); PG8_MMA(0, 1, At, B1); PG8_BAR;
;             PG8_LDA(At, 1, 1); PG8_STAGE(PG8_SA(1, 0), a3, voffA);
;             PG8_BAR; PG8_WAIT_L(0); PG8_MMA(1, 0, At, B0); PG8_BAR; PG8_SCHED;
;             PG8_STAGE(PG8_SB(1, 1), b3 + hstep, voffB);
;             PG8_WAIT_V(6); PG8_BAR; PG8_MMA(1, 1, At, B1); PG8_BAR;
;         }
;         if constexpr (!Epi::AFTER_DRAIN) { E(acc, cur, wr, wc, fr, fq); S.done(cur); }
;         if (!has_next) break;
; #pragma unroll
;         for (int a = 0; a < 2; ++a)
; #pragma unroll
;             for (int b = 0; b < 2; ++b)
; #pragma unroll
;                 for (int m = 0; m < 4; ++m)
; #pragma unroll
;                     for (int n = 0; n < 2; ++n) acc[a][b][m][n] = (f32x4){0.f, 0.f, 0.f, 0.f};
;         cur = nxt; cA = nA; cB = nB; ++ui;
	s_waitcnt lgkmcnt(0)
	s_setprio 1
	v_mfma_f32_16x16x32_bf16 v[92:95], v[160:163], v[176:179], v[92:95]
	v_mfma_f32_16x16x32_bf16 v[88:91], v[168:171], v[176:179], v[88:91]
	v_mfma_f32_16x16x32_bf16 v[84:87], v[160:163], v[184:187], v[84:87]
	v_mfma_f32_16x16x32_bf16 v[80:83], v[168:171], v[184:187], v[80:83]
	v_mfma_f32_16x16x32_bf16 v[76:79], v[160:163], v[214:217], v[76:79]
	v_mfma_f32_16x16x32_bf16 v[72:75], v[168:171], v[214:217], v[72:75]
	v_mfma_f32_16x16x32_bf16 v[68:71], v[160:163], v[222:225], v[68:71]
	v_mfma_f32_16x16x32_bf16 v[64:67], v[168:171], v[222:225], v[64:67]
	v_mfma_f32_16x16x32_bf16 v[92:95], v[164:167], v[180:183], v[92:95]
	v_mfma_f32_16x16x32_bf16 v[88:91], v[172:175], v[180:183], v[88:91]
	v_mfma_f32_16x16x32_bf16 v[84:87], v[164:167], v[210:213], v[84:87]
	v_mfma_f32_16x16x32_bf16 v[80:83], v[172:175], v[210:213], v[80:83]
	v_mfma_f32_16x16x32_bf16 v[76:79], v[164:167], v[218:221], v[76:79]
	v_mfma_f32_16x16x32_bf16 v[72:75], v[172:175], v[218:221], v[72:75]
	v_mfma_f32_16x16x32_bf16 v[68:71], v[164:167], v[226:229], v[68:71]
	v_mfma_f32_16x16x32_bf16 v[64:67], v[172:175], v[226:229], v[64:67]
	s_setprio 0
	s_barrier
	s_add_u32 s12, s26, 0x40080
	s_addc_u32 s13, s27, 0
	s_add_i32 s26, s28, s59
	v_lshl_add_u64 v[160:161], s[12:13], 0, v[138:139]
	s_mov_b32 m0, s26
	s_nop 0
	global_load_lds_dwordx4 v[160:161], off
	v_lshl_add_u64 v[160:161], s[12:13], 0, v[132:133]
	s_add_i32 m0, s26, 0x2000
	s_nop 0
	global_load_lds_dwordx4 v[160:161], off
	s_waitcnt vmcnt(6)
	s_barrier
	s_setprio 1
	v_mfma_f32_16x16x32_bf16 v[28:31], v[230:233], v[176:179], v[28:31]
	v_mfma_f32_16x16x32_bf16 v[24:27], v[238:241], v[176:179], v[24:27]
	v_mfma_f32_16x16x32_bf16 v[20:23], v[230:233], v[184:187], v[20:23]
	v_mfma_f32_16x16x32_bf16 v[16:19], v[238:241], v[184:187], v[16:19]
	v_mfma_f32_16x16x32_bf16 v[12:15], v[230:233], v[214:217], v[12:15]
	v_mfma_f32_16x16x32_bf16 v[8:11], v[238:241], v[214:217], v[8:11]
	v_mfma_f32_16x16x32_bf16 v[4:7], v[230:233], v[222:225], v[4:7]
	v_mfma_f32_16x16x32_bf16 v[0:3], v[238:241], v[222:225], v[0:3]
	v_mfma_f32_16x16x32_bf16 v[28:31], v[234:237], v[180:183], v[28:31]
	v_mfma_f32_16x16x32_bf16 v[24:27], v[242:245], v[180:183], v[24:27]
	v_mfma_f32_16x16x32_bf16 v[20:23], v[234:237], v[210:213], v[20:23]
	v_mfma_f32_16x16x32_bf16 v[16:19], v[242:245], v[210:213], v[16:19]
	v_mfma_f32_16x16x32_bf16 v[12:15], v[234:237], v[218:221], v[12:15]
	v_mfma_f32_16x16x32_bf16 v[8:11], v[242:245], v[218:221], v[8:11]
	v_mfma_f32_16x16x32_bf16 v[4:7], v[234:237], v[226:229], v[4:7]
	v_mfma_f32_16x16x32_bf16 v[0:3], v[242:245], v[226:229], v[0:3]
	s_setprio 0
	s_add_i32 vcc_hi, vcc_hi, 2
	s_add_u32 s24, s24, 0x100
	s_addc_u32 s25, s25, 0
	s_cmp_gt_u32 vcc_hi, 13
	s_barrier
	s_cbranch_scc0 .LBB0_803
	s_add_u32 s24, s83, 0xffffff00
	s_addc_u32 s25, s84, -1
	s_andn2_b64 vcc, exec, s[0:1]
	s_cbranch_vccnz .LBB0_806
	v_mov_b32_e32 v0, 0
	s_mov_b32 s34, s6
	s_mov_b32 s16, s18
	s_mov_b64 s[4:5], s[22:23]
	s_mov_b32 s68, s82
	v_mov_b32_e32 v1, v0
	v_mov_b32_e32 v2, v0
	v_mov_b32_e32 v3, v0
	v_mov_b32_e32 v4, v0
	v_mov_b32_e32 v5, v0
	v_mov_b32_e32 v6, v0
	v_mov_b32_e32 v7, v0
	v_mov_b32_e32 v8, v0
	v_mov_b32_e32 v9, v0
	v_mov_b32_e32 v10, v0
	v_mov_b32_e32 v11, v0
	v_mov_b32_e32 v12, v0
	v_mov_b32_e32 v13, v0
	v_mov_b32_e32 v14, v0
	v_mov_b32_e32 v15, v0
	v_mov_b32_e32 v16, v0
	v_mov_b32_e32 v17, v0
	v_mov_b32_e32 v18, v0
	v_mov_b32_e32 v19, v0
	v_mov_b32_e32 v20, v0
	v_mov_b32_e32 v21, v0
	v_mov_b32_e32 v22, v0
	v_mov_b32_e32 v23, v0
	v_mov_b32_e32 v24, v0
	v_mov_b32_e32 v25, v0
	v_mov_b32_e32 v26, v0
	v_mov_b32_e32 v27, v0
	v_mov_b32_e32 v28, v0
	v_mov_b32_e32 v29, v0
	v_mov_b32_e32 v30, v0
	v_mov_b32_e32 v31, v0
	v_mov_b32_e32 v64, v0
	v_mov_b32_e32 v65, v0
	v_mov_b32_e32 v66, v0
	v_mov_b32_e32 v67, v0
	v_mov_b32_e32 v68, v0
	v_mov_b32_e32 v69, v0
	v_mov_b32_e32 v70, v0
	v_mov_b32_e32 v71, v0
	v_mov_b32_e32 v72, v0
	v_mov_b32_e32 v73, v0
	v_mov_b32_e32 v74, v0
	v_mov_b32_e32 v75, v0
	v_mov_b32_e32 v76, v0
	v_mov_b32_e32 v77, v0
	v_mov_b32_e32 v78, v0
	v_mov_b32_e32 v79, v0
	v_mov_b32_e32 v80, v0
	v_mov_b32_e32 v81, v0
	v_mov_b32_e32 v82, v0
	v_mov_b32_e32 v83, v0
	v_mov_b32_e32 v84, v0
	v_mov_b32_e32 v85, v0
	v_mov_b32_e32 v86, v0
	v_mov_b32_e32 v87, v0
	v_mov_b32_e32 v88, v0
	v_mov_b32_e32 v89, v0
	v_mov_b32_e32 v90, v0
	v_mov_b32_e32 v91, v0
	v_mov_b32_e32 v92, v0
	v_mov_b32_e32 v93, v0
	v_mov_b32_e32 v94, v0
	v_mov_b32_e32 v95, v0
	v_mov_b32_e32 v32, v0
	v_mov_b32_e32 v33, v0
	v_mov_b32_e32 v34, v0
	v_mov_b32_e32 v35, v0
	v_mov_b32_e32 v36, v0
	v_mov_b32_e32 v37, v0
	v_mov_b32_e32 v38, v0
	v_mov_b32_e32 v39, v0
	v_mov_b32_e32 v40, v0
	v_mov_b32_e32 v41, v0
	v_mov_b32_e32 v42, v0
	v_mov_b32_e32 v43, v0
	v_mov_b32_e32 v44, v0
	v_mov_b32_e32 v45, v0
	v_mov_b32_e32 v46, v0
	v_mov_b32_e32 v47, v0
	v_mov_b32_e32 v48, v0
	v_mov_b32_e32 v49, v0
	v_mov_b32_e32 v50, v0
	v_mov_b32_e32 v51, v0
	v_mov_b32_e32 v52, v0
	v_mov_b32_e32 v53, v0
	v_mov_b32_e32 v54, v0
	v_mov_b32_e32 v55, v0
	v_mov_b32_e32 v56, v0
	v_mov_b32_e32 v57, v0
	v_mov_b32_e32 v58, v0
	v_mov_b32_e32 v59, v0
	v_mov_b32_e32 v60, v0
	v_mov_b32_e32 v61, v0
	v_mov_b32_e32 v62, v0
	v_mov_b32_e32 v63, v0
	v_mov_b32_e32 v96, v0
	v_mov_b32_e32 v97, v0
	v_mov_b32_e32 v98, v0
	v_mov_b32_e32 v99, v0
	v_mov_b32_e32 v100, v0
	v_mov_b32_e32 v101, v0
	v_mov_b32_e32 v102, v0
	v_mov_b32_e32 v103, v0
	v_mov_b32_e32 v104, v0
	v_mov_b32_e32 v105, v0
	v_mov_b32_e32 v106, v0
	v_mov_b32_e32 v107, v0
	v_mov_b32_e32 v108, v0
	v_mov_b32_e32 v109, v0
	v_mov_b32_e32 v110, v0
	v_mov_b32_e32 v111, v0
	v_mov_b32_e32 v112, v0
	v_mov_b32_e32 v113, v0
	v_mov_b32_e32 v114, v0
	v_mov_b32_e32 v115, v0
	v_mov_b32_e32 v116, v0
	v_mov_b32_e32 v117, v0
	v_mov_b32_e32 v118, v0
	v_mov_b32_e32 v119, v0
	v_mov_b32_e32 v120, v0
	v_mov_b32_e32 v121, v0
	v_mov_b32_e32 v122, v0
	v_mov_b32_e32 v123, v0
	v_mov_b32_e32 v124, v0
	v_mov_b32_e32 v125, v0
	v_mov_b32_e32 v126, v0
	v_mov_b32_e32 v127, v0
	s_mov_b32 s91, 0x12000
	s_andn2_b64 vcc, exec, s[2:3]
	s_cbranch_vccnz .LBB0_807
	s_branch .LBB0_808

; #define PG8_STAGE(bufoff, gbase, voff) do { _Pragma("unroll") for (int _i = 0; _i < 2; ++_i) \
;         __builtin_amdgcn_global_load_lds((const unsigned*)((const char*)(gbase) + (voff)[_i]), (PG8_LAS unsigned*)(lds + (bufoff) + ldsw + _i * 8192), 16, 0, 0); } while (0)
; #define PG8_LDA(dst, b, h) do { _Pragma("unroll") for (int m = 0; m < 4; ++m) _Pragma("unroll") for (int k = 0; k < 2; ++k) dst[m][k] = *(const PG8_LAS bf16x8*)(lds + PG8_SA(b, h) + aoff + m * 2048 + k * 1024); } while (0)
; #define PG8_WAIT_V(n) asm volatile("s_waitcnt vmcnt(" #n ")" ::: "memory")
; template <class Epi, class Sched>
; __device__ __forceinline__ void gemm_phase(PG8_LAS unsigned char* lds, const Gemm g, const Sched& S, const Epi& E) {
;     ...
;         for (int t = 0; t < nt; t += 2) {
;             const bool last = (t == nt - 2);
;             const char* a1 = cA + (size_t)(t + 1) * kstep;
;             const char* a2 = last ? nA : cA + (size_t)(t + 2) * kstep; const char* b2 = last ? nB : cB + (size_t)(t + 2) * kstep;
;             const char* a3 = a2 + kstep; const char* b3 = b2 + kstep;
;             if (last && has_next) S.a_ready(nxt);
;             PG8_LDB(B0, 0, 0); PG8_SCHED; PG8_LDA(At, 0, 0); PG8_STAGE(PG8_SA(1, 1), a1 + hstep, voffA);
;             PG8_WAIT_L(8); PG8_BAR; PG8_WAIT_L(0); PG8_MMA(0, 0, At, B0); PG8_BAR; PG8_SCHED;
;             PG8_LDB(B1, 0, 1); PG8_STAGE(PG8_SB(0, 0), b2, voffB);
;             PG8_BAR; PG8_WAIT_L(0); PG8_MMA(0, 1, At, B1); PG8_BAR;
;             PG8_LDA(At, 0, 1); PG8_STAGE(PG8_SA(0, 0), a2, voffA);
;             PG8_BAR; PG8_WAIT_L(0); PG8_MMA(1, 0, At, B0); PG8_BAR; PG8_SCHED;
;             PG8_STAGE(PG8_SB(0, 1), b2 + hstep, voffB);
;             PG8_WAIT_V(6); PG8_BAR; PG8_MMA(1, 1, At, B1); PG8_BAR;
;             PG8_LDB(B0, 1, 0); PG8_SCHED; PG8_LDA(At, 1, 0); PG8_STAGE(PG8_SA(0, 1), a2 + hstep, voffA);
;             PG8_WAIT_L(8); PG8_BAR; PG8_WAIT_L(0); PG8_MMA(0, 0, At, B0); PG8_BAR; PG8_SCHED;
;             PG8_LDB(B1, 1, 1); PG8_STAGE(PG8_SB(1, 0), b3, voffB);
;             PG8_BAR; PG8_WAIT_L(0); PG8_MMA(0, 1, At, B1); PG8_BAR;
;             PG8_LDA(At, 1, 1); PG8_STAGE(PG8_SA(1, 0), a3, voffA);
;             PG8_BAR; PG8_WAIT_L(0); PG8_MMA(1, 0, At, B0); PG8_BAR; PG8_SCHED;
;             PG8_STAGE(PG8_SB(1, 1), b3 + hstep, voffB);
;             PG8_WAIT_V(6); PG8_BAR; PG8_MMA(1, 1, At, B1); PG8_BAR;
.LBB0_997:
	s_add_u32 s12, s18, 0xfffc0080
	s_addc_u32 s13, s19, -1
	s_add_i32 s61, s46, 0x100
	v_add_u32_e32 v166, s61, v155
	ds_read_b128 v[150:153], v166
	ds_read_b128 v[158:161], v166 offset:1024
	ds_read_b128 v[162:165], v166 offset:2048
	ds_read_b128 v[166:169], v166 offset:3072
	s_cmp_eq_u32 s60, 12
	s_cselect_b32 s23, s7, s13
	s_cselect_b32 s22, s40, s12
	s_cselect_b32 s21, s5, s59
	s_cselect_b32 s20, s41, s58
	v_lshl_add_u64 v[186:187], s[18:19], 0, v[134:135]
	s_add_i32 m0, s17, 0xc000
	ds_read_b128 v[170:173], v157
	ds_read_b128 v[174:177], v157 offset:1024
	ds_read_b128 v[178:181], v157 offset:2048
	ds_read_b128 v[182:185], v157 offset:3072
	ds_read_b128 v[210:213], v157 offset:4096
	ds_read_b128 v[214:217], v157 offset:5120
	ds_read_b128 v[218:221], v157 offset:6144
	ds_read_b128 v[222:225], v157 offset:7168
	global_load_lds_dwordx4 v[186:187], off
	v_lshl_add_u64 v[186:187], s[18:19], 0, v[148:149]
	s_add_i32 m0, s17, 0xe000
	s_nop 0
	global_load_lds_dwordx4 v[186:187], off
	s_waitcnt lgkmcnt(8)
	s_barrier
	s_waitcnt lgkmcnt(0)
	s_setprio 1
	v_mfma_f32_16x16x32_bf16 v[124:127], v[150:153], v[170:173], v[124:127]
	v_mfma_f32_16x16x32_bf16 v[116:119], v[162:165], v[170:173], v[116:119]
	v_mfma_f32_16x16x32_bf16 v[108:111], v[150:153], v[178:181], v[108:111]
	v_mfma_f32_16x16x32_bf16 v[100:103], v[162:165], v[178:181], v[100:103]
	v_mfma_f32_16x16x32_bf16 v[92:95], v[150:153], v[210:213], v[92:95]
	v_mfma_f32_16x16x32_bf16 v[84:87], v[162:165], v[210:213], v[84:87]
	v_mfma_f32_16x16x32_bf16 v[76:79], v[150:153], v[218:221], v[76:79]
	v_mfma_f32_16x16x32_bf16 v[68:71], v[162:165], v[218:221], v[68:71]
	v_mfma_f32_16x16x32_bf16 v[124:127], v[158:161], v[174:177], v[124:127]
	v_mfma_f32_16x16x32_bf16 v[116:119], v[166:169], v[174:177], v[116:119]
	v_mfma_f32_16x16x32_bf16 v[108:111], v[158:161], v[182:185], v[108:111]
	v_mfma_f32_16x16x32_bf16 v[100:103], v[166:169], v[182:185], v[100:103]
	v_mfma_f32_16x16x32_bf16 v[92:95], v[158:161], v[214:217], v[92:95]
	v_mfma_f32_16x16x32_bf16 v[84:87], v[166:169], v[214:217], v[84:87]
	v_mfma_f32_16x16x32_bf16 v[76:79], v[158:161], v[222:225], v[76:79]
	v_mfma_f32_16x16x32_bf16 v[68:71], v[166:169], v[222:225], v[68:71]
	s_setprio 0
	s_barrier
	s_add_i32 s62, s48, 0x100
	v_add_u32_e32 v186, s62, v155
	s_add_i32 s12, s61, s31
	ds_read_b128 v[226:229], v186
	ds_read_b128 v[230:233], v186 offset:1024
	ds_read_b128 v[234:237], v186 offset:2048
	ds_read_b128 v[238:241], v186 offset:3072
	v_lshl_add_u64 v[186:187], s[20:21], 0, v[138:139]
	s_mov_b32 m0, s12
	v_lshl_add_u64 v[242:243], s[20:21], 0, v[132:133]
	global_load_lds_dwordx4 v[186:187], off
	s_add_i32 m0, s12, 0x2000
	s_nop 0
	global_load_lds_dwordx4 v[242:243], off
	s_barrier
	s_waitcnt lgkmcnt(0)
	s_setprio 1
	v_mfma_f32_16x16x32_bf16 v[120:123], v[226:229], v[170:173], v[120:123]
	v_mfma_f32_16x16x32_bf16 v[112:115], v[234:237], v[170:173], v[112:115]
	v_mfma_f32_16x16x32_bf16 v[104:107], v[226:229], v[178:181], v[104:107]
	v_mfma_f32_16x16x32_bf16 v[96:99], v[234:237], v[178:181], v[96:99]
	v_mfma_f32_16x16x32_bf16 v[88:91], v[226:229], v[210:213], v[88:91]
	v_mfma_f32_16x16x32_bf16 v[80:83], v[234:237], v[210:213], v[80:83]
	v_mfma_f32_16x16x32_bf16 v[72:75], v[226:229], v[218:221], v[72:75]
	v_mfma_f32_16x16x32_bf16 v[64:67], v[234:237], v[218:221], v[64:67]
	v_mfma_f32_16x16x32_bf16 v[120:123], v[230:233], v[174:177], v[120:123]
	v_mfma_f32_16x16x32_bf16 v[112:115], v[238:241], v[174:177], v[112:115]
	v_mfma_f32_16x16x32_bf16 v[104:107], v[230:233], v[182:185], v[104:107]
	v_mfma_f32_16x16x32_bf16 v[96:99], v[238:241], v[182:185], v[96:99]
	v_mfma_f32_16x16x32_bf16 v[88:91], v[230:233], v[214:217], v[88:91]
	v_mfma_f32_16x16x32_bf16 v[80:83], v[238:241], v[214:217], v[80:83]
	v_mfma_f32_16x16x32_bf16 v[72:75], v[230:233], v[222:225], v[72:75]
	v_mfma_f32_16x16x32_bf16 v[64:67], v[238:241], v[222:225], v[64:67]
	s_setprio 0
	s_mov_b32 m0, s17
	v_lshl_add_u64 v[244:245], s[22:23], 0, v[128:129]
	s_barrier
	ds_read_b128 v[170:173], v157 offset:16384
	ds_read_b128 v[174:177], v157 offset:17408
	ds_read_b128 v[178:181], v157 offset:18432
	ds_read_b128 v[182:185], v157 offset:19456
	ds_read_b128 v[210:213], v157 offset:20480
	ds_read_b128 v[214:217], v157 offset:21504
	ds_read_b128 v[218:221], v157 offset:22528
	ds_read_b128 v[222:225], v157 offset:23552
	global_load_lds_dwordx4 v[244:245], off
	v_lshl_add_u64 v[246:247], s[22:23], 0, v[130:131]
	s_mov_b32 m0, s33
	s_nop 0
	global_load_lds_dwordx4 v[246:247], off
	s_barrier
	s_waitcnt lgkmcnt(0)
	s_setprio 1
	v_mfma_f32_16x16x32_bf16 v[60:63], v[150:153], v[170:173], v[60:63]
	v_mfma_f32_16x16x32_bf16 v[52:55], v[162:165], v[170:173], v[52:55]
	v_mfma_f32_16x16x32_bf16 v[44:47], v[150:153], v[178:181], v[44:47]
	v_mfma_f32_16x16x32_bf16 v[36:39], v[162:165], v[178:181], v[36:39]
	v_mfma_f32_16x16x32_bf16 v[28:31], v[150:153], v[210:213], v[28:31]
	v_mfma_f32_16x16x32_bf16 v[20:23], v[162:165], v[210:213], v[20:23]
	v_mfma_f32_16x16x32_bf16 v[12:15], v[150:153], v[218:221], v[12:15]
	v_mfma_f32_16x16x32_bf16 v[4:7], v[162:165], v[218:221], v[4:7]
	v_mfma_f32_16x16x32_bf16 v[60:63], v[158:161], v[174:177], v[60:63]
	v_mfma_f32_16x16x32_bf16 v[52:55], v[166:169], v[174:177], v[52:55]
	v_mfma_f32_16x16x32_bf16 v[44:47], v[158:161], v[182:185], v[44:47]
	v_mfma_f32_16x16x32_bf16 v[36:39], v[166:169], v[182:185], v[36:39]
	v_mfma_f32_16x16x32_bf16 v[28:31], v[158:161], v[214:217], v[28:31]
	v_mfma_f32_16x16x32_bf16 v[20:23], v[166:169], v[214:217], v[20:23]
	v_mfma_f32_16x16x32_bf16 v[12:15], v[158:161], v[222:225], v[12:15]
	v_mfma_f32_16x16x32_bf16 v[4:7], v[166:169], v[222:225], v[4:7]
	s_setprio 0
	s_barrier
; #define PG8_STAGE(bufoff, gbase, voff) do { _Pragma("unroll") for (int _i = 0; _i < 2; ++_i) \
;         __builtin_amdgcn_global_load_lds((const unsigned*)((const char*)(gbase) + (voff)[_i]), (PG8_LAS unsigned*)(lds + (bufoff) + ldsw + _i * 8192), 16, 0, 0); } while (0)
; #define PG8_LDA(dst, b, h) do { _Pragma("unroll") for (int m = 0; m < 4; ++m) _Pragma("unroll") for (int k = 0; k < 2; ++k) dst[m][k] = *(const PG8_LAS bf16x8*)(lds + PG8_SA(b, h) + aoff + m * 2048 + k * 1024); } while (0)
; #define PG8_WAIT_V(n) asm volatile("s_waitcnt vmcnt(" #n ")" ::: "memory")
; template <class Epi, class Sched>
; __device__ __forceinline__ void gemm_phase(PG8_LAS unsigned char* lds, const Gemm g, const Sched& S, const Epi& E) {
;     ...
;         for (int t = 0; t < nt; t += 2) {
;             const bool last = (t == nt - 2);
;             const char* a1 = cA + (size_t)(t + 1) * kstep;
;             const char* a2 = last ? nA : cA + (size_t)(t + 2) * kstep; const char* b2 = last ? nB : cB + (size_t)(t + 2) * kstep;
;             const char* a3 = a2 + kstep; const char* b3 = b2 + kstep;
;             if (last && has_next) S.a_ready(nxt);
;             PG8_LDB(B0, 0, 0); PG8_SCHED; PG8_LDA(At, 0, 0); PG8_STAGE(PG8_SA(1, 1), a1 + hstep, voffA);
;             PG8_WAIT_L(8); PG8_BAR; PG8_WAIT_L(0); PG8_MMA(0, 0, At, B0); PG8_BAR; PG8_SCHED;
;             PG8_LDB(B1, 0, 1); PG8_STAGE(PG8_SB(0, 0), b2, voffB);
;             PG8_BAR; PG8_WAIT_L(0); PG8_MMA(0, 1, At, B1); PG8_BAR;
;             PG8_LDA(At, 0, 1); PG8_STAGE(PG8_SA(0, 0), a2, voffA);
;             PG8_BAR; PG8_WAIT_L(0); PG8_MMA(1, 0, At, B0); PG8_BAR; PG8_SCHED;
;             PG8_STAGE(PG8_SB(0, 1), b2 + hstep, voffB);
;             PG8_WAIT_V(6); PG8_BAR; PG8_MMA(1, 1, At, B1); PG8_BAR;
;             PG8_LDB(B0, 1, 0); PG8_SCHED; PG8_LDA(At, 1, 0); PG8_STAGE(PG8_SA(0, 1), a2 + hstep, voffA);
;             PG8_WAIT_L(8); PG8_BAR; PG8_WAIT_L(0); PG8_MMA(0, 0, At, B0); PG8_BAR; PG8_SCHED;
;             PG8_LDB(B1, 1, 1); PG8_STAGE(PG8_SB(1, 0), b3, voffB);
;             PG8_BAR; PG8_WAIT_L(0); PG8_MMA(0, 1, At, B1); PG8_BAR;
;             PG8_LDA(At, 1, 1); PG8_STAGE(PG8_SA(1, 0), a3, voffA);
;             PG8_BAR; PG8_WAIT_L(0); PG8_MMA(1, 0, At, B0); PG8_BAR; PG8_SCHED;
;             PG8_STAGE(PG8_SB(1, 1), b3 + hstep, voffB);
;             PG8_WAIT_V(6); PG8_BAR; PG8_MMA(1, 1, At, B1); PG8_BAR;
	s_add_u32 s12, s20, 0x40000
	s_addc_u32 s13, s21, 0
	s_add_i32 s61, s62, s31
	v_lshl_add_u64 v[150:151], s[12:13], 0, v[138:139]
	s_mov_b32 m0, s61
	s_nop 0
	global_load_lds_dwordx4 v[150:151], off
	v_lshl_add_u64 v[150:151], s[12:13], 0, v[132:133]
	s_add_i32 m0, s61, 0x2000
	s_nop 0
	global_load_lds_dwordx4 v[150:151], off
	s_waitcnt vmcnt(6)
	s_barrier
	s_setprio 1
	v_mfma_f32_16x16x32_bf16 v[56:59], v[226:229], v[170:173], v[56:59]
	v_mfma_f32_16x16x32_bf16 v[48:51], v[234:237], v[170:173], v[48:51]
	v_mfma_f32_16x16x32_bf16 v[40:43], v[226:229], v[178:181], v[40:43]
	v_mfma_f32_16x16x32_bf16 v[32:35], v[234:237], v[178:181], v[32:35]
	v_mfma_f32_16x16x32_bf16 v[24:27], v[226:229], v[210:213], v[24:27]
	v_mfma_f32_16x16x32_bf16 v[16:19], v[234:237], v[210:213], v[16:19]
	v_mfma_f32_16x16x32_bf16 v[8:11], v[226:229], v[218:221], v[8:11]
	v_mfma_f32_16x16x32_bf16 v[0:3], v[234:237], v[218:221], v[0:3]
	v_mfma_f32_16x16x32_bf16 v[56:59], v[230:233], v[174:177], v[56:59]
	v_mfma_f32_16x16x32_bf16 v[48:51], v[238:241], v[174:177], v[48:51]
	v_mfma_f32_16x16x32_bf16 v[40:43], v[230:233], v[182:185], v[40:43]
	v_mfma_f32_16x16x32_bf16 v[32:35], v[238:241], v[182:185], v[32:35]
	v_mfma_f32_16x16x32_bf16 v[24:27], v[230:233], v[214:217], v[24:27]
	v_mfma_f32_16x16x32_bf16 v[16:19], v[238:241], v[214:217], v[16:19]
	v_mfma_f32_16x16x32_bf16 v[8:11], v[230:233], v[222:225], v[8:11]
	v_mfma_f32_16x16x32_bf16 v[0:3], v[238:241], v[222:225], v[0:3]
	s_setprio 0
	s_add_i32 s61, s51, 0x100
	v_add_u32_e32 v166, s61, v155
	s_barrier
	ds_read_b128 v[150:153], v166
	ds_read_b128 v[158:161], v166 offset:1024
	ds_read_b128 v[162:165], v166 offset:2048
	ds_read_b128 v[166:169], v166 offset:3072
	s_add_u32 s12, s22, 0x40000
	s_addc_u32 s13, s23, 0
	s_mov_b32 m0, s34
	v_lshl_add_u64 v[226:227], s[12:13], 0, v[128:129]
	ds_read_b128 v[170:173], v157 offset:32768
	ds_read_b128 v[174:177], v157 offset:33792
	ds_read_b128 v[178:181], v157 offset:34816
	ds_read_b128 v[182:185], v157 offset:35840
	ds_read_b128 v[210:213], v157 offset:36864
	ds_read_b128 v[214:217], v157 offset:37888
	ds_read_b128 v[218:221], v157 offset:38912
	ds_read_b128 v[222:225], v157 offset:39936
	global_load_lds_dwordx4 v[226:227], off
	v_lshl_add_u64 v[226:227], s[12:13], 0, v[130:131]
	s_mov_b32 m0, s35
	s_nop 0
	global_load_lds_dwordx4 v[226:227], off
	s_waitcnt lgkmcnt(8)
	s_barrier
	s_waitcnt lgkmcnt(0)
	s_setprio 1
	v_mfma_f32_16x16x32_bf16 v[124:127], v[150:153], v[170:173], v[124:127]
	v_mfma_f32_16x16x32_bf16 v[116:119], v[162:165], v[170:173], v[116:119]
	v_mfma_f32_16x16x32_bf16 v[108:111], v[150:153], v[178:181], v[108:111]
	v_mfma_f32_16x16x32_bf16 v[100:103], v[162:165], v[178:181], v[100:103]
	v_mfma_f32_16x16x32_bf16 v[92:95], v[150:153], v[210:213], v[92:95]
	v_mfma_f32_16x16x32_bf16 v[84:87], v[162:165], v[210:213], v[84:87]
	v_mfma_f32_16x16x32_bf16 v[76:79], v[150:153], v[218:221], v[76:79]
	v_mfma_f32_16x16x32_bf16 v[68:71], v[162:165], v[218:221], v[68:71]
	v_mfma_f32_16x16x32_bf16 v[124:127], v[158:161], v[174:177], v[124:127]
	v_mfma_f32_16x16x32_bf16 v[116:119], v[166:169], v[174:177], v[116:119]
	v_mfma_f32_16x16x32_bf16 v[108:111], v[158:161], v[182:185], v[108:111]
	v_mfma_f32_16x16x32_bf16 v[100:103], v[166:169], v[182:185], v[100:103]
	v_mfma_f32_16x16x32_bf16 v[92:95], v[158:161], v[214:217], v[92:95]
	v_mfma_f32_16x16x32_bf16 v[84:87], v[166:169], v[214:217], v[84:87]
	v_mfma_f32_16x16x32_bf16 v[76:79], v[158:161], v[222:225], v[76:79]
	v_mfma_f32_16x16x32_bf16 v[68:71], v[166:169], v[222:225], v[68:71]
	s_setprio 0
	s_barrier
	s_add_i32 s22, s55, 0x100
	s_add_i32 s12, s61, s31
	v_add_u32_e32 v209, s22, v155
	v_lshl_add_u64 v[186:187], v[186:187], 0, s[94:95]
	s_mov_b32 m0, s12
	ds_read_b128 v[226:229], v209
	ds_read_b128 v[230:233], v209 offset:1024
	ds_read_b128 v[234:237], v209 offset:2048
	ds_read_b128 v[238:241], v209 offset:3072
	global_load_lds_dwordx4 v[186:187], off
	v_lshl_add_u64 v[186:187], v[242:243], 0, s[94:95]
	s_add_i32 m0, s12, 0x2000
	s_nop 0
	global_load_lds_dwordx4 v[186:187], off
	s_barrier
	s_waitcnt lgkmcnt(0)
	s_setprio 1
	v_mfma_f32_16x16x32_bf16 v[120:123], v[226:229], v[170:173], v[120:123]
	v_mfma_f32_16x16x32_bf16 v[112:115], v[234:237], v[170:173], v[112:115]
	v_mfma_f32_16x16x32_bf16 v[104:107], v[226:229], v[178:181], v[104:107]
	v_mfma_f32_16x16x32_bf16 v[96:99], v[234:237], v[178:181], v[96:99]
	v_mfma_f32_16x16x32_bf16 v[88:91], v[226:229], v[210:213], v[88:91]
	v_mfma_f32_16x16x32_bf16 v[80:83], v[234:237], v[210:213], v[80:83]
	v_mfma_f32_16x16x32_bf16 v[72:75], v[226:229], v[218:221], v[72:75]
	v_mfma_f32_16x16x32_bf16 v[64:67], v[234:237], v[218:221], v[64:67]
	v_mfma_f32_16x16x32_bf16 v[120:123], v[230:233], v[174:177], v[120:123]
	v_mfma_f32_16x16x32_bf16 v[112:115], v[238:241], v[174:177], v[112:115]
	v_mfma_f32_16x16x32_bf16 v[104:107], v[230:233], v[182:185], v[104:107]
	v_mfma_f32_16x16x32_bf16 v[96:99], v[238:241], v[182:185], v[96:99]
	v_mfma_f32_16x16x32_bf16 v[88:91], v[230:233], v[214:217], v[88:91]
	v_mfma_f32_16x16x32_bf16 v[80:83], v[238:241], v[214:217], v[80:83]
	v_mfma_f32_16x16x32_bf16 v[72:75], v[230:233], v[222:225], v[72:75]
	v_mfma_f32_16x16x32_bf16 v[64:67], v[238:241], v[222:225], v[64:67]
	s_setprio 0
	s_mov_b32 m0, s36
	v_lshl_add_u64 v[186:187], v[244:245], 0, s[94:95]
	s_barrier
	ds_read_b128 v[170:173], v157 offset:49152
	ds_read_b128 v[174:177], v157 offset:50176
	ds_read_b128 v[178:181], v157 offset:51200
	ds_read_b128 v[182:185], v157 offset:52224
	ds_read_b128 v[210:213], v157 offset:53248
	ds_read_b128 v[214:217], v157 offset:54272
	ds_read_b128 v[218:221], v157 offset:55296
	ds_read_b128 v[222:225], v157 offset:56320
	global_load_lds_dwordx4 v[186:187], off
	v_lshl_add_u64 v[186:187], v[246:247], 0, s[94:95]
	s_mov_b32 m0, s37
	s_nop 0
	global_load_lds_dwordx4 v[186:187], off
	s_barrier
;   __device__ __forceinline__ bf16* y() const { unsigned o_ = (unsigned)(OFF_y); asm volatile("" : "+s"(o_)); return (bf16*)(ws + o_); }
; __device__ __forceinline__ unsigned pk2(float a, float b) { unsigned r; asm("v_cvt_pk_bf16_f32 %0, %1, %2" : "=v"(r) : "v"(a), "v"(b)); return r; }
; __device__ __forceinline__ float silu(float x) { return x * sigm(x); }
; #define PG8_LDA(dst, b, h) do { _Pragma("unroll") for (int m = 0; m < 4; ++m) _Pragma("unroll") for (int k = 0; k < 2; ++k) dst[m][k] = *(const PG8_LAS bf16x8*)(lds + PG8_SA(b, h) + aoff + m * 2048 + k * 1024); } while (0)
; #define PG8_BAR __builtin_amdgcn_s_barrier()
; template <class Epi, class Sched>
; __device__ __forceinline__ void gemm_phase(PG8_LAS unsigned char* lds, const Gemm g, const Sched& S, const Epi& E) {
;     ...
;             PG8_WAIT_V(6); PG8_BAR; PG8_MMA(1, 1, At, B1); PG8_BAR;
;             PG8_LDB(B0, 1, 0); PG8_SCHED; PG8_LDA(At, 1, 0); PG8_STAGE(PG8_SA(0, 1), a2 + hstep, voffA);
;             PG8_WAIT_L(8); PG8_BAR; PG8_WAIT_L(0); PG8_MMA(0, 0, At, B0); PG8_BAR; PG8_SCHED;
;             PG8_LDB(B1, 1, 1); PG8_STAGE(PG8_SB(1, 0), b3, voffB);
;             PG8_BAR; PG8_WAIT_L(0); PG8_MMA(0, 1, At, B1); PG8_BAR;
;             PG8_LDA(At, 1, 1); PG8_STAGE(PG8_SA(1, 0), a3, voffA);
;             PG8_BAR; PG8_WAIT_L(0); PG8_MMA(1, 0, At, B0); PG8_BAR; PG8_SCHED;
;             PG8_STAGE(PG8_SB(1, 1), b3 + hstep, voffB);
;             PG8_WAIT_V(6); PG8_BAR; PG8_MMA(1, 1, At, B1); PG8_BAR;
;         }
;         if constexpr (!Epi::AFTER_DRAIN) { E(acc, cur, wr, wc, fr, fq); S.done(cur); }
;   __device__ __forceinline__ void operator()(const f32x4 (&acc)[2][2][4][2], const pg8::Unit& u, int wr, int wc, int fr, int fq) const {
;     const int row0 = u.pm * 256 + wr * 64 + fr, col0 = u.pn * 128 + wc * 32 + 8 * fq;
; #pragma unroll
;     for (int ai = 0; ai < 2; ++ai)
; #pragma unroll
;       for (int m = 0; m < 4; ++m) {
;         bf16* rowp = O + (size_t)(row0 + ai * 128 + m * 16) * FF + col0;
;         const f32x4 g0 = acc[ai][0][m][0], g1 = acc[ai][0][m][1], u0 = acc[ai][1][m][0], u1 = acc[ai][1][m][1];
;         uint4 o;
;         o.x = pk2(silu(g0[0]) * u0[0], silu(g0[1]) * u0[1]); o.y = pk2(silu(g0[2]) * u0[2], silu(g0[3]) * u0[3]);
;         o.z = pk2(silu(g1[0]) * u1[0], silu(g1[1]) * u1[1]); o.w = pk2(silu(g1[2]) * u1[2], silu(g1[3]) * u1[3]);
;         *(uint4*)rowp = o;
;       }
;   }
	s_waitcnt lgkmcnt(0)
	s_setprio 1
	v_mfma_f32_16x16x32_bf16 v[60:63], v[150:153], v[170:173], v[60:63]
	v_mfma_f32_16x16x32_bf16 v[52:55], v[162:165], v[170:173], v[52:55]
	v_mfma_f32_16x16x32_bf16 v[44:47], v[150:153], v[178:181], v[44:47]
	v_mfma_f32_16x16x32_bf16 v[36:39], v[162:165], v[178:181], v[36:39]
	v_mfma_f32_16x16x32_bf16 v[28:31], v[150:153], v[210:213], v[28:31]
	v_mfma_f32_16x16x32_bf16 v[20:23], v[162:165], v[210:213], v[20:23]
	v_mfma_f32_16x16x32_bf16 v[12:15], v[150:153], v[218:221], v[12:15]
	v_mfma_f32_16x16x32_bf16 v[4:7], v[162:165], v[218:221], v[4:7]
	v_mfma_f32_16x16x32_bf16 v[60:63], v[158:161], v[174:177], v[60:63]
	v_mfma_f32_16x16x32_bf16 v[52:55], v[166:169], v[174:177], v[52:55]
	v_mfma_f32_16x16x32_bf16 v[44:47], v[158:161], v[182:185], v[44:47]
	v_mfma_f32_16x16x32_bf16 v[36:39], v[166:169], v[182:185], v[36:39]
	v_mfma_f32_16x16x32_bf16 v[28:31], v[158:161], v[214:217], v[28:31]
	v_mfma_f32_16x16x32_bf16 v[20:23], v[166:169], v[214:217], v[20:23]
	v_mfma_f32_16x16x32_bf16 v[12:15], v[158:161], v[222:225], v[12:15]
	v_mfma_f32_16x16x32_bf16 v[4:7], v[166:169], v[222:225], v[4:7]
	s_setprio 0
	s_barrier
	s_add_u32 s12, s20, 0x40080
	s_addc_u32 s13, s21, 0
	s_add_i32 s20, s22, s31
	v_lshl_add_u64 v[150:151], s[12:13], 0, v[138:139]
	s_mov_b32 m0, s20
	s_nop 0
	global_load_lds_dwordx4 v[150:151], off
	v_lshl_add_u64 v[150:151], s[12:13], 0, v[132:133]
	s_add_i32 m0, s20, 0x2000
	s_nop 0
	global_load_lds_dwordx4 v[150:151], off
	s_waitcnt vmcnt(6)
	s_barrier
	s_setprio 1
	v_mfma_f32_16x16x32_bf16 v[56:59], v[226:229], v[170:173], v[56:59]
	v_mfma_f32_16x16x32_bf16 v[48:51], v[234:237], v[170:173], v[48:51]
	v_mfma_f32_16x16x32_bf16 v[40:43], v[226:229], v[178:181], v[40:43]
	v_mfma_f32_16x16x32_bf16 v[32:35], v[234:237], v[178:181], v[32:35]
	v_mfma_f32_16x16x32_bf16 v[24:27], v[226:229], v[210:213], v[24:27]
	v_mfma_f32_16x16x32_bf16 v[16:19], v[234:237], v[210:213], v[16:19]
	v_mfma_f32_16x16x32_bf16 v[8:11], v[226:229], v[218:221], v[8:11]
	v_mfma_f32_16x16x32_bf16 v[0:3], v[234:237], v[218:221], v[0:3]
	v_mfma_f32_16x16x32_bf16 v[56:59], v[230:233], v[174:177], v[56:59]
	v_mfma_f32_16x16x32_bf16 v[48:51], v[238:241], v[174:177], v[48:51]
	v_mfma_f32_16x16x32_bf16 v[40:43], v[230:233], v[182:185], v[40:43]
	v_mfma_f32_16x16x32_bf16 v[32:35], v[238:241], v[182:185], v[32:35]
	v_mfma_f32_16x16x32_bf16 v[24:27], v[230:233], v[214:217], v[24:27]
	v_mfma_f32_16x16x32_bf16 v[16:19], v[238:241], v[214:217], v[16:19]
	v_mfma_f32_16x16x32_bf16 v[8:11], v[230:233], v[222:225], v[8:11]
	v_mfma_f32_16x16x32_bf16 v[0:3], v[238:241], v[222:225], v[0:3]
	s_setprio 0
	s_add_i32 s60, s60, 2
	s_add_u32 s18, s18, 0x100
	s_addc_u32 s19, s19, 0
	s_add_u32 s58, s58, 0x100
	s_addc_u32 s59, s59, 0
	s_cmp_gt_u32 s60, 13
	s_barrier
	s_cbranch_scc0 .LBB0_997
	v_mul_f32_e32 v159, 0xbfb8aa3b, v124
	v_exp_f32_e32 v159, v159
	v_lshl_add_u32 v158, s16, 8, v154
	v_lshl_or_b32 v152, s39, 7, v156
	v_ashrrev_i32_e32 v153, 31, v152
	v_add_f32_e32 v159, 1.0, v159
	v_rcp_f32_e32 v159, v159
	v_mov_b64_e32 v[150:151], s[0:1]
	v_mad_i64_i32 v[160:161], s[12:13], v158, s52, v[150:151]
	v_mul_f32_e32 v124, v124, v159
	v_mul_f32_e32 v120, v124, v120
	v_mul_f32_e32 v124, 0xbfb8aa3b, v125
	v_exp_f32_e32 v124, v124
	v_lshlrev_b64 v[152:153], 1, v[152:153]
	v_lshl_add_u64 v[160:161], v[160:161], 0, v[152:153]
	s_and_b64 vcc, exec, s[2:3]
	v_add_f32_e32 v124, 1.0, v124
	v_rcp_f32_e32 v124, v124
	s_mov_b32 s39, s4
	s_mov_b32 s16, s6
	s_mov_b64 s[20:21], s[14:15]
	v_mul_f32_e32 v124, v125, v124
	v_mul_f32_e32 v121, v124, v121
	v_cvt_pk_bf16_f32 v120, v120, v121
	v_mul_f32_e32 v121, 0xbfb8aa3b, v126
	v_exp_f32_e32 v121, v121
	s_mov_b64 s[18:19], s[8:9]
	v_add_f32_e32 v121, 1.0, v121
	v_rcp_f32_e32 v121, v121
	s_nop 0
	v_mul_f32_e32 v121, v126, v121
	v_mul_f32_e32 v121, v121, v122
	v_mul_f32_e32 v122, 0xbfb8aa3b, v127
	v_exp_f32_e32 v122, v122
	s_nop 0
	v_add_f32_e32 v122, 1.0, v122
	v_rcp_f32_e32 v122, v122
	s_nop 0
	v_mul_f32_e32 v122, v127, v122
	v_mul_f32_e32 v122, v122, v123
	v_cvt_pk_bf16_f32 v121, v121, v122
	v_mul_f32_e32 v122, 0xbfb8aa3b, v116
	v_exp_f32_e32 v122, v122
	s_nop 0
	v_add_f32_e32 v122, 1.0, v122
	v_rcp_f32_e32 v122, v122
	s_nop 0
	v_mul_f32_e32 v116, v116, v122
	v_mul_f32_e32 v112, v116, v112
	v_mul_f32_e32 v116, 0xbfb8aa3b, v117
	v_exp_f32_e32 v116, v116
	s_nop 0
	v_add_f32_e32 v116, 1.0, v116
	v_rcp_f32_e32 v116, v116
	s_nop 0
	v_mul_f32_e32 v116, v117, v116
	v_mul_f32_e32 v113, v116, v113
	v_cvt_pk_bf16_f32 v122, v112, v113
	v_mul_f32_e32 v112, 0xbfb8aa3b, v118
	v_exp_f32_e32 v112, v112
	v_mul_f32_e32 v113, 0xbfb8aa3b, v119
	v_exp_f32_e32 v113, v113
	v_add_f32_e32 v112, 1.0, v112
	v_rcp_f32_e32 v112, v112
	v_add_f32_e32 v113, 1.0, v113
	v_rcp_f32_e32 v113, v113
	v_mul_f32_e32 v112, v118, v112
	v_mul_f32_e32 v112, v112, v114
	v_mul_f32_e32 v114, 0xbfb8aa3b, v108
	v_exp_f32_e32 v114, v114
	v_mul_f32_e32 v113, v119, v113
	v_mul_f32_e32 v113, v113, v115
	v_cvt_pk_bf16_f32 v123, v112, v113
	v_add_f32_e32 v114, 1.0, v114
	v_rcp_f32_e32 v114, v114
	v_or_b32_e32 v112, 16, v158
	v_mad_i64_i32 v[112:113], s[12:13], v112, s52, v[150:151]
	v_mul_f32_e32 v108, v108, v114
	v_mul_f32_e32 v104, v108, v104
	v_mul_f32_e32 v108, 0xbfb8aa3b, v109
	v_exp_f32_e32 v108, v108
	v_lshl_add_u64 v[112:113], v[112:113], 0, v[152:153]
	global_store_dwordx4 v[160:161], v[120:123], off
	v_add_f32_e32 v108, 1.0, v108
	v_rcp_f32_e32 v108, v108
	s_nop 0
	v_mul_f32_e32 v108, v109, v108
	v_mul_f32_e32 v105, v108, v105
	v_cvt_pk_bf16_f32 v104, v104, v105
	v_mul_f32_e32 v105, 0xbfb8aa3b, v110
	v_exp_f32_e32 v105, v105
	s_nop 0
	v_add_f32_e32 v105, 1.0, v105
;   __device__ __forceinline__ bf16* y() const { unsigned o_ = (unsigned)(OFF_y); asm volatile("" : "+s"(o_)); return (bf16*)(ws + o_); }
; __device__ __forceinline__ unsigned pk2(float a, float b) { unsigned r; asm("v_cvt_pk_bf16_f32 %0, %1, %2" : "=v"(r) : "v"(a), "v"(b)); return r; }
; __device__ __forceinline__ float silu(float x) { return x * sigm(x); }
;   __device__ __forceinline__ void operator()(const f32x4 (&acc)[2][2][4][2], const pg8::Unit& u, int wr, int wc, int fr, int fq) const {
;     const int row0 = u.pm * 256 + wr * 64 + fr, col0 = u.pn * 128 + wc * 32 + 8 * fq;
; #pragma unroll
;     for (int ai = 0; ai < 2; ++ai)
; #pragma unroll
;       for (int m = 0; m < 4; ++m) {
;         bf16* rowp = O + (size_t)(row0 + ai * 128 + m * 16) * FF + col0;
;         const f32x4 g0 = acc[ai][0][m][0], g1 = acc[ai][0][m][1], u0 = acc[ai][1][m][0], u1 = acc[ai][1][m][1];
;         uint4 o;
;         o.x = pk2(silu(g0[0]) * u0[0], silu(g0[1]) * u0[1]); o.y = pk2(silu(g0[2]) * u0[2], silu(g0[3]) * u0[3]);
;         o.z = pk2(silu(g1[0]) * u1[0], silu(g1[1]) * u1[1]); o.w = pk2(silu(g1[2]) * u1[2], silu(g1[3]) * u1[3]);
;         *(uint4*)rowp = o;
;       }
;   }
	v_rcp_f32_e32 v105, v105
	s_nop 0
	v_mul_f32_e32 v105, v110, v105
	v_mul_f32_e32 v105, v105, v106
	v_mul_f32_e32 v106, 0xbfb8aa3b, v111
	v_exp_f32_e32 v106, v106
	s_nop 0
	v_add_f32_e32 v106, 1.0, v106
	v_rcp_f32_e32 v106, v106
	s_nop 0
	v_mul_f32_e32 v106, v111, v106
	v_mul_f32_e32 v106, v106, v107
	v_cvt_pk_bf16_f32 v105, v105, v106
	v_mul_f32_e32 v106, 0xbfb8aa3b, v100
	v_exp_f32_e32 v106, v106
	s_nop 0
	v_add_f32_e32 v106, 1.0, v106
	v_rcp_f32_e32 v106, v106
	s_nop 0
	v_mul_f32_e32 v100, v100, v106
	v_mul_f32_e32 v96, v100, v96
	v_mul_f32_e32 v100, 0xbfb8aa3b, v101
	v_exp_f32_e32 v100, v100
	s_nop 0
	v_add_f32_e32 v100, 1.0, v100
	v_rcp_f32_e32 v100, v100
	s_nop 0
	v_mul_f32_e32 v100, v101, v100
	v_mul_f32_e32 v97, v100, v97
	v_cvt_pk_bf16_f32 v106, v96, v97
	v_mul_f32_e32 v96, 0xbfb8aa3b, v102
	v_exp_f32_e32 v96, v96
	v_mul_f32_e32 v97, 0xbfb8aa3b, v103
	v_exp_f32_e32 v97, v97
	v_add_f32_e32 v96, 1.0, v96
	v_rcp_f32_e32 v96, v96
	v_add_f32_e32 v97, 1.0, v97
	v_rcp_f32_e32 v97, v97
	v_mul_f32_e32 v96, v102, v96
	v_mul_f32_e32 v96, v96, v98
	v_mul_f32_e32 v98, 0xbfb8aa3b, v92
	v_exp_f32_e32 v98, v98
	v_mul_f32_e32 v97, v103, v97
	v_mul_f32_e32 v97, v97, v99
	v_cvt_pk_bf16_f32 v107, v96, v97
	v_add_f32_e32 v98, 1.0, v98
	v_rcp_f32_e32 v98, v98
	v_or_b32_e32 v96, 32, v158
	v_mad_i64_i32 v[96:97], s[12:13], v96, s52, v[150:151]
	v_mul_f32_e32 v92, v92, v98
	v_mul_f32_e32 v88, v92, v88
	v_mul_f32_e32 v92, 0xbfb8aa3b, v93
	v_exp_f32_e32 v92, v92
	v_lshl_add_u64 v[96:97], v[96:97], 0, v[152:153]
	global_store_dwordx4 v[112:113], v[104:107], off
	v_add_f32_e32 v92, 1.0, v92
	v_rcp_f32_e32 v92, v92
	s_nop 0
	v_mul_f32_e32 v92, v93, v92
	v_mul_f32_e32 v89, v92, v89
	v_cvt_pk_bf16_f32 v88, v88, v89
	v_mul_f32_e32 v89, 0xbfb8aa3b, v94
	v_exp_f32_e32 v89, v89
	s_nop 0
	v_add_f32_e32 v89, 1.0, v89
	v_rcp_f32_e32 v89, v89
	s_nop 0
	v_mul_f32_e32 v89, v94, v89
	v_mul_f32_e32 v89, v89, v90
	v_mul_f32_e32 v90, 0xbfb8aa3b, v95
	v_exp_f32_e32 v90, v90
	s_nop 0
	v_add_f32_e32 v90, 1.0, v90
	v_rcp_f32_e32 v90, v90
	s_nop 0
	v_mul_f32_e32 v90, v95, v90
	v_mul_f32_e32 v90, v90, v91
	v_cvt_pk_bf16_f32 v89, v89, v90
	v_mul_f32_e32 v90, 0xbfb8aa3b, v84
	v_exp_f32_e32 v90, v90
	s_nop 0
	v_add_f32_e32 v90, 1.0, v90
	v_rcp_f32_e32 v90, v90
	s_nop 0
	v_mul_f32_e32 v84, v84, v90
	v_mul_f32_e32 v80, v84, v80
	v_mul_f32_e32 v84, 0xbfb8aa3b, v85
	v_exp_f32_e32 v84, v84
	s_nop 0
	v_add_f32_e32 v84, 1.0, v84
	v_rcp_f32_e32 v84, v84
	s_nop 0
	v_mul_f32_e32 v84, v85, v84
	v_mul_f32_e32 v81, v84, v81
	v_cvt_pk_bf16_f32 v90, v80, v81
	v_mul_f32_e32 v80, 0xbfb8aa3b, v86
	v_exp_f32_e32 v80, v80
	v_mul_f32_e32 v81, 0xbfb8aa3b, v87
	v_exp_f32_e32 v81, v81
	v_add_f32_e32 v80, 1.0, v80
	v_rcp_f32_e32 v80, v80
	v_add_f32_e32 v81, 1.0, v81
	v_rcp_f32_e32 v81, v81
	v_mul_f32_e32 v80, v86, v80
	v_mul_f32_e32 v80, v80, v82
	v_mul_f32_e32 v82, 0xbfb8aa3b, v76
	v_exp_f32_e32 v82, v82
	v_mul_f32_e32 v81, v87, v81
	v_mul_f32_e32 v81, v81, v83
	v_cvt_pk_bf16_f32 v91, v80, v81
	v_add_f32_e32 v82, 1.0, v82
	v_rcp_f32_e32 v82, v82
	v_or_b32_e32 v80, 48, v158
	v_mad_i64_i32 v[80:81], s[12:13], v80, s52, v[150:151]
	v_mul_f32_e32 v76, v76, v82
	v_mul_f32_e32 v72, v76, v72
	v_mul_f32_e32 v76, 0xbfb8aa3b, v77
	v_exp_f32_e32 v76, v76
	v_lshl_add_u64 v[80:81], v[80:81], 0, v[152:153]
	global_store_dwordx4 v[96:97], v[88:91], off
	v_add_f32_e32 v76, 1.0, v76
	v_rcp_f32_e32 v76, v76
	s_nop 0
	v_mul_f32_e32 v76, v77, v76
	v_mul_f32_e32 v73, v76, v73
	v_cvt_pk_bf16_f32 v72, v72, v73
	v_mul_f32_e32 v73, 0xbfb8aa3b, v78
	v_exp_f32_e32 v73, v73
	s_nop 0
	v_add_f32_e32 v73, 1.0, v73
	v_rcp_f32_e32 v73, v73
	s_nop 0
	v_mul_f32_e32 v73, v78, v73
	v_mul_f32_e32 v73, v73, v74
	v_mul_f32_e32 v74, 0xbfb8aa3b, v79
	v_exp_f32_e32 v74, v74
	s_nop 0
	v_add_f32_e32 v74, 1.0, v74
	v_rcp_f32_e32 v74, v74
	s_nop 0
	v_mul_f32_e32 v74, v79, v74
	v_mul_f32_e32 v74, v74, v75
	v_cvt_pk_bf16_f32 v73, v73, v74
	v_mul_f32_e32 v74, 0xbfb8aa3b, v68
	v_exp_f32_e32 v74, v74
	s_nop 0
	v_add_f32_e32 v74, 1.0, v74
	v_rcp_f32_e32 v74, v74
	s_nop 0
	v_mul_f32_e32 v68, v68, v74
	v_mul_f32_e32 v64, v68, v64
	v_mul_f32_e32 v68, 0xbfb8aa3b, v69
	v_exp_f32_e32 v68, v68
	s_nop 0
	v_add_f32_e32 v68, 1.0, v68
	v_rcp_f32_e32 v68, v68
	s_nop 0
	v_mul_f32_e32 v68, v69, v68
	v_mul_f32_e32 v65, v68, v65
	v_cvt_pk_bf16_f32 v74, v64, v65
	v_mul_f32_e32 v64, 0xbfb8aa3b, v70
	v_exp_f32_e32 v64, v64
	v_mul_f32_e32 v65, 0xbfb8aa3b, v71
	v_exp_f32_e32 v65, v65
	v_add_f32_e32 v64, 1.0, v64
	v_rcp_f32_e32 v64, v64
	v_add_f32_e32 v65, 1.0, v65
	v_rcp_f32_e32 v65, v65
	v_mul_f32_e32 v64, v70, v64
	v_mul_f32_e32 v64, v64, v66
	v_mul_f32_e32 v66, 0xbfb8aa3b, v60
	v_exp_f32_e32 v66, v66
	v_mul_f32_e32 v65, v71, v65
	v_mul_f32_e32 v65, v65, v67
	v_cvt_pk_bf16_f32 v75, v64, v65
	v_add_f32_e32 v66, 1.0, v66
	v_rcp_f32_e32 v66, v66
	v_add_u32_e32 v64, 0x80, v158
	v_mad_i64_i32 v[64:65], s[12:13], v64, s52, v[150:151]
	v_mul_f32_e32 v60, v60, v66
	v_mul_f32_e32 v56, v60, v56
	v_mul_f32_e32 v60, 0xbfb8aa3b, v61
	v_exp_f32_e32 v60, v60
	v_lshl_add_u64 v[64:65], v[64:65], 0, v[152:153]
	global_store_dwordx4 v[80:81], v[72:75], off
	v_add_f32_e32 v60, 1.0, v60
	v_rcp_f32_e32 v60, v60
	s_nop 0
	v_mul_f32_e32 v60, v61, v60
	v_mul_f32_e32 v57, v60, v57
	v_cvt_pk_bf16_f32 v56, v56, v57
	v_mul_f32_e32 v57, 0xbfb8aa3b, v62
	v_exp_f32_e32 v57, v57
	s_nop 0
	v_add_f32_e32 v57, 1.0, v57
	v_rcp_f32_e32 v57, v57
	s_nop 0
	v_mul_f32_e32 v57, v62, v57
	v_mul_f32_e32 v57, v57, v58
	v_mul_f32_e32 v58, 0xbfb8aa3b, v63
	v_exp_f32_e32 v58, v58
	s_nop 0
	v_add_f32_e32 v58, 1.0, v58
	v_rcp_f32_e32 v58, v58
	s_nop 0
	v_mul_f32_e32 v58, v63, v58
	v_mul_f32_e32 v58, v58, v59
;   __device__ __forceinline__ bf16* y() const { unsigned o_ = (unsigned)(OFF_y); asm volatile("" : "+s"(o_)); return (bf16*)(ws + o_); }
; __device__ __forceinline__ unsigned pk2(float a, float b) { unsigned r; asm("v_cvt_pk_bf16_f32 %0, %1, %2" : "=v"(r) : "v"(a), "v"(b)); return r; }
; __device__ __forceinline__ float silu(float x) { return x * sigm(x); }
; #define PG8_WAIT_V(n) asm volatile("s_waitcnt vmcnt(" #n ")" ::: "memory")
; #define PG8_BAR __builtin_amdgcn_s_barrier()
; template <class Epi, class Sched>
; __device__ __forceinline__ void gemm_phase(PG8_LAS unsigned char* lds, const Gemm g, const Sched& S, const Epi& E) {
;     ...
;         if constexpr (!Epi::AFTER_DRAIN) { E(acc, cur, wr, wc, fr, fq); S.done(cur); }
;         if (!has_next) break;
; #pragma unroll
;         for (int a = 0; a < 2; ++a)
; #pragma unroll
;             for (int b = 0; b < 2; ++b)
; #pragma unroll
;                 for (int m = 0; m < 4; ++m)
; #pragma unroll
;                     for (int n = 0; n < 2; ++n) acc[a][b][m][n] = (f32x4){0.f, 0.f, 0.f, 0.f};
;         cur = nxt; cA = nA; cB = nB; ++ui;
;     }
;     PG8_WAIT_V(0);
;     if (wr == 0) PG8_BAR;
;     PG8_BAR;
;   __device__ __forceinline__ void operator()(const f32x4 (&acc)[2][2][4][2], const pg8::Unit& u, int wr, int wc, int fr, int fq) const {
;     const int row0 = u.pm * 256 + wr * 64 + fr, col0 = u.pn * 128 + wc * 32 + 8 * fq;
; #pragma unroll
;     for (int ai = 0; ai < 2; ++ai)
; #pragma unroll
;       for (int m = 0; m < 4; ++m) {
;         bf16* rowp = O + (size_t)(row0 + ai * 128 + m * 16) * FF + col0;
;         const f32x4 g0 = acc[ai][0][m][0], g1 = acc[ai][0][m][1], u0 = acc[ai][1][m][0], u1 = acc[ai][1][m][1];
;         uint4 o;
;         o.x = pk2(silu(g0[0]) * u0[0], silu(g0[1]) * u0[1]); o.y = pk2(silu(g0[2]) * u0[2], silu(g0[3]) * u0[3]);
;         o.z = pk2(silu(g1[0]) * u1[0], silu(g1[1]) * u1[1]); o.w = pk2(silu(g1[2]) * u1[2], silu(g1[3]) * u1[3]);
;         *(uint4*)rowp = o;
;       }
;   }
	v_cvt_pk_bf16_f32 v57, v57, v58
	v_mul_f32_e32 v58, 0xbfb8aa3b, v52
	v_exp_f32_e32 v58, v58
	s_nop 0
	v_add_f32_e32 v58, 1.0, v58
	v_rcp_f32_e32 v58, v58
	s_nop 0
	v_mul_f32_e32 v52, v52, v58
	v_mul_f32_e32 v48, v52, v48
	v_mul_f32_e32 v52, 0xbfb8aa3b, v53
	v_exp_f32_e32 v52, v52
	s_nop 0
	v_add_f32_e32 v52, 1.0, v52
	v_rcp_f32_e32 v52, v52
	s_nop 0
	v_mul_f32_e32 v52, v53, v52
	v_mul_f32_e32 v49, v52, v49
	v_cvt_pk_bf16_f32 v58, v48, v49
	v_mul_f32_e32 v48, 0xbfb8aa3b, v54
	v_exp_f32_e32 v48, v48
	v_mul_f32_e32 v49, 0xbfb8aa3b, v55
	v_exp_f32_e32 v49, v49
	v_add_f32_e32 v48, 1.0, v48
	v_rcp_f32_e32 v48, v48
	v_add_f32_e32 v49, 1.0, v49
	v_rcp_f32_e32 v49, v49
	v_mul_f32_e32 v48, v54, v48
	v_mul_f32_e32 v48, v48, v50
	v_mul_f32_e32 v50, 0xbfb8aa3b, v44
	v_exp_f32_e32 v50, v50
	v_mul_f32_e32 v49, v55, v49
	v_mul_f32_e32 v49, v49, v51
	v_cvt_pk_bf16_f32 v59, v48, v49
	v_add_f32_e32 v50, 1.0, v50
	v_rcp_f32_e32 v50, v50
	v_add_u32_e32 v48, 0x90, v158
	v_mad_i64_i32 v[48:49], s[12:13], v48, s52, v[150:151]
	v_mul_f32_e32 v44, v44, v50
	v_mul_f32_e32 v40, v44, v40
	v_mul_f32_e32 v44, 0xbfb8aa3b, v45
	v_exp_f32_e32 v44, v44
	v_lshl_add_u64 v[48:49], v[48:49], 0, v[152:153]
	global_store_dwordx4 v[64:65], v[56:59], off
	v_add_f32_e32 v44, 1.0, v44
	v_rcp_f32_e32 v44, v44
	s_nop 0
	v_mul_f32_e32 v44, v45, v44
	v_mul_f32_e32 v41, v44, v41
	v_cvt_pk_bf16_f32 v40, v40, v41
	v_mul_f32_e32 v41, 0xbfb8aa3b, v46
	v_exp_f32_e32 v41, v41
	s_nop 0
	v_add_f32_e32 v41, 1.0, v41
	v_rcp_f32_e32 v41, v41
	s_nop 0
	v_mul_f32_e32 v41, v46, v41
	v_mul_f32_e32 v41, v41, v42
	v_mul_f32_e32 v42, 0xbfb8aa3b, v47
	v_exp_f32_e32 v42, v42
	s_nop 0
	v_add_f32_e32 v42, 1.0, v42
	v_rcp_f32_e32 v42, v42
	s_nop 0
	v_mul_f32_e32 v42, v47, v42
	v_mul_f32_e32 v42, v42, v43
	v_cvt_pk_bf16_f32 v41, v41, v42
	v_mul_f32_e32 v42, 0xbfb8aa3b, v36
	v_exp_f32_e32 v42, v42
	s_nop 0
	v_add_f32_e32 v42, 1.0, v42
	v_rcp_f32_e32 v42, v42
	s_nop 0
	v_mul_f32_e32 v36, v36, v42
	v_mul_f32_e32 v32, v36, v32
	v_mul_f32_e32 v36, 0xbfb8aa3b, v37
	v_exp_f32_e32 v36, v36
	s_nop 0
	v_add_f32_e32 v36, 1.0, v36
	v_rcp_f32_e32 v36, v36
	s_nop 0
	v_mul_f32_e32 v36, v37, v36
	v_mul_f32_e32 v33, v36, v33
	v_cvt_pk_bf16_f32 v42, v32, v33
	v_mul_f32_e32 v32, 0xbfb8aa3b, v38
	v_exp_f32_e32 v32, v32
	v_mul_f32_e32 v33, 0xbfb8aa3b, v39
	v_exp_f32_e32 v33, v33
	v_add_f32_e32 v32, 1.0, v32
	v_rcp_f32_e32 v32, v32
	v_add_f32_e32 v33, 1.0, v33
	v_rcp_f32_e32 v33, v33
	v_mul_f32_e32 v32, v38, v32
	v_mul_f32_e32 v32, v32, v34
	v_mul_f32_e32 v34, 0xbfb8aa3b, v28
	v_exp_f32_e32 v34, v34
	v_mul_f32_e32 v33, v39, v33
	v_mul_f32_e32 v33, v33, v35
	v_cvt_pk_bf16_f32 v43, v32, v33
	v_add_f32_e32 v34, 1.0, v34
	v_rcp_f32_e32 v34, v34
	v_add_u32_e32 v32, 0xa0, v158
	v_mad_i64_i32 v[32:33], s[12:13], v32, s52, v[150:151]
	v_mul_f32_e32 v28, v28, v34
	v_mul_f32_e32 v24, v28, v24
	v_mul_f32_e32 v28, 0xbfb8aa3b, v29
	v_exp_f32_e32 v28, v28
	v_lshl_add_u64 v[32:33], v[32:33], 0, v[152:153]
	global_store_dwordx4 v[48:49], v[40:43], off
	v_add_f32_e32 v28, 1.0, v28
	v_rcp_f32_e32 v28, v28
	s_nop 0
	v_mul_f32_e32 v28, v29, v28
	v_mul_f32_e32 v25, v28, v25
	v_cvt_pk_bf16_f32 v24, v24, v25
	v_mul_f32_e32 v25, 0xbfb8aa3b, v30
	v_exp_f32_e32 v25, v25
	s_nop 0
	v_add_f32_e32 v25, 1.0, v25
	v_rcp_f32_e32 v25, v25
	s_nop 0
	v_mul_f32_e32 v25, v30, v25
	v_mul_f32_e32 v25, v25, v26
	v_mul_f32_e32 v26, 0xbfb8aa3b, v31
	v_exp_f32_e32 v26, v26
	s_nop 0
	v_add_f32_e32 v26, 1.0, v26
	v_rcp_f32_e32 v26, v26
	s_nop 0
	v_mul_f32_e32 v26, v31, v26
	v_mul_f32_e32 v26, v26, v27
	v_cvt_pk_bf16_f32 v25, v25, v26
	v_mul_f32_e32 v26, 0xbfb8aa3b, v20
	v_exp_f32_e32 v26, v26
	s_nop 0
	v_add_f32_e32 v26, 1.0, v26
	v_rcp_f32_e32 v26, v26
	s_nop 0
	v_mul_f32_e32 v20, v20, v26
	v_mul_f32_e32 v16, v20, v16
	v_mul_f32_e32 v20, 0xbfb8aa3b, v21
	v_exp_f32_e32 v20, v20
	s_nop 0
	v_add_f32_e32 v20, 1.0, v20
	v_rcp_f32_e32 v20, v20
	s_nop 0
	v_mul_f32_e32 v20, v21, v20
	v_mul_f32_e32 v17, v20, v17
	v_cvt_pk_bf16_f32 v26, v16, v17
	v_mul_f32_e32 v16, 0xbfb8aa3b, v22
	v_exp_f32_e32 v16, v16
	v_mul_f32_e32 v17, 0xbfb8aa3b, v23
	v_exp_f32_e32 v17, v17
	v_add_f32_e32 v16, 1.0, v16
	v_rcp_f32_e32 v16, v16
	v_add_f32_e32 v17, 1.0, v17
	v_rcp_f32_e32 v17, v17
	v_mul_f32_e32 v16, v22, v16
	v_mul_f32_e32 v16, v16, v18
	v_mul_f32_e32 v18, 0xbfb8aa3b, v12
	v_exp_f32_e32 v18, v18
	v_mul_f32_e32 v17, v23, v17
	v_mul_f32_e32 v17, v17, v19
	v_cvt_pk_bf16_f32 v27, v16, v17
	v_add_f32_e32 v18, 1.0, v18
	v_rcp_f32_e32 v18, v18
	v_add_u32_e32 v16, 0xb0, v158
	v_mad_i64_i32 v[16:17], s[12:13], v16, s52, v[150:151]
	v_mul_f32_e32 v12, v12, v18
	v_mul_f32_e32 v8, v12, v8
	v_mul_f32_e32 v12, 0xbfb8aa3b, v13
	v_exp_f32_e32 v12, v12
	v_lshl_add_u64 v[16:17], v[16:17], 0, v[152:153]
	global_store_dwordx4 v[32:33], v[24:27], off
	v_add_f32_e32 v12, 1.0, v12
	v_rcp_f32_e32 v12, v12
	s_nop 0
	v_mul_f32_e32 v12, v13, v12
	v_mul_f32_e32 v9, v12, v9
	v_cvt_pk_bf16_f32 v8, v8, v9
	v_mul_f32_e32 v9, 0xbfb8aa3b, v14
	v_exp_f32_e32 v9, v9
	s_nop 0
	v_add_f32_e32 v9, 1.0, v9
	v_rcp_f32_e32 v9, v9
	s_nop 0
	v_mul_f32_e32 v9, v14, v9
	v_mul_f32_e32 v9, v9, v10
	v_mul_f32_e32 v10, 0xbfb8aa3b, v15
	v_exp_f32_e32 v10, v10
	s_nop 0
	v_add_f32_e32 v10, 1.0, v10
	v_rcp_f32_e32 v10, v10
	s_nop 0
	v_mul_f32_e32 v10, v15, v10
	v_mul_f32_e32 v10, v10, v11
	v_cvt_pk_bf16_f32 v9, v9, v10
	v_mul_f32_e32 v10, 0xbfb8aa3b, v4
	v_exp_f32_e32 v10, v10
	s_nop 0
	v_add_f32_e32 v10, 1.0, v10
	v_rcp_f32_e32 v10, v10
	s_nop 0
	v_mul_f32_e32 v4, v4, v10
	v_mul_f32_e32 v0, v4, v0
	v_mul_f32_e32 v4, 0xbfb8aa3b, v5
	v_exp_f32_e32 v4, v4
	s_nop 0
	v_add_f32_e32 v4, 1.0, v4
	v_rcp_f32_e32 v4, v4
	s_nop 0
	v_mul_f32_e32 v4, v5, v4
	v_mul_f32_e32 v1, v4, v1
	v_cvt_pk_bf16_f32 v10, v0, v1
	v_mul_f32_e32 v0, 0xbfb8aa3b, v6
	v_mul_f32_e32 v1, 0xbfb8aa3b, v7
	v_exp_f32_e32 v0, v0
	v_exp_f32_e32 v1, v1
	v_add_f32_e32 v0, 1.0, v0
	v_add_f32_e32 v1, 1.0, v1
	v_rcp_f32_e32 v0, v0
	v_rcp_f32_e32 v1, v1
	v_mul_f32_e32 v0, v6, v0
	v_mul_f32_e32 v1, v7, v1
	v_mul_f32_e32 v0, v0, v2
	v_mul_f32_e32 v1, v1, v3
	v_cvt_pk_bf16_f32 v11, v0, v1
	global_store_dwordx4 v[16:17], v[8:11], off
	s_cbranch_vccz .LBB0_990
	s_waitcnt vmcnt(0)
	s_cmpk_gt_u32 s25, 0xff
	s_cbranch_scc1 .LBB0_1001
	s_barrier

; #define PG8_STAGE(bufoff, gbase, voff) do { _Pragma("unroll") for (int _i = 0; _i < 2; ++_i) \
;         __builtin_amdgcn_global_load_lds((const unsigned*)((const char*)(gbase) + (voff)[_i]), (PG8_LAS unsigned*)(lds + (bufoff) + ldsw + _i * 8192), 16, 0, 0); } while (0)
; #define PG8_LDA(dst, b, h) do { _Pragma("unroll") for (int m = 0; m < 4; ++m) _Pragma("unroll") for (int k = 0; k < 2; ++k) dst[m][k] = *(const PG8_LAS bf16x8*)(lds + PG8_SA(b, h) + aoff + m * 2048 + k * 1024); } while (0)
; #define PG8_WAIT_V(n) asm volatile("s_waitcnt vmcnt(" #n ")" ::: "memory")
; template <class Epi, class Sched>
; __device__ __forceinline__ void gemm_phase(PG8_LAS unsigned char* lds, const Gemm g, const Sched& S, const Epi& E) {
;     ...
;         for (int t = 0; t < nt; t += 2) {
;             const bool last = (t == nt - 2);
;             const char* a1 = cA + (size_t)(t + 1) * kstep;
;             const char* a2 = last ? nA : cA + (size_t)(t + 2) * kstep; const char* b2 = last ? nB : cB + (size_t)(t + 2) * kstep;
;             const char* a3 = a2 + kstep; const char* b3 = b2 + kstep;
;             if (last && has_next) S.a_ready(nxt);
;             PG8_LDB(B0, 0, 0); PG8_SCHED; PG8_LDA(At, 0, 0); PG8_STAGE(PG8_SA(1, 1), a1 + hstep, voffA);
;             PG8_WAIT_L(8); PG8_BAR; PG8_WAIT_L(0); PG8_MMA(0, 0, At, B0); PG8_BAR; PG8_SCHED;
;             PG8_LDB(B1, 0, 1); PG8_STAGE(PG8_SB(0, 0), b2, voffB);
;             PG8_BAR; PG8_WAIT_L(0); PG8_MMA(0, 1, At, B1); PG8_BAR;
;             PG8_LDA(At, 0, 1); PG8_STAGE(PG8_SA(0, 0), a2, voffA);
;             PG8_BAR; PG8_WAIT_L(0); PG8_MMA(1, 0, At, B0); PG8_BAR; PG8_SCHED;
;             PG8_STAGE(PG8_SB(0, 1), b2 + hstep, voffB);
;             PG8_WAIT_V(6); PG8_BAR; PG8_MMA(1, 1, At, B1); PG8_BAR;
;             PG8_LDB(B0, 1, 0); PG8_SCHED; PG8_LDA(At, 1, 0); PG8_STAGE(PG8_SA(0, 1), a2 + hstep, voffA);
;             PG8_WAIT_L(8); PG8_BAR; PG8_WAIT_L(0); PG8_MMA(0, 0, At, B0); PG8_BAR; PG8_SCHED;
;             PG8_LDB(B1, 1, 1); PG8_STAGE(PG8_SB(1, 0), b3, voffB);
;             PG8_BAR; PG8_WAIT_L(0); PG8_MMA(0, 1, At, B1); PG8_BAR;
;             PG8_LDA(At, 1, 1); PG8_STAGE(PG8_SA(1, 0), a3, voffA);
;             PG8_BAR; PG8_WAIT_L(0); PG8_MMA(1, 0, At, B0); PG8_BAR; PG8_SCHED;
;             PG8_STAGE(PG8_SB(1, 1), b3 + hstep, voffB);
;             PG8_WAIT_V(6); PG8_BAR; PG8_MMA(1, 1, At, B1); PG8_BAR;
.LBB0_1074:
	s_add_u32 s12, s8, s20
	s_addc_u32 s13, s9, s21
	s_add_u32 s12, s12, 0x100
	s_addc_u32 s13, s13, 0
	s_add_u32 s22, s68, s20
	s_addc_u32 s23, s82, s21
	s_add_i32 s69, s46, 0x100
	v_add_u32_e32 v159, s69, v155
	ds_read_b128 v[160:163], v159
	ds_read_b128 v[164:167], v159 offset:1024
	ds_read_b128 v[168:171], v159 offset:2048
	ds_read_b128 v[172:175], v159 offset:3072
	s_cmpk_eq_i32 s20, 0x1500
	s_cselect_b32 s25, s19, s13
	s_cselect_b32 s24, s18, s12
	s_cselect_b32 s23, s7, s23
	s_cselect_b32 s22, s6, s22
	v_lshl_add_u64 v[230:231], v[150:151], 0, s[20:21]
	s_add_i32 m0, s58, 0xc000
	ds_read_b128 v[176:179], v158
	ds_read_b128 v[180:183], v158 offset:1024
	ds_read_b128 v[184:187], v158 offset:2048
	ds_read_b128 v[210:213], v158 offset:3072
	ds_read_b128 v[214:217], v158 offset:4096
	ds_read_b128 v[218:221], v158 offset:5120
	ds_read_b128 v[222:225], v158 offset:6144
	ds_read_b128 v[226:229], v158 offset:7168
	global_load_lds_dwordx4 v[230:231], off
	v_lshl_add_u64 v[230:231], v[152:153], 0, s[20:21]
	s_add_i32 m0, s58, 0xe000
	s_nop 0
	global_load_lds_dwordx4 v[230:231], off
	s_waitcnt lgkmcnt(8)
	s_barrier
	s_waitcnt lgkmcnt(0)
	s_setprio 1
	v_mfma_f32_16x16x32_bf16 v[124:127], v[160:163], v[176:179], v[124:127]
	v_mfma_f32_16x16x32_bf16 v[120:123], v[168:171], v[176:179], v[120:123]
	v_mfma_f32_16x16x32_bf16 v[116:119], v[160:163], v[184:187], v[116:119]
	v_mfma_f32_16x16x32_bf16 v[112:115], v[168:171], v[184:187], v[112:115]
	v_mfma_f32_16x16x32_bf16 v[108:111], v[160:163], v[214:217], v[108:111]
	v_mfma_f32_16x16x32_bf16 v[104:107], v[168:171], v[214:217], v[104:107]
	v_mfma_f32_16x16x32_bf16 v[100:103], v[160:163], v[222:225], v[100:103]
	v_mfma_f32_16x16x32_bf16 v[96:99], v[168:171], v[222:225], v[96:99]
	v_mfma_f32_16x16x32_bf16 v[124:127], v[164:167], v[180:183], v[124:127]
	v_mfma_f32_16x16x32_bf16 v[120:123], v[172:175], v[180:183], v[120:123]
	v_mfma_f32_16x16x32_bf16 v[116:119], v[164:167], v[210:213], v[116:119]
	v_mfma_f32_16x16x32_bf16 v[112:115], v[172:175], v[210:213], v[112:115]
	v_mfma_f32_16x16x32_bf16 v[108:111], v[164:167], v[218:221], v[108:111]
	v_mfma_f32_16x16x32_bf16 v[104:107], v[172:175], v[218:221], v[104:107]
	v_mfma_f32_16x16x32_bf16 v[100:103], v[164:167], v[226:229], v[100:103]
	v_mfma_f32_16x16x32_bf16 v[96:99], v[172:175], v[226:229], v[96:99]
	s_setprio 0
	s_barrier
	s_add_i32 s84, s48, 0x100
	s_add_i32 s12, s69, s41
	v_add_u32_e32 v159, s84, v155
	v_lshl_add_u64 v[246:247], s[22:23], 0, v[138:139]
	s_mov_b32 m0, s12
	ds_read_b128 v[230:233], v159
	ds_read_b128 v[234:237], v159 offset:1024
	ds_read_b128 v[238:241], v159 offset:2048
	ds_read_b128 v[242:245], v159 offset:3072
	global_load_lds_dwordx4 v[246:247], off
	v_lshl_add_u64 v[248:249], s[22:23], 0, v[132:133]
	s_add_i32 m0, s12, 0x2000
	s_nop 0
	global_load_lds_dwordx4 v[248:249], off
	s_barrier
	s_waitcnt lgkmcnt(0)
	s_setprio 1
	v_mfma_f32_16x16x32_bf16 v[60:63], v[230:233], v[176:179], v[60:63]
	v_mfma_f32_16x16x32_bf16 v[56:59], v[238:241], v[176:179], v[56:59]
	v_mfma_f32_16x16x32_bf16 v[52:55], v[230:233], v[184:187], v[52:55]
	v_mfma_f32_16x16x32_bf16 v[48:51], v[238:241], v[184:187], v[48:51]
	v_mfma_f32_16x16x32_bf16 v[44:47], v[230:233], v[214:217], v[44:47]
	v_mfma_f32_16x16x32_bf16 v[40:43], v[238:241], v[214:217], v[40:43]
	v_mfma_f32_16x16x32_bf16 v[36:39], v[230:233], v[222:225], v[36:39]
	v_mfma_f32_16x16x32_bf16 v[32:35], v[238:241], v[222:225], v[32:35]
	v_mfma_f32_16x16x32_bf16 v[60:63], v[234:237], v[180:183], v[60:63]
	v_mfma_f32_16x16x32_bf16 v[56:59], v[242:245], v[180:183], v[56:59]
	v_mfma_f32_16x16x32_bf16 v[52:55], v[234:237], v[210:213], v[52:55]
	v_mfma_f32_16x16x32_bf16 v[48:51], v[242:245], v[210:213], v[48:51]
	v_mfma_f32_16x16x32_bf16 v[44:47], v[234:237], v[218:221], v[44:47]
	v_mfma_f32_16x16x32_bf16 v[40:43], v[242:245], v[218:221], v[40:43]
	v_mfma_f32_16x16x32_bf16 v[36:39], v[234:237], v[226:229], v[36:39]
	v_mfma_f32_16x16x32_bf16 v[32:35], v[242:245], v[226:229], v[32:35]
	s_setprio 0
	s_mov_b32 m0, s58
	v_lshl_add_u64 v[250:251], s[24:25], 0, v[128:129]
	s_barrier
	ds_read_b128 v[176:179], v158 offset:16384
	ds_read_b128 v[180:183], v158 offset:17408
	ds_read_b128 v[184:187], v158 offset:18432
	ds_read_b128 v[210:213], v158 offset:19456
	ds_read_b128 v[214:217], v158 offset:20480
	ds_read_b128 v[218:221], v158 offset:21504
	ds_read_b128 v[222:225], v158 offset:22528
	ds_read_b128 v[226:229], v158 offset:23552
	global_load_lds_dwordx4 v[250:251], off
	v_lshl_add_u64 v[252:253], s[24:25], 0, v[130:131]
	s_mov_b32 m0, s59
	s_nop 0
	global_load_lds_dwordx4 v[252:253], off
	s_barrier
	s_waitcnt lgkmcnt(0)
	s_setprio 1
	v_mfma_f32_16x16x32_bf16 v[92:95], v[160:163], v[176:179], v[92:95]
	v_mfma_f32_16x16x32_bf16 v[88:91], v[168:171], v[176:179], v[88:91]
	v_mfma_f32_16x16x32_bf16 v[84:87], v[160:163], v[184:187], v[84:87]
	v_mfma_f32_16x16x32_bf16 v[80:83], v[168:171], v[184:187], v[80:83]
	v_mfma_f32_16x16x32_bf16 v[76:79], v[160:163], v[214:217], v[76:79]
	v_mfma_f32_16x16x32_bf16 v[72:75], v[168:171], v[214:217], v[72:75]
	v_mfma_f32_16x16x32_bf16 v[68:71], v[160:163], v[222:225], v[68:71]
	v_mfma_f32_16x16x32_bf16 v[64:67], v[168:171], v[222:225], v[64:67]
	v_mfma_f32_16x16x32_bf16 v[92:95], v[164:167], v[180:183], v[92:95]
	v_mfma_f32_16x16x32_bf16 v[88:91], v[172:175], v[180:183], v[88:91]
	v_mfma_f32_16x16x32_bf16 v[84:87], v[164:167], v[210:213], v[84:87]
	v_mfma_f32_16x16x32_bf16 v[80:83], v[172:175], v[210:213], v[80:83]
	v_mfma_f32_16x16x32_bf16 v[76:79], v[164:167], v[218:221], v[76:79]
	v_mfma_f32_16x16x32_bf16 v[72:75], v[172:175], v[218:221], v[72:75]
	v_mfma_f32_16x16x32_bf16 v[68:71], v[164:167], v[226:229], v[68:71]
	v_mfma_f32_16x16x32_bf16 v[64:67], v[172:175], v[226:229], v[64:67]
	s_setprio 0
	s_barrier
; #define PG8_STAGE(bufoff, gbase, voff) do { _Pragma("unroll") for (int _i = 0; _i < 2; ++_i) \
;         __builtin_amdgcn_global_load_lds((const unsigned*)((const char*)(gbase) + (voff)[_i]), (PG8_LAS unsigned*)(lds + (bufoff) + ldsw + _i * 8192), 16, 0, 0); } while (0)
; #define PG8_LDA(dst, b, h) do { _Pragma("unroll") for (int m = 0; m < 4; ++m) _Pragma("unroll") for (int k = 0; k < 2; ++k) dst[m][k] = *(const PG8_LAS bf16x8*)(lds + PG8_SA(b, h) + aoff + m * 2048 + k * 1024); } while (0)
; #define PG8_WAIT_V(n) asm volatile("s_waitcnt vmcnt(" #n ")" ::: "memory")
; template <class Epi, class Sched>
; __device__ __forceinline__ void gemm_phase(PG8_LAS unsigned char* lds, const Gemm g, const Sched& S, const Epi& E) {
;     ...
;         for (int t = 0; t < nt; t += 2) {
;             const bool last = (t == nt - 2);
;             const char* a1 = cA + (size_t)(t + 1) * kstep;
;             const char* a2 = last ? nA : cA + (size_t)(t + 2) * kstep; const char* b2 = last ? nB : cB + (size_t)(t + 2) * kstep;
;             const char* a3 = a2 + kstep; const char* b3 = b2 + kstep;
;             if (last && has_next) S.a_ready(nxt);
;             PG8_LDB(B0, 0, 0); PG8_SCHED; PG8_LDA(At, 0, 0); PG8_STAGE(PG8_SA(1, 1), a1 + hstep, voffA);
;             PG8_WAIT_L(8); PG8_BAR; PG8_WAIT_L(0); PG8_MMA(0, 0, At, B0); PG8_BAR; PG8_SCHED;
;             PG8_LDB(B1, 0, 1); PG8_STAGE(PG8_SB(0, 0), b2, voffB);
;             PG8_BAR; PG8_WAIT_L(0); PG8_MMA(0, 1, At, B1); PG8_BAR;
;             PG8_LDA(At, 0, 1); PG8_STAGE(PG8_SA(0, 0), a2, voffA);
;             PG8_BAR; PG8_WAIT_L(0); PG8_MMA(1, 0, At, B0); PG8_BAR; PG8_SCHED;
;             PG8_STAGE(PG8_SB(0, 1), b2 + hstep, voffB);
;             PG8_WAIT_V(6); PG8_BAR; PG8_MMA(1, 1, At, B1); PG8_BAR;
;             PG8_LDB(B0, 1, 0); PG8_SCHED; PG8_LDA(At, 1, 0); PG8_STAGE(PG8_SA(0, 1), a2 + hstep, voffA);
;             PG8_WAIT_L(8); PG8_BAR; PG8_WAIT_L(0); PG8_MMA(0, 0, At, B0); PG8_BAR; PG8_SCHED;
;             PG8_LDB(B1, 1, 1); PG8_STAGE(PG8_SB(1, 0), b3, voffB);
;             PG8_BAR; PG8_WAIT_L(0); PG8_MMA(0, 1, At, B1); PG8_BAR;
;             PG8_LDA(At, 1, 1); PG8_STAGE(PG8_SA(1, 0), a3, voffA);
;             PG8_BAR; PG8_WAIT_L(0); PG8_MMA(1, 0, At, B0); PG8_BAR; PG8_SCHED;
;             PG8_STAGE(PG8_SB(1, 1), b3 + hstep, voffB);
;             PG8_WAIT_V(6); PG8_BAR; PG8_MMA(1, 1, At, B1); PG8_BAR;
	s_add_u32 s12, s22, 0xb0000
	s_addc_u32 s13, s23, 0
	s_add_i32 s69, s84, s41
	v_lshl_add_u64 v[160:161], s[12:13], 0, v[138:139]
	s_mov_b32 m0, s69
	s_nop 0
	global_load_lds_dwordx4 v[160:161], off
	v_lshl_add_u64 v[160:161], s[12:13], 0, v[132:133]
	s_add_i32 m0, s69, 0x2000
	s_nop 0
	global_load_lds_dwordx4 v[160:161], off
	s_waitcnt vmcnt(6)
	s_barrier
	s_setprio 1
	v_mfma_f32_16x16x32_bf16 v[28:31], v[230:233], v[176:179], v[28:31]
	v_mfma_f32_16x16x32_bf16 v[24:27], v[238:241], v[176:179], v[24:27]
	v_mfma_f32_16x16x32_bf16 v[20:23], v[230:233], v[184:187], v[20:23]
	v_mfma_f32_16x16x32_bf16 v[16:19], v[238:241], v[184:187], v[16:19]
	v_mfma_f32_16x16x32_bf16 v[12:15], v[230:233], v[214:217], v[12:15]
	v_mfma_f32_16x16x32_bf16 v[8:11], v[238:241], v[214:217], v[8:11]
	v_mfma_f32_16x16x32_bf16 v[4:7], v[230:233], v[222:225], v[4:7]
	v_mfma_f32_16x16x32_bf16 v[0:3], v[238:241], v[222:225], v[0:3]
	v_mfma_f32_16x16x32_bf16 v[28:31], v[234:237], v[180:183], v[28:31]
	v_mfma_f32_16x16x32_bf16 v[24:27], v[242:245], v[180:183], v[24:27]
	v_mfma_f32_16x16x32_bf16 v[20:23], v[234:237], v[210:213], v[20:23]
	v_mfma_f32_16x16x32_bf16 v[16:19], v[242:245], v[210:213], v[16:19]
	v_mfma_f32_16x16x32_bf16 v[12:15], v[234:237], v[218:221], v[12:15]
	v_mfma_f32_16x16x32_bf16 v[8:11], v[242:245], v[218:221], v[8:11]
	v_mfma_f32_16x16x32_bf16 v[4:7], v[234:237], v[226:229], v[4:7]
	v_mfma_f32_16x16x32_bf16 v[0:3], v[242:245], v[226:229], v[0:3]
	s_setprio 0
	s_add_i32 s69, s51, 0x100
	v_add_u32_e32 v159, s69, v155
	s_barrier
	ds_read_b128 v[160:163], v159
	ds_read_b128 v[164:167], v159 offset:1024
	ds_read_b128 v[168:171], v159 offset:2048
	ds_read_b128 v[172:175], v159 offset:3072
	s_add_u32 s12, s24, 0xb0000
	s_addc_u32 s13, s25, 0
	s_mov_b32 m0, s60
	v_lshl_add_u64 v[230:231], s[12:13], 0, v[128:129]
	ds_read_b128 v[176:179], v158 offset:32768
	ds_read_b128 v[180:183], v158 offset:33792
	ds_read_b128 v[184:187], v158 offset:34816
	ds_read_b128 v[210:213], v158 offset:35840
	ds_read_b128 v[214:217], v158 offset:36864
	ds_read_b128 v[218:221], v158 offset:37888
	ds_read_b128 v[222:225], v158 offset:38912
	ds_read_b128 v[226:229], v158 offset:39936
	global_load_lds_dwordx4 v[230:231], off
	v_lshl_add_u64 v[230:231], s[12:13], 0, v[130:131]
	s_mov_b32 m0, s61
	s_nop 0
	global_load_lds_dwordx4 v[230:231], off
	s_waitcnt lgkmcnt(8)
	s_barrier
	s_waitcnt lgkmcnt(0)
	s_setprio 1
	v_mfma_f32_16x16x32_bf16 v[124:127], v[160:163], v[176:179], v[124:127]
	v_mfma_f32_16x16x32_bf16 v[120:123], v[168:171], v[176:179], v[120:123]
	v_mfma_f32_16x16x32_bf16 v[116:119], v[160:163], v[184:187], v[116:119]
	v_mfma_f32_16x16x32_bf16 v[112:115], v[168:171], v[184:187], v[112:115]
	v_mfma_f32_16x16x32_bf16 v[108:111], v[160:163], v[214:217], v[108:111]
	v_mfma_f32_16x16x32_bf16 v[104:107], v[168:171], v[214:217], v[104:107]
	v_mfma_f32_16x16x32_bf16 v[100:103], v[160:163], v[222:225], v[100:103]
	v_mfma_f32_16x16x32_bf16 v[96:99], v[168:171], v[222:225], v[96:99]
	v_mfma_f32_16x16x32_bf16 v[124:127], v[164:167], v[180:183], v[124:127]
	v_mfma_f32_16x16x32_bf16 v[120:123], v[172:175], v[180:183], v[120:123]
	v_mfma_f32_16x16x32_bf16 v[116:119], v[164:167], v[210:213], v[116:119]
	v_mfma_f32_16x16x32_bf16 v[112:115], v[172:175], v[210:213], v[112:115]
	v_mfma_f32_16x16x32_bf16 v[108:111], v[164:167], v[218:221], v[108:111]
	v_mfma_f32_16x16x32_bf16 v[104:107], v[172:175], v[218:221], v[104:107]
	v_mfma_f32_16x16x32_bf16 v[100:103], v[164:167], v[226:229], v[100:103]
	v_mfma_f32_16x16x32_bf16 v[96:99], v[172:175], v[226:229], v[96:99]
	s_setprio 0
	s_barrier
	s_add_i32 s24, s55, 0x100
	s_add_i32 s12, s69, s41
	v_add_u32_e32 v159, s24, v155
	v_lshl_add_u64 v[246:247], v[246:247], 0, s[94:95]
	s_mov_b32 m0, s12
	ds_read_b128 v[230:233], v159
	ds_read_b128 v[234:237], v159 offset:1024
	ds_read_b128 v[238:241], v159 offset:2048
	ds_read_b128 v[242:245], v159 offset:3072
	global_load_lds_dwordx4 v[246:247], off
	v_lshl_add_u64 v[246:247], v[248:249], 0, s[94:95]
	s_add_i32 m0, s12, 0x2000
	s_nop 0
	global_load_lds_dwordx4 v[246:247], off
	s_barrier
	s_waitcnt lgkmcnt(0)
	s_setprio 1
	v_mfma_f32_16x16x32_bf16 v[60:63], v[230:233], v[176:179], v[60:63]
	v_mfma_f32_16x16x32_bf16 v[56:59], v[238:241], v[176:179], v[56:59]
	v_mfma_f32_16x16x32_bf16 v[52:55], v[230:233], v[184:187], v[52:55]
	v_mfma_f32_16x16x32_bf16 v[48:51], v[238:241], v[184:187], v[48:51]
	v_mfma_f32_16x16x32_bf16 v[44:47], v[230:233], v[214:217], v[44:47]
	v_mfma_f32_16x16x32_bf16 v[40:43], v[238:241], v[214:217], v[40:43]
	v_mfma_f32_16x16x32_bf16 v[36:39], v[230:233], v[222:225], v[36:39]
	v_mfma_f32_16x16x32_bf16 v[32:35], v[238:241], v[222:225], v[32:35]
	v_mfma_f32_16x16x32_bf16 v[60:63], v[234:237], v[180:183], v[60:63]
	v_mfma_f32_16x16x32_bf16 v[56:59], v[242:245], v[180:183], v[56:59]
	v_mfma_f32_16x16x32_bf16 v[52:55], v[234:237], v[210:213], v[52:55]
	v_mfma_f32_16x16x32_bf16 v[48:51], v[242:245], v[210:213], v[48:51]
	v_mfma_f32_16x16x32_bf16 v[44:47], v[234:237], v[218:221], v[44:47]
	v_mfma_f32_16x16x32_bf16 v[40:43], v[242:245], v[218:221], v[40:43]
	v_mfma_f32_16x16x32_bf16 v[36:39], v[234:237], v[226:229], v[36:39]
	v_mfma_f32_16x16x32_bf16 v[32:35], v[242:245], v[226:229], v[32:35]
	s_setprio 0
	s_mov_b32 m0, s62
	v_lshl_add_u64 v[246:247], v[250:251], 0, s[94:95]
	s_barrier
	ds_read_b128 v[176:179], v158 offset:49152
	ds_read_b128 v[180:183], v158 offset:50176
	ds_read_b128 v[184:187], v158 offset:51200
	ds_read_b128 v[210:213], v158 offset:52224
	ds_read_b128 v[214:217], v158 offset:53248
	ds_read_b128 v[218:221], v158 offset:54272
	ds_read_b128 v[222:225], v158 offset:55296
	ds_read_b128 v[226:229], v158 offset:56320
	global_load_lds_dwordx4 v[246:247], off
	v_lshl_add_u64 v[246:247], v[252:253], 0, s[94:95]
	s_mov_b32 m0, s63
	s_nop 0
	global_load_lds_dwordx4 v[246:247], off
	s_barrier
; #define PG8_WAIT_V(n) asm volatile("s_waitcnt vmcnt(" #n ")" ::: "memory")
; #define PG8_BAR __builtin_amdgcn_s_barrier()
; template <class Epi, class Sched>
; __device__ __forceinline__ void gemm_phase(PG8_LAS unsigned char* lds, const Gemm g, const Sched& S, const Epi& E) {
;     ...
;         for (int t = 0; t < nt; t += 2) {
;             const bool last = (t == nt - 2);
;             const char* a1 = cA + (size_t)(t + 1) * kstep;
;             const char* a2 = last ? nA : cA + (size_t)(t + 2) * kstep; const char* b2 = last ? nB : cB + (size_t)(t + 2) * kstep;
;             const char* a3 = a2 + kstep; const char* b3 = b2 + kstep;
;             if (last && has_next) S.a_ready(nxt);
;             PG8_LDB(B0, 0, 0); PG8_SCHED; PG8_LDA(At, 0, 0); PG8_STAGE(PG8_SA(1, 1), a1 + hstep, voffA);
;             PG8_WAIT_L(8); PG8_BAR; PG8_WAIT_L(0); PG8_MMA(0, 0, At, B0); PG8_BAR; PG8_SCHED;
;             PG8_LDB(B1, 0, 1); PG8_STAGE(PG8_SB(0, 0), b2, voffB);
;             PG8_BAR; PG8_WAIT_L(0); PG8_MMA(0, 1, At, B1); PG8_BAR;
;             PG8_LDA(At, 0, 1); PG8_STAGE(PG8_SA(0, 0), a2, voffA);
;             PG8_BAR; PG8_WAIT_L(0); PG8_MMA(1, 0, At, B0); PG8_BAR; PG8_SCHED;
;             PG8_STAGE(PG8_SB(0, 1), b2 + hstep, voffB);
;             PG8_WAIT_V(6); PG8_BAR; PG8_MMA(1, 1, At, B1); PG8_BAR;
;             PG8_LDB(B0, 1, 0); PG8_SCHED; PG8_LDA(At, 1, 0); PG8_STAGE(PG8_SA(0, 1), a2 + hstep, voffA);
;             PG8_WAIT_L(8); PG8_BAR; PG8_WAIT_L(0); PG8_MMA(0, 0, At, B0); PG8_BAR; PG8_SCHED;
;             PG8_LDB(B1, 1, 1); PG8_STAGE(PG8_SB(1, 0), b3, voffB);
;             PG8_BAR; PG8_WAIT_L(0); PG8_MMA(0, 1, At, B1); PG8_BAR;
;             PG8_LDA(At, 1, 1); PG8_STAGE(PG8_SA(1, 0), a3, voffA);
;             PG8_BAR; PG8_WAIT_L(0); PG8_MMA(1, 0, At, B0); PG8_BAR; PG8_SCHED;
;             PG8_STAGE(PG8_SB(1, 1), b3 + hstep, voffB);
;             PG8_WAIT_V(6); PG8_BAR; PG8_MMA(1, 1, At, B1); PG8_BAR;
;         }
;         if constexpr (!Epi::AFTER_DRAIN) { E(acc, cur, wr, wc, fr, fq); S.done(cur); }
;         if (!has_next) break;
; #pragma unroll
;         for (int a = 0; a < 2; ++a)
; #pragma unroll
;             for (int b = 0; b < 2; ++b)
; #pragma unroll
;                 for (int m = 0; m < 4; ++m)
; #pragma unroll
;                     for (int n = 0; n < 2; ++n) acc[a][b][m][n] = (f32x4){0.f, 0.f, 0.f, 0.f};
;         cur = nxt; cA = nA; cB = nB; ++ui;
	s_waitcnt lgkmcnt(0)
	s_setprio 1
	v_mfma_f32_16x16x32_bf16 v[92:95], v[160:163], v[176:179], v[92:95]
	v_mfma_f32_16x16x32_bf16 v[88:91], v[168:171], v[176:179], v[88:91]
	v_mfma_f32_16x16x32_bf16 v[84:87], v[160:163], v[184:187], v[84:87]
	v_mfma_f32_16x16x32_bf16 v[80:83], v[168:171], v[184:187], v[80:83]
	v_mfma_f32_16x16x32_bf16 v[76:79], v[160:163], v[214:217], v[76:79]
	v_mfma_f32_16x16x32_bf16 v[72:75], v[168:171], v[214:217], v[72:75]
	v_mfma_f32_16x16x32_bf16 v[68:71], v[160:163], v[222:225], v[68:71]
	v_mfma_f32_16x16x32_bf16 v[64:67], v[168:171], v[222:225], v[64:67]
	v_mfma_f32_16x16x32_bf16 v[92:95], v[164:167], v[180:183], v[92:95]
	v_mfma_f32_16x16x32_bf16 v[88:91], v[172:175], v[180:183], v[88:91]
	v_mfma_f32_16x16x32_bf16 v[84:87], v[164:167], v[210:213], v[84:87]
	v_mfma_f32_16x16x32_bf16 v[80:83], v[172:175], v[210:213], v[80:83]
	v_mfma_f32_16x16x32_bf16 v[76:79], v[164:167], v[218:221], v[76:79]
	v_mfma_f32_16x16x32_bf16 v[72:75], v[172:175], v[218:221], v[72:75]
	v_mfma_f32_16x16x32_bf16 v[68:71], v[164:167], v[226:229], v[68:71]
	v_mfma_f32_16x16x32_bf16 v[64:67], v[172:175], v[226:229], v[64:67]
	s_setprio 0
	s_barrier
	s_add_u32 s12, s22, 0xb0080
	s_addc_u32 s13, s23, 0
	s_add_i32 s22, s24, s41
	v_lshl_add_u64 v[160:161], s[12:13], 0, v[138:139]
	s_mov_b32 m0, s22
	s_nop 0
	global_load_lds_dwordx4 v[160:161], off
	v_lshl_add_u64 v[160:161], s[12:13], 0, v[132:133]
	s_add_i32 m0, s22, 0x2000
	s_nop 0
	global_load_lds_dwordx4 v[160:161], off
	s_waitcnt vmcnt(6)
	s_barrier
	s_setprio 1
	v_mfma_f32_16x16x32_bf16 v[28:31], v[230:233], v[176:179], v[28:31]
	v_mfma_f32_16x16x32_bf16 v[24:27], v[238:241], v[176:179], v[24:27]
	v_mfma_f32_16x16x32_bf16 v[20:23], v[230:233], v[184:187], v[20:23]
	v_mfma_f32_16x16x32_bf16 v[16:19], v[238:241], v[184:187], v[16:19]
	v_mfma_f32_16x16x32_bf16 v[12:15], v[230:233], v[214:217], v[12:15]
	v_mfma_f32_16x16x32_bf16 v[8:11], v[238:241], v[214:217], v[8:11]
	v_mfma_f32_16x16x32_bf16 v[4:7], v[230:233], v[222:225], v[4:7]
	v_mfma_f32_16x16x32_bf16 v[0:3], v[238:241], v[222:225], v[0:3]
	v_mfma_f32_16x16x32_bf16 v[28:31], v[234:237], v[180:183], v[28:31]
	v_mfma_f32_16x16x32_bf16 v[24:27], v[242:245], v[180:183], v[24:27]
	v_mfma_f32_16x16x32_bf16 v[20:23], v[234:237], v[210:213], v[20:23]
	v_mfma_f32_16x16x32_bf16 v[16:19], v[242:245], v[210:213], v[16:19]
	v_mfma_f32_16x16x32_bf16 v[12:15], v[234:237], v[218:221], v[12:15]
	v_mfma_f32_16x16x32_bf16 v[8:11], v[242:245], v[218:221], v[8:11]
	v_mfma_f32_16x16x32_bf16 v[4:7], v[234:237], v[226:229], v[4:7]
	v_mfma_f32_16x16x32_bf16 v[0:3], v[242:245], v[226:229], v[0:3]
	s_setprio 0
	s_add_i32 s83, s83, 2
	s_add_u32 s20, s20, 0x100
	s_addc_u32 s21, s21, 0
	s_cmp_gt_u32 s83, 41
	s_barrier
	s_cbranch_scc0 .LBB0_1074
	s_add_u32 s20, s68, 0xffffff00
	s_addc_u32 s21, s82, -1
	s_and_b64 vcc, exec, s[0:1]
	s_cbranch_vccnz .LBB0_1077
	v_mov_b32_e32 v0, 0
	s_mov_b32 s29, s65
	s_mov_b32 s16, s66
	s_mov_b64 s[8:9], s[18:19]
	s_mov_b32 s64, s67
	v_mov_b32_e32 v1, v0
	v_mov_b32_e32 v2, v0
	v_mov_b32_e32 v3, v0
	v_mov_b32_e32 v4, v0
	v_mov_b32_e32 v5, v0
	v_mov_b32_e32 v6, v0
	v_mov_b32_e32 v7, v0
	v_mov_b32_e32 v8, v0
	v_mov_b32_e32 v9, v0
	v_mov_b32_e32 v10, v0
	v_mov_b32_e32 v11, v0
	v_mov_b32_e32 v12, v0
	v_mov_b32_e32 v13, v0
	v_mov_b32_e32 v14, v0
	v_mov_b32_e32 v15, v0
	v_mov_b32_e32 v16, v0
	v_mov_b32_e32 v17, v0
	v_mov_b32_e32 v18, v0
	v_mov_b32_e32 v19, v0
	v_mov_b32_e32 v20, v0
	v_mov_b32_e32 v21, v0
	v_mov_b32_e32 v22, v0
	v_mov_b32_e32 v23, v0
	v_mov_b32_e32 v24, v0
	v_mov_b32_e32 v25, v0
	v_mov_b32_e32 v26, v0
	v_mov_b32_e32 v27, v0
	v_mov_b32_e32 v28, v0
	v_mov_b32_e32 v29, v0
	v_mov_b32_e32 v30, v0
	v_mov_b32_e32 v31, v0
	v_mov_b32_e32 v64, v0
	v_mov_b32_e32 v65, v0
	v_mov_b32_e32 v66, v0
	v_mov_b32_e32 v67, v0
	v_mov_b32_e32 v68, v0
	v_mov_b32_e32 v69, v0
	v_mov_b32_e32 v70, v0
	v_mov_b32_e32 v71, v0
	v_mov_b32_e32 v72, v0
	v_mov_b32_e32 v73, v0
	v_mov_b32_e32 v74, v0
	v_mov_b32_e32 v75, v0
	v_mov_b32_e32 v76, v0
	v_mov_b32_e32 v77, v0
	v_mov_b32_e32 v78, v0
	v_mov_b32_e32 v79, v0
	v_mov_b32_e32 v80, v0
	v_mov_b32_e32 v81, v0
	v_mov_b32_e32 v82, v0
	v_mov_b32_e32 v83, v0
	v_mov_b32_e32 v84, v0
	v_mov_b32_e32 v85, v0
	v_mov_b32_e32 v86, v0
	v_mov_b32_e32 v87, v0
	v_mov_b32_e32 v88, v0
	v_mov_b32_e32 v89, v0
	v_mov_b32_e32 v90, v0
	v_mov_b32_e32 v91, v0
	v_mov_b32_e32 v92, v0
	v_mov_b32_e32 v93, v0
	v_mov_b32_e32 v94, v0
	v_mov_b32_e32 v95, v0
	v_mov_b32_e32 v32, v0
	v_mov_b32_e32 v33, v0
	v_mov_b32_e32 v34, v0
	v_mov_b32_e32 v35, v0
	v_mov_b32_e32 v36, v0
	v_mov_b32_e32 v37, v0
	v_mov_b32_e32 v38, v0
	v_mov_b32_e32 v39, v0
	v_mov_b32_e32 v40, v0
	v_mov_b32_e32 v41, v0
	v_mov_b32_e32 v42, v0
	v_mov_b32_e32 v43, v0
	v_mov_b32_e32 v44, v0
	v_mov_b32_e32 v45, v0
	v_mov_b32_e32 v46, v0
	v_mov_b32_e32 v47, v0
	v_mov_b32_e32 v48, v0
	v_mov_b32_e32 v49, v0
	v_mov_b32_e32 v50, v0
	v_mov_b32_e32 v51, v0
	v_mov_b32_e32 v52, v0
	v_mov_b32_e32 v53, v0
	v_mov_b32_e32 v54, v0
	v_mov_b32_e32 v55, v0
	v_mov_b32_e32 v56, v0
	v_mov_b32_e32 v57, v0
	v_mov_b32_e32 v58, v0
	v_mov_b32_e32 v59, v0
	v_mov_b32_e32 v60, v0
	v_mov_b32_e32 v61, v0
	v_mov_b32_e32 v62, v0
	v_mov_b32_e32 v63, v0
	v_mov_b32_e32 v96, v0
	v_mov_b32_e32 v97, v0
	v_mov_b32_e32 v98, v0
	v_mov_b32_e32 v99, v0
	v_mov_b32_e32 v100, v0
	v_mov_b32_e32 v101, v0
	v_mov_b32_e32 v102, v0
	v_mov_b32_e32 v103, v0
	v_mov_b32_e32 v104, v0
	v_mov_b32_e32 v105, v0
	v_mov_b32_e32 v106, v0
	v_mov_b32_e32 v107, v0
	v_mov_b32_e32 v108, v0
	v_mov_b32_e32 v109, v0
	v_mov_b32_e32 v110, v0
	v_mov_b32_e32 v111, v0
	v_mov_b32_e32 v112, v0
	v_mov_b32_e32 v113, v0
	v_mov_b32_e32 v114, v0
	v_mov_b32_e32 v115, v0
	v_mov_b32_e32 v116, v0
	v_mov_b32_e32 v117, v0
	v_mov_b32_e32 v118, v0
	v_mov_b32_e32 v119, v0
	v_mov_b32_e32 v120, v0
	v_mov_b32_e32 v121, v0
	v_mov_b32_e32 v122, v0
	v_mov_b32_e32 v123, v0
	v_mov_b32_e32 v124, v0
	v_mov_b32_e32 v125, v0
	v_mov_b32_e32 v126, v0
	v_mov_b32_e32 v127, v0
	s_andn2_b64 vcc, exec, s[4:5]
	s_cbranch_vccnz .LBB0_1078
	s_branch .LBB0_1079

; #define PG8_STAGE(bufoff, gbase, voff) do { _Pragma("unroll") for (int _i = 0; _i < 2; ++_i) \
;         __builtin_amdgcn_global_load_lds((const unsigned*)((const char*)(gbase) + (voff)[_i]), (PG8_LAS unsigned*)(lds + (bufoff) + ldsw + _i * 8192), 16, 0, 0); } while (0)
; #define PG8_LDA(dst, b, h) do { _Pragma("unroll") for (int m = 0; m < 4; ++m) _Pragma("unroll") for (int k = 0; k < 2; ++k) dst[m][k] = *(const PG8_LAS bf16x8*)(lds + PG8_SA(b, h) + aoff + m * 2048 + k * 1024); } while (0)
; #define PG8_LDB(dst, b, h) do { _Pragma("unroll") for (int n = 0; n < 2; ++n) _Pragma("unroll") for (int k = 0; k < 2; ++k) dst[n][k] = *(const PG8_LAS bf16x8*)(lds + PG8_SB(b, h) + boff + n * 2048 + k * 1024); } while (0)
; #define PG8_MMA(ai, bj, At, Bt) do { __builtin_amdgcn_s_setprio(1); _Pragma("unroll") for (int m = 0; m < 4; ++m) _Pragma("unroll") for (int n = 0; n < 2; ++n) _Pragma("unroll") for (int k = 0; k < 2; ++k) \
;         acc[ai][bj][m][n] = __builtin_amdgcn_mfma_f32_16x16x32_bf16(Bt[n][k], At[m][k], acc[ai][bj][m][n], 0, 0, 0); __builtin_amdgcn_s_setprio(0); } while (0)
; #define PG8_WAIT_L(n) asm volatile("s_waitcnt lgkmcnt(" #n ")" ::: "memory")
; #define PG8_BAR __builtin_amdgcn_s_barrier()
; #define PG8_SCHED __builtin_amdgcn_sched_barrier(0)
; template <class Epi, class Sched>
; __device__ __forceinline__ void gemm_phase(PG8_LAS unsigned char* lds, const Gemm g, const Sched& S, const Epi& E) {
;     ...
;         for (int t = 0; t < nt; t += 2) {
;             const bool last = (t == nt - 2);
;             const char* a1 = cA + (size_t)(t + 1) * kstep;
;             const char* a2 = last ? nA : cA + (size_t)(t + 2) * kstep; const char* b2 = last ? nB : cB + (size_t)(t + 2) * kstep;
;             const char* a3 = a2 + kstep; const char* b3 = b2 + kstep;
;             if (last && has_next) S.a_ready(nxt);
;             PG8_LDB(B0, 0, 0); PG8_SCHED; PG8_LDA(At, 0, 0); PG8_STAGE(PG8_SA(1, 1), a1 + hstep, voffA);
;             PG8_WAIT_L(8); PG8_BAR; PG8_WAIT_L(0); PG8_MMA(0, 0, At, B0); PG8_BAR; PG8_SCHED;
;             PG8_LDB(B1, 0, 1); PG8_STAGE(PG8_SB(0, 0), b2, voffB);
;             PG8_BAR; PG8_WAIT_L(0); PG8_MMA(0, 1, At, B1); PG8_BAR;
;             PG8_LDA(At, 0, 1); PG8_STAGE(PG8_SA(0, 0), a2, voffA);
;             PG8_BAR; PG8_WAIT_L(0); PG8_MMA(1, 0, At, B0); PG8_BAR; PG8_SCHED;
.LBB0_1165:
	s_add_u32 s12, s16, s20
	s_addc_u32 s13, s17, s21
	s_add_u32 s12, s12, 0x100
	s_addc_u32 s13, s13, 0
	s_add_u32 s22, s65, s20
	s_addc_u32 s23, s66, s21
	s_add_i32 s68, s46, 0x100
	v_add_u32_e32 v159, s68, v156
	ds_read_b128 v[160:163], v159
	ds_read_b128 v[164:167], v159 offset:1024
	ds_read_b128 v[168:171], v159 offset:2048
	ds_read_b128 v[172:175], v159 offset:3072
	s_cmpk_eq_i32 s20, 0x1500
	s_cselect_b32 s25, s19, s13
	s_cselect_b32 s24, s18, s12
	s_cselect_b32 s23, s7, s23
	s_cselect_b32 s22, s6, s22
	v_lshl_add_u64 v[230:231], v[150:151], 0, s[20:21]
	s_add_i32 m0, s39, 0xc000
	ds_read_b128 v[176:179], v157
	ds_read_b128 v[180:183], v157 offset:1024
	ds_read_b128 v[184:187], v157 offset:2048
	ds_read_b128 v[210:213], v157 offset:3072
	ds_read_b128 v[214:217], v157 offset:4096
	ds_read_b128 v[218:221], v157 offset:5120
	ds_read_b128 v[222:225], v157 offset:6144
	ds_read_b128 v[226:229], v157 offset:7168
	global_load_lds_dwordx4 v[230:231], off
	v_lshl_add_u64 v[230:231], v[152:153], 0, s[20:21]
	s_add_i32 m0, s39, 0xe000
	s_nop 0
	global_load_lds_dwordx4 v[230:231], off
	s_waitcnt lgkmcnt(8)
	s_barrier
	s_waitcnt lgkmcnt(0)
	s_setprio 1
	v_mfma_f32_16x16x32_bf16 v[124:127], v[160:163], v[176:179], v[124:127]
	v_mfma_f32_16x16x32_bf16 v[120:123], v[168:171], v[176:179], v[120:123]
	v_mfma_f32_16x16x32_bf16 v[116:119], v[160:163], v[184:187], v[116:119]
	v_mfma_f32_16x16x32_bf16 v[112:115], v[168:171], v[184:187], v[112:115]
	v_mfma_f32_16x16x32_bf16 v[108:111], v[160:163], v[214:217], v[108:111]
	v_mfma_f32_16x16x32_bf16 v[104:107], v[168:171], v[214:217], v[104:107]
	v_mfma_f32_16x16x32_bf16 v[100:103], v[160:163], v[222:225], v[100:103]
	v_mfma_f32_16x16x32_bf16 v[96:99], v[168:171], v[222:225], v[96:99]
	v_mfma_f32_16x16x32_bf16 v[124:127], v[164:167], v[180:183], v[124:127]
	v_mfma_f32_16x16x32_bf16 v[120:123], v[172:175], v[180:183], v[120:123]
	v_mfma_f32_16x16x32_bf16 v[116:119], v[164:167], v[210:213], v[116:119]
	v_mfma_f32_16x16x32_bf16 v[112:115], v[172:175], v[210:213], v[112:115]
	v_mfma_f32_16x16x32_bf16 v[108:111], v[164:167], v[218:221], v[108:111]
	v_mfma_f32_16x16x32_bf16 v[104:107], v[172:175], v[218:221], v[104:107]
	v_mfma_f32_16x16x32_bf16 v[100:103], v[164:167], v[226:229], v[100:103]
	v_mfma_f32_16x16x32_bf16 v[96:99], v[172:175], v[226:229], v[96:99]
	s_setprio 0
	s_barrier
	s_add_i32 s69, s48, 0x100
	s_add_i32 s12, s68, s38
	v_add_u32_e32 v159, s69, v156
	v_lshl_add_u64 v[246:247], s[22:23], 0, v[138:139]
	s_mov_b32 m0, s12
	ds_read_b128 v[230:233], v159
	ds_read_b128 v[234:237], v159 offset:1024
	ds_read_b128 v[238:241], v159 offset:2048
	ds_read_b128 v[242:245], v159 offset:3072
	global_load_lds_dwordx4 v[246:247], off
	v_lshl_add_u64 v[248:249], s[22:23], 0, v[132:133]
	s_add_i32 m0, s12, 0x2000
	s_nop 0
	global_load_lds_dwordx4 v[248:249], off
	s_barrier
	s_waitcnt lgkmcnt(0)
	s_setprio 1
	v_mfma_f32_16x16x32_bf16 v[60:63], v[230:233], v[176:179], v[60:63]
	v_mfma_f32_16x16x32_bf16 v[56:59], v[238:241], v[176:179], v[56:59]
	v_mfma_f32_16x16x32_bf16 v[52:55], v[230:233], v[184:187], v[52:55]
	v_mfma_f32_16x16x32_bf16 v[48:51], v[238:241], v[184:187], v[48:51]
	v_mfma_f32_16x16x32_bf16 v[44:47], v[230:233], v[214:217], v[44:47]
	v_mfma_f32_16x16x32_bf16 v[40:43], v[238:241], v[214:217], v[40:43]
	v_mfma_f32_16x16x32_bf16 v[36:39], v[230:233], v[222:225], v[36:39]
	v_mfma_f32_16x16x32_bf16 v[32:35], v[238:241], v[222:225], v[32:35]
	v_mfma_f32_16x16x32_bf16 v[60:63], v[234:237], v[180:183], v[60:63]
	v_mfma_f32_16x16x32_bf16 v[56:59], v[242:245], v[180:183], v[56:59]
	v_mfma_f32_16x16x32_bf16 v[52:55], v[234:237], v[210:213], v[52:55]
	v_mfma_f32_16x16x32_bf16 v[48:51], v[242:245], v[210:213], v[48:51]
	v_mfma_f32_16x16x32_bf16 v[44:47], v[234:237], v[218:221], v[44:47]
	v_mfma_f32_16x16x32_bf16 v[40:43], v[242:245], v[218:221], v[40:43]
	v_mfma_f32_16x16x32_bf16 v[36:39], v[234:237], v[226:229], v[36:39]
	v_mfma_f32_16x16x32_bf16 v[32:35], v[242:245], v[226:229], v[32:35]
	s_setprio 0
	s_mov_b32 m0, s39
	v_lshl_add_u64 v[250:251], s[24:25], 0, v[128:129]
	s_barrier
	ds_read_b128 v[176:179], v157 offset:16384
	ds_read_b128 v[180:183], v157 offset:17408
	ds_read_b128 v[184:187], v157 offset:18432
	ds_read_b128 v[210:213], v157 offset:19456
	ds_read_b128 v[214:217], v157 offset:20480
	ds_read_b128 v[218:221], v157 offset:21504
	ds_read_b128 v[222:225], v157 offset:22528
	ds_read_b128 v[226:229], v157 offset:23552
	global_load_lds_dwordx4 v[250:251], off
	v_lshl_add_u64 v[252:253], s[24:25], 0, v[130:131]
	s_mov_b32 m0, s40
	s_nop 0
	global_load_lds_dwordx4 v[252:253], off
	s_barrier
	s_waitcnt lgkmcnt(0)
	s_setprio 1
	v_mfma_f32_16x16x32_bf16 v[92:95], v[160:163], v[176:179], v[92:95]
	v_mfma_f32_16x16x32_bf16 v[88:91], v[168:171], v[176:179], v[88:91]
	v_mfma_f32_16x16x32_bf16 v[84:87], v[160:163], v[184:187], v[84:87]
	v_mfma_f32_16x16x32_bf16 v[80:83], v[168:171], v[184:187], v[80:83]
	v_mfma_f32_16x16x32_bf16 v[76:79], v[160:163], v[214:217], v[76:79]
	v_mfma_f32_16x16x32_bf16 v[72:75], v[168:171], v[214:217], v[72:75]
	v_mfma_f32_16x16x32_bf16 v[68:71], v[160:163], v[222:225], v[68:71]
	v_mfma_f32_16x16x32_bf16 v[64:67], v[168:171], v[222:225], v[64:67]
	v_mfma_f32_16x16x32_bf16 v[92:95], v[164:167], v[180:183], v[92:95]
	v_mfma_f32_16x16x32_bf16 v[88:91], v[172:175], v[180:183], v[88:91]
	v_mfma_f32_16x16x32_bf16 v[84:87], v[164:167], v[210:213], v[84:87]
	v_mfma_f32_16x16x32_bf16 v[80:83], v[172:175], v[210:213], v[80:83]
	v_mfma_f32_16x16x32_bf16 v[76:79], v[164:167], v[218:221], v[76:79]
	v_mfma_f32_16x16x32_bf16 v[72:75], v[172:175], v[218:221], v[72:75]
	v_mfma_f32_16x16x32_bf16 v[68:71], v[164:167], v[226:229], v[68:71]
	v_mfma_f32_16x16x32_bf16 v[64:67], v[172:175], v[226:229], v[64:67]
	s_setprio 0
	s_barrier
; #define PG8_STAGE(bufoff, gbase, voff) do { _Pragma("unroll") for (int _i = 0; _i < 2; ++_i) \
;         __builtin_amdgcn_global_load_lds((const unsigned*)((const char*)(gbase) + (voff)[_i]), (PG8_LAS unsigned*)(lds + (bufoff) + ldsw + _i * 8192), 16, 0, 0); } while (0)
; #define PG8_LDA(dst, b, h) do { _Pragma("unroll") for (int m = 0; m < 4; ++m) _Pragma("unroll") for (int k = 0; k < 2; ++k) dst[m][k] = *(const PG8_LAS bf16x8*)(lds + PG8_SA(b, h) + aoff + m * 2048 + k * 1024); } while (0)
; #define PG8_LDB(dst, b, h) do { _Pragma("unroll") for (int n = 0; n < 2; ++n) _Pragma("unroll") for (int k = 0; k < 2; ++k) dst[n][k] = *(const PG8_LAS bf16x8*)(lds + PG8_SB(b, h) + boff + n * 2048 + k * 1024); } while (0)
; #define PG8_MMA(ai, bj, At, Bt) do { __builtin_amdgcn_s_setprio(1); _Pragma("unroll") for (int m = 0; m < 4; ++m) _Pragma("unroll") for (int n = 0; n < 2; ++n) _Pragma("unroll") for (int k = 0; k < 2; ++k) \
;         acc[ai][bj][m][n] = __builtin_amdgcn_mfma_f32_16x16x32_bf16(Bt[n][k], At[m][k], acc[ai][bj][m][n], 0, 0, 0); __builtin_amdgcn_s_setprio(0); } while (0)
; #define PG8_WAIT_V(n) asm volatile("s_waitcnt vmcnt(" #n ")" ::: "memory")
; #define PG8_WAIT_L(n) asm volatile("s_waitcnt lgkmcnt(" #n ")" ::: "memory")
; #define PG8_BAR __builtin_amdgcn_s_barrier()
; #define PG8_SCHED __builtin_amdgcn_sched_barrier(0)
; template <class Epi, class Sched>
; __device__ __forceinline__ void gemm_phase(PG8_LAS unsigned char* lds, const Gemm g, const Sched& S, const Epi& E) {
;     ...
;             PG8_STAGE(PG8_SB(0, 1), b2 + hstep, voffB);
;             PG8_WAIT_V(6); PG8_BAR; PG8_MMA(1, 1, At, B1); PG8_BAR;
;             PG8_LDB(B0, 1, 0); PG8_SCHED; PG8_LDA(At, 1, 0); PG8_STAGE(PG8_SA(0, 1), a2 + hstep, voffA);
;             PG8_WAIT_L(8); PG8_BAR; PG8_WAIT_L(0); PG8_MMA(0, 0, At, B0); PG8_BAR; PG8_SCHED;
;             PG8_LDB(B1, 1, 1); PG8_STAGE(PG8_SB(1, 0), b3, voffB);
;             PG8_BAR; PG8_WAIT_L(0); PG8_MMA(0, 1, At, B1); PG8_BAR;
;             PG8_LDA(At, 1, 1); PG8_STAGE(PG8_SA(1, 0), a3, voffA);
;             PG8_BAR; PG8_WAIT_L(0); PG8_MMA(1, 0, At, B0); PG8_BAR; PG8_SCHED;
	s_add_u32 s12, s22, 0xb0000
	s_addc_u32 s13, s23, 0
	s_add_i32 s68, s69, s38
	v_lshl_add_u64 v[160:161], s[12:13], 0, v[138:139]
	s_mov_b32 m0, s68
	s_nop 0
	global_load_lds_dwordx4 v[160:161], off
	v_lshl_add_u64 v[160:161], s[12:13], 0, v[132:133]
	s_add_i32 m0, s68, 0x2000
	s_nop 0
	global_load_lds_dwordx4 v[160:161], off
	s_waitcnt vmcnt(6)
	s_barrier
	s_setprio 1
	v_mfma_f32_16x16x32_bf16 v[28:31], v[230:233], v[176:179], v[28:31]
	v_mfma_f32_16x16x32_bf16 v[24:27], v[238:241], v[176:179], v[24:27]
	v_mfma_f32_16x16x32_bf16 v[20:23], v[230:233], v[184:187], v[20:23]
	v_mfma_f32_16x16x32_bf16 v[16:19], v[238:241], v[184:187], v[16:19]
	v_mfma_f32_16x16x32_bf16 v[12:15], v[230:233], v[214:217], v[12:15]
	v_mfma_f32_16x16x32_bf16 v[8:11], v[238:241], v[214:217], v[8:11]
	v_mfma_f32_16x16x32_bf16 v[4:7], v[230:233], v[222:225], v[4:7]
	v_mfma_f32_16x16x32_bf16 v[0:3], v[238:241], v[222:225], v[0:3]
	v_mfma_f32_16x16x32_bf16 v[28:31], v[234:237], v[180:183], v[28:31]
	v_mfma_f32_16x16x32_bf16 v[24:27], v[242:245], v[180:183], v[24:27]
	v_mfma_f32_16x16x32_bf16 v[20:23], v[234:237], v[210:213], v[20:23]
	v_mfma_f32_16x16x32_bf16 v[16:19], v[242:245], v[210:213], v[16:19]
	v_mfma_f32_16x16x32_bf16 v[12:15], v[234:237], v[218:221], v[12:15]
	v_mfma_f32_16x16x32_bf16 v[8:11], v[242:245], v[218:221], v[8:11]
	v_mfma_f32_16x16x32_bf16 v[4:7], v[234:237], v[226:229], v[4:7]
	v_mfma_f32_16x16x32_bf16 v[0:3], v[242:245], v[226:229], v[0:3]
	s_setprio 0
	s_add_i32 s68, s51, 0x100
	v_add_u32_e32 v159, s68, v156
	s_barrier
	ds_read_b128 v[160:163], v159
	ds_read_b128 v[164:167], v159 offset:1024
	ds_read_b128 v[168:171], v159 offset:2048
	ds_read_b128 v[172:175], v159 offset:3072
	s_add_u32 s12, s24, 0xb0000
	s_addc_u32 s13, s25, 0
	s_mov_b32 m0, s41
	v_lshl_add_u64 v[230:231], s[12:13], 0, v[128:129]
	ds_read_b128 v[176:179], v157 offset:32768
	ds_read_b128 v[180:183], v157 offset:33792
	ds_read_b128 v[184:187], v157 offset:34816
	ds_read_b128 v[210:213], v157 offset:35840
	ds_read_b128 v[214:217], v157 offset:36864
	ds_read_b128 v[218:221], v157 offset:37888
	ds_read_b128 v[222:225], v157 offset:38912
	ds_read_b128 v[226:229], v157 offset:39936
	global_load_lds_dwordx4 v[230:231], off
	v_lshl_add_u64 v[230:231], s[12:13], 0, v[130:131]
	s_mov_b32 m0, s58
	s_nop 0
	global_load_lds_dwordx4 v[230:231], off
	s_waitcnt lgkmcnt(8)
	s_barrier
	s_waitcnt lgkmcnt(0)
	s_setprio 1
	v_mfma_f32_16x16x32_bf16 v[124:127], v[160:163], v[176:179], v[124:127]
	v_mfma_f32_16x16x32_bf16 v[120:123], v[168:171], v[176:179], v[120:123]
	v_mfma_f32_16x16x32_bf16 v[116:119], v[160:163], v[184:187], v[116:119]
	v_mfma_f32_16x16x32_bf16 v[112:115], v[168:171], v[184:187], v[112:115]
	v_mfma_f32_16x16x32_bf16 v[108:111], v[160:163], v[214:217], v[108:111]
	v_mfma_f32_16x16x32_bf16 v[104:107], v[168:171], v[214:217], v[104:107]
	v_mfma_f32_16x16x32_bf16 v[100:103], v[160:163], v[222:225], v[100:103]
	v_mfma_f32_16x16x32_bf16 v[96:99], v[168:171], v[222:225], v[96:99]
	v_mfma_f32_16x16x32_bf16 v[124:127], v[164:167], v[180:183], v[124:127]
	v_mfma_f32_16x16x32_bf16 v[120:123], v[172:175], v[180:183], v[120:123]
	v_mfma_f32_16x16x32_bf16 v[116:119], v[164:167], v[210:213], v[116:119]
	v_mfma_f32_16x16x32_bf16 v[112:115], v[172:175], v[210:213], v[112:115]
	v_mfma_f32_16x16x32_bf16 v[108:111], v[164:167], v[218:221], v[108:111]
	v_mfma_f32_16x16x32_bf16 v[104:107], v[172:175], v[218:221], v[104:107]
	v_mfma_f32_16x16x32_bf16 v[100:103], v[164:167], v[226:229], v[100:103]
	v_mfma_f32_16x16x32_bf16 v[96:99], v[172:175], v[226:229], v[96:99]
	s_setprio 0
	s_barrier
	s_add_i32 s24, s55, 0x100
	s_add_i32 s12, s68, s38
	v_add_u32_e32 v159, s24, v156
	v_lshl_add_u64 v[246:247], v[246:247], 0, s[94:95]
	s_mov_b32 m0, s12
	ds_read_b128 v[230:233], v159
	ds_read_b128 v[234:237], v159 offset:1024
	ds_read_b128 v[238:241], v159 offset:2048
	ds_read_b128 v[242:245], v159 offset:3072
	global_load_lds_dwordx4 v[246:247], off
	v_lshl_add_u64 v[246:247], v[248:249], 0, s[94:95]
	s_add_i32 m0, s12, 0x2000
	s_nop 0
	global_load_lds_dwordx4 v[246:247], off
	s_barrier
	s_waitcnt lgkmcnt(0)
	s_setprio 1
	v_mfma_f32_16x16x32_bf16 v[60:63], v[230:233], v[176:179], v[60:63]
	v_mfma_f32_16x16x32_bf16 v[56:59], v[238:241], v[176:179], v[56:59]
	v_mfma_f32_16x16x32_bf16 v[52:55], v[230:233], v[184:187], v[52:55]
	v_mfma_f32_16x16x32_bf16 v[48:51], v[238:241], v[184:187], v[48:51]
	v_mfma_f32_16x16x32_bf16 v[44:47], v[230:233], v[214:217], v[44:47]
	v_mfma_f32_16x16x32_bf16 v[40:43], v[238:241], v[214:217], v[40:43]
	v_mfma_f32_16x16x32_bf16 v[36:39], v[230:233], v[222:225], v[36:39]
	v_mfma_f32_16x16x32_bf16 v[32:35], v[238:241], v[222:225], v[32:35]
	v_mfma_f32_16x16x32_bf16 v[60:63], v[234:237], v[180:183], v[60:63]
	v_mfma_f32_16x16x32_bf16 v[56:59], v[242:245], v[180:183], v[56:59]
	v_mfma_f32_16x16x32_bf16 v[52:55], v[234:237], v[210:213], v[52:55]
	v_mfma_f32_16x16x32_bf16 v[48:51], v[242:245], v[210:213], v[48:51]
	v_mfma_f32_16x16x32_bf16 v[44:47], v[234:237], v[218:221], v[44:47]
	v_mfma_f32_16x16x32_bf16 v[40:43], v[242:245], v[218:221], v[40:43]
	v_mfma_f32_16x16x32_bf16 v[36:39], v[234:237], v[226:229], v[36:39]
	v_mfma_f32_16x16x32_bf16 v[32:35], v[242:245], v[226:229], v[32:35]
	s_setprio 0
	s_mov_b32 m0, s59
	v_lshl_add_u64 v[246:247], v[250:251], 0, s[94:95]
	s_barrier
	ds_read_b128 v[176:179], v157 offset:49152
	ds_read_b128 v[180:183], v157 offset:50176
	ds_read_b128 v[184:187], v157 offset:51200
	ds_read_b128 v[210:213], v157 offset:52224
	ds_read_b128 v[214:217], v157 offset:53248
	ds_read_b128 v[218:221], v157 offset:54272
	ds_read_b128 v[222:225], v157 offset:55296
	ds_read_b128 v[226:229], v157 offset:56320
	global_load_lds_dwordx4 v[246:247], off
	v_lshl_add_u64 v[246:247], v[252:253], 0, s[94:95]
	s_mov_b32 m0, s60
	s_nop 0
	global_load_lds_dwordx4 v[246:247], off
	s_barrier
; #define PG8_STAGE(bufoff, gbase, voff) do { _Pragma("unroll") for (int _i = 0; _i < 2; ++_i) \
;         __builtin_amdgcn_global_load_lds((const unsigned*)((const char*)(gbase) + (voff)[_i]), (PG8_LAS unsigned*)(lds + (bufoff) + ldsw + _i * 8192), 16, 0, 0); } while (0)
; #define PG8_MMA(ai, bj, At, Bt) do { __builtin_amdgcn_s_setprio(1); _Pragma("unroll") for (int m = 0; m < 4; ++m) _Pragma("unroll") for (int n = 0; n < 2; ++n) _Pragma("unroll") for (int k = 0; k < 2; ++k) \
;         acc[ai][bj][m][n] = __builtin_amdgcn_mfma_f32_16x16x32_bf16(Bt[n][k], At[m][k], acc[ai][bj][m][n], 0, 0, 0); __builtin_amdgcn_s_setprio(0); } while (0)
; #define PG8_WAIT_V(n) asm volatile("s_waitcnt vmcnt(" #n ")" ::: "memory")
; #define PG8_WAIT_L(n) asm volatile("s_waitcnt lgkmcnt(" #n ")" ::: "memory")
; #define PG8_BAR __builtin_amdgcn_s_barrier()
; #define PG8_SCHED __builtin_amdgcn_sched_barrier(0)
; template <class Epi, class Sched>
; __device__ __forceinline__ void gemm_phase(PG8_LAS unsigned char* lds, const Gemm g, const Sched& S, const Epi& E) {
;     ...
;             PG8_BAR; PG8_WAIT_L(0); PG8_MMA(1, 0, At, B0); PG8_BAR; PG8_SCHED;
;             PG8_STAGE(PG8_SB(1, 1), b3 + hstep, voffB);
;             PG8_WAIT_V(6); PG8_BAR; PG8_MMA(1, 1, At, B1); PG8_BAR;
;         }
;         if constexpr (!Epi::AFTER_DRAIN) { E(acc, cur, wr, wc, fr, fq); S.done(cur); }
;         if (!has_next) break;
; #pragma unroll
;         for (int a = 0; a < 2; ++a)
; #pragma unroll
;             for (int b = 0; b < 2; ++b)
; #pragma unroll
;                 for (int m = 0; m < 4; ++m)
; #pragma unroll
;                     for (int n = 0; n < 2; ++n) acc[a][b][m][n] = (f32x4){0.f, 0.f, 0.f, 0.f};
;         cur = nxt; cA = nA; cB = nB; ++ui;
	s_waitcnt lgkmcnt(0)
	s_setprio 1
	v_mfma_f32_16x16x32_bf16 v[92:95], v[160:163], v[176:179], v[92:95]
	v_mfma_f32_16x16x32_bf16 v[88:91], v[168:171], v[176:179], v[88:91]
	v_mfma_f32_16x16x32_bf16 v[84:87], v[160:163], v[184:187], v[84:87]
	v_mfma_f32_16x16x32_bf16 v[80:83], v[168:171], v[184:187], v[80:83]
	v_mfma_f32_16x16x32_bf16 v[76:79], v[160:163], v[214:217], v[76:79]
	v_mfma_f32_16x16x32_bf16 v[72:75], v[168:171], v[214:217], v[72:75]
	v_mfma_f32_16x16x32_bf16 v[68:71], v[160:163], v[222:225], v[68:71]
	v_mfma_f32_16x16x32_bf16 v[64:67], v[168:171], v[222:225], v[64:67]
	v_mfma_f32_16x16x32_bf16 v[92:95], v[164:167], v[180:183], v[92:95]
	v_mfma_f32_16x16x32_bf16 v[88:91], v[172:175], v[180:183], v[88:91]
	v_mfma_f32_16x16x32_bf16 v[84:87], v[164:167], v[210:213], v[84:87]
	v_mfma_f32_16x16x32_bf16 v[80:83], v[172:175], v[210:213], v[80:83]
	v_mfma_f32_16x16x32_bf16 v[76:79], v[164:167], v[218:221], v[76:79]
	v_mfma_f32_16x16x32_bf16 v[72:75], v[172:175], v[218:221], v[72:75]
	v_mfma_f32_16x16x32_bf16 v[68:71], v[164:167], v[226:229], v[68:71]
	v_mfma_f32_16x16x32_bf16 v[64:67], v[172:175], v[226:229], v[64:67]
	s_setprio 0
	s_barrier
	s_add_u32 s12, s22, 0xb0080
	s_addc_u32 s13, s23, 0
	s_add_i32 s22, s24, s38
	v_lshl_add_u64 v[160:161], s[12:13], 0, v[138:139]
	s_mov_b32 m0, s22
	s_nop 0
	global_load_lds_dwordx4 v[160:161], off
	v_lshl_add_u64 v[160:161], s[12:13], 0, v[132:133]
	s_add_i32 m0, s22, 0x2000
	s_nop 0
	global_load_lds_dwordx4 v[160:161], off
	s_waitcnt vmcnt(6)
	s_barrier
	s_setprio 1
	v_mfma_f32_16x16x32_bf16 v[28:31], v[230:233], v[176:179], v[28:31]
	v_mfma_f32_16x16x32_bf16 v[24:27], v[238:241], v[176:179], v[24:27]
	v_mfma_f32_16x16x32_bf16 v[20:23], v[230:233], v[184:187], v[20:23]
	v_mfma_f32_16x16x32_bf16 v[16:19], v[238:241], v[184:187], v[16:19]
	v_mfma_f32_16x16x32_bf16 v[12:15], v[230:233], v[214:217], v[12:15]
	v_mfma_f32_16x16x32_bf16 v[8:11], v[238:241], v[214:217], v[8:11]
	v_mfma_f32_16x16x32_bf16 v[4:7], v[230:233], v[222:225], v[4:7]
	v_mfma_f32_16x16x32_bf16 v[0:3], v[238:241], v[222:225], v[0:3]
	v_mfma_f32_16x16x32_bf16 v[28:31], v[234:237], v[180:183], v[28:31]
	v_mfma_f32_16x16x32_bf16 v[24:27], v[242:245], v[180:183], v[24:27]
	v_mfma_f32_16x16x32_bf16 v[20:23], v[234:237], v[210:213], v[20:23]
	v_mfma_f32_16x16x32_bf16 v[16:19], v[242:245], v[210:213], v[16:19]
	v_mfma_f32_16x16x32_bf16 v[12:15], v[234:237], v[218:221], v[12:15]
	v_mfma_f32_16x16x32_bf16 v[8:11], v[242:245], v[218:221], v[8:11]
	v_mfma_f32_16x16x32_bf16 v[4:7], v[234:237], v[226:229], v[4:7]
	v_mfma_f32_16x16x32_bf16 v[0:3], v[242:245], v[226:229], v[0:3]
	s_setprio 0
	s_add_i32 s67, s67, 2
	s_add_u32 s20, s20, 0x100
	s_addc_u32 s21, s21, 0
	s_cmp_gt_u32 s67, 41
	s_barrier
	s_cbranch_scc0 .LBB0_1165
	s_add_u32 s20, s65, 0xffffff00
	s_addc_u32 s21, s66, -1
	s_and_b64 vcc, exec, s[0:1]
	s_cbranch_vccnz .LBB0_1168
	v_mov_b32_e32 v0, 0
	s_mov_b32 s27, s62
	s_mov_b32 s8, s63
	s_mov_b64 s[16:17], s[18:19]
	s_mov_b32 s61, s64
	v_mov_b32_e32 v1, v0
	v_mov_b32_e32 v2, v0
	v_mov_b32_e32 v3, v0
	v_mov_b32_e32 v4, v0
	v_mov_b32_e32 v5, v0
	v_mov_b32_e32 v6, v0
	v_mov_b32_e32 v7, v0
	v_mov_b32_e32 v8, v0
	v_mov_b32_e32 v9, v0
	v_mov_b32_e32 v10, v0
	v_mov_b32_e32 v11, v0
	v_mov_b32_e32 v12, v0
	v_mov_b32_e32 v13, v0
	v_mov_b32_e32 v14, v0
	v_mov_b32_e32 v15, v0
	v_mov_b32_e32 v16, v0
	v_mov_b32_e32 v17, v0
	v_mov_b32_e32 v18, v0
	v_mov_b32_e32 v19, v0
	v_mov_b32_e32 v20, v0
	v_mov_b32_e32 v21, v0
	v_mov_b32_e32 v22, v0
	v_mov_b32_e32 v23, v0
	v_mov_b32_e32 v24, v0
	v_mov_b32_e32 v25, v0
	v_mov_b32_e32 v26, v0
	v_mov_b32_e32 v27, v0
	v_mov_b32_e32 v28, v0
	v_mov_b32_e32 v29, v0
	v_mov_b32_e32 v30, v0
	v_mov_b32_e32 v31, v0
	v_mov_b32_e32 v64, v0
	v_mov_b32_e32 v65, v0
	v_mov_b32_e32 v66, v0
	v_mov_b32_e32 v67, v0
	v_mov_b32_e32 v68, v0
	v_mov_b32_e32 v69, v0
	v_mov_b32_e32 v70, v0
	v_mov_b32_e32 v71, v0
	v_mov_b32_e32 v72, v0
	v_mov_b32_e32 v73, v0
	v_mov_b32_e32 v74, v0
	v_mov_b32_e32 v75, v0
	v_mov_b32_e32 v76, v0
	v_mov_b32_e32 v77, v0
	v_mov_b32_e32 v78, v0
	v_mov_b32_e32 v79, v0
	v_mov_b32_e32 v80, v0
	v_mov_b32_e32 v81, v0
	v_mov_b32_e32 v82, v0
	v_mov_b32_e32 v83, v0
	v_mov_b32_e32 v84, v0
	v_mov_b32_e32 v85, v0
	v_mov_b32_e32 v86, v0
	v_mov_b32_e32 v87, v0
	v_mov_b32_e32 v88, v0
	v_mov_b32_e32 v89, v0
	v_mov_b32_e32 v90, v0
	v_mov_b32_e32 v91, v0
	v_mov_b32_e32 v92, v0
	v_mov_b32_e32 v93, v0
	v_mov_b32_e32 v94, v0
	v_mov_b32_e32 v95, v0
	v_mov_b32_e32 v32, v0
	v_mov_b32_e32 v33, v0
	v_mov_b32_e32 v34, v0
	v_mov_b32_e32 v35, v0
	v_mov_b32_e32 v36, v0
	v_mov_b32_e32 v37, v0
	v_mov_b32_e32 v38, v0
	v_mov_b32_e32 v39, v0
	v_mov_b32_e32 v40, v0
	v_mov_b32_e32 v41, v0
	v_mov_b32_e32 v42, v0
	v_mov_b32_e32 v43, v0
	v_mov_b32_e32 v44, v0
	v_mov_b32_e32 v45, v0
	v_mov_b32_e32 v46, v0
	v_mov_b32_e32 v47, v0
	v_mov_b32_e32 v48, v0
	v_mov_b32_e32 v49, v0
	v_mov_b32_e32 v50, v0
	v_mov_b32_e32 v51, v0
	v_mov_b32_e32 v52, v0
	v_mov_b32_e32 v53, v0
	v_mov_b32_e32 v54, v0
	v_mov_b32_e32 v55, v0
	v_mov_b32_e32 v56, v0
	v_mov_b32_e32 v57, v0
	v_mov_b32_e32 v58, v0
	v_mov_b32_e32 v59, v0
	v_mov_b32_e32 v60, v0
	v_mov_b32_e32 v61, v0
	v_mov_b32_e32 v62, v0
	v_mov_b32_e32 v63, v0
	v_mov_b32_e32 v96, v0
	v_mov_b32_e32 v97, v0
	v_mov_b32_e32 v98, v0
	v_mov_b32_e32 v99, v0
	v_mov_b32_e32 v100, v0
	v_mov_b32_e32 v101, v0
	v_mov_b32_e32 v102, v0
	v_mov_b32_e32 v103, v0
	v_mov_b32_e32 v104, v0
	v_mov_b32_e32 v105, v0
	v_mov_b32_e32 v106, v0
	v_mov_b32_e32 v107, v0
	v_mov_b32_e32 v108, v0
	v_mov_b32_e32 v109, v0
	v_mov_b32_e32 v110, v0
	v_mov_b32_e32 v111, v0
	v_mov_b32_e32 v112, v0
	v_mov_b32_e32 v113, v0
	v_mov_b32_e32 v114, v0
	v_mov_b32_e32 v115, v0
	v_mov_b32_e32 v116, v0
	v_mov_b32_e32 v117, v0
	v_mov_b32_e32 v118, v0
	v_mov_b32_e32 v119, v0
	v_mov_b32_e32 v120, v0
	v_mov_b32_e32 v121, v0
	v_mov_b32_e32 v122, v0
	v_mov_b32_e32 v123, v0
	v_mov_b32_e32 v124, v0
	v_mov_b32_e32 v125, v0
	v_mov_b32_e32 v126, v0
	v_mov_b32_e32 v127, v0
	s_andn2_b64 vcc, exec, s[4:5]
	s_cbranch_vccnz .LBB0_1169
	s_branch .LBB0_1170
